# S12 plus write-through (sc0 sc1) on all 16-byte global stores, to shorten the L2 write-back in the grid barriers
# speedup vs baseline: 1.0199x; 1.0048x over previous
; #define LAS __attribute__((address_space(3)))
; __device__ __forceinline__ void p0_prologue(Frame& F) {
;     ...
;         for (int o = F.tid; o < 3 * 192; o += 512) { const int r = o / 192, cidx = 4 * (o % 192); f32x4 sm = {0.f, 0.f, 0.f, 0.f};
; #pragma unroll
;             for (int w = 0; w < 8; ++w) sm += *(const LAS f32x4*)(red + (w * 3 + r) * 768 + cidx);
;             *(f32x4*)(PART + ((size_t)((l * 16 + ks) * 3 + r)) * 12288 + 768 * ng + cidx) = sm; }
.LBB0_31:
	ds_read_b128 v[6:9], v3
	ds_read_b128 v[10:13], v3 offset:9216
	ds_read_b128 v[14:17], v3 offset:18432
	ds_read_b128 v[18:21], v3 offset:27648
	ds_read_b128 v[22:25], v3 offset:36864
	ds_read_b128 v[26:29], v3 offset:46080
	ds_read_b128 v[30:33], v3 offset:55296
	ds_read_b128 v[34:37], v3 offset:64512
	s_waitcnt lgkmcnt(7)
	v_pk_add_f32 v[8:9], v[8:9], 0 op_sel_hi:[1,0]
	v_pk_add_f32 v[6:7], v[6:7], 0 op_sel_hi:[1,0]
	s_waitcnt lgkmcnt(6)
	v_pk_add_f32 v[8:9], v[8:9], v[12:13]
	v_pk_add_f32 v[6:7], v[6:7], v[10:11]
	v_mul_hi_i32 v5, v4, s17
	s_waitcnt lgkmcnt(5)
	v_pk_add_f32 v[8:9], v[8:9], v[16:17]
	v_pk_add_f32 v[6:7], v[6:7], v[14:15]
	v_lshrrev_b32_e32 v41, 31, v5
	v_ashrrev_i32_e32 v5, 5, v5
	s_waitcnt lgkmcnt(4)
	v_pk_add_f32 v[8:9], v[8:9], v[20:21]
	v_pk_add_f32 v[6:7], v[6:7], v[18:19]
	v_add_u32_e32 v40, 0x200, v4
	v_add_u32_e32 v3, 0x2000, v3
	v_cmp_lt_i32_e64 s[0:1], 63, v4
	v_add_u32_e32 v5, v5, v41
	s_waitcnt lgkmcnt(3)
	v_pk_add_f32 v[8:9], v[8:9], v[24:25]
	v_pk_add_f32 v[6:7], v[6:7], v[22:23]
	v_mov_b64_e32 v[38:39], s[4:5]
	s_or_b64 s[10:11], s[0:1], s[10:11]
	v_mov_b32_e32 v4, v40
	v_mad_u64_u32 v[40:41], s[0:1], v5, s18, v[2:3]
	v_add_u32_e32 v5, s20, v5
	s_waitcnt lgkmcnt(2)
	v_pk_add_f32 v[8:9], v[8:9], v[28:29]
	v_pk_add_f32 v[6:7], v[6:7], v[26:27]
	v_mad_i64_i32 v[38:39], s[0:1], v5, s16, v[38:39]
	v_ashrrev_i32_e32 v41, 31, v40
	s_waitcnt lgkmcnt(1)
	v_pk_add_f32 v[8:9], v[8:9], v[32:33]
	v_pk_add_f32 v[6:7], v[6:7], v[30:31]
	v_add_u32_e32 v2, 0x800, v2
	v_lshl_add_u64 v[38:39], v[40:41], 2, v[38:39]
	s_waitcnt lgkmcnt(0)
	v_pk_add_f32 v[8:9], v[8:9], v[36:37]
	v_pk_add_f32 v[6:7], v[6:7], v[34:35]
	global_store_dwordx4 v[38:39], v[6:9], off sc0 sc1
	s_andn2_b64 exec, exec, s[10:11]
	s_cbranch_execnz .LBB0_31
	s_branch .LBB0_28

; #define GAS __attribute__((address_space(1)))
; #define LAS __attribute__((address_space(3)))
; #define LDS_WAIT() asm volatile("s_waitcnt lgkmcnt(0)" ::: "memory")
; __device__ __forceinline__ unsigned pk2(float lo, float hi) { return f2bf(lo) | (f2bf(hi) << 16); }
; __device__ __forceinline__ void cv_finish(const CvDesc& d, const f32x4 (&wv)[8], LAS float* scr, int lane) {
; #pragma unroll
;     for (int i = 0; i < 8; ++i) { LAS float* w = scr + (8 * i + (lane >> 3)) * 33 + 4 * (lane & 7);
; #pragma unroll
;         for (int c = 0; c < 4; ++c) w[c] = wv[i][c]; }
;     LDS_WAIT(); asm volatile("" ::: "memory");
;     const int cch = lane & 7;
; #pragma unroll
;     for (int j = 0; j < 4; ++j) { const int n = (lane >> 3) + 8 * j; const LAS float* s = scr + (8 * cch) * 33 + n;
;         v4u o; o.x = pk2(s[0 * 33], s[1 * 33]); o.y = pk2(s[2 * 33], s[3 * 33]); o.z = pk2(s[4 * 33], s[5 * 33]); o.w = pk2(s[6 * 33], s[7 * 33]);
;         const int nn = d.n0 + n; const int drow = d.mode ? (d.row_off + (nn >> 7) * 256 + (nn & 127)) : (d.row_off + nn);
;         *(GAS v4u*)(d.WT + (size_t)drow * d.K + d.k0 + 8 * cch) = o; }
;     LDS_WAIT(); asm volatile("" ::: "memory");
; }
.LBB0_90:
	s_waitcnt lgkmcnt(3)
	v_bfe_u32 v115, v109, 16, 1
	v_add3_u32 v109, v109, v115, s31
	v_bfe_u32 v115, v108, 16, 1
	v_add3_u32 v108, v108, v115, s31
	v_lshrrev_b32_e32 v108, 16, v108
	v_and_or_b32 v116, v109, s35, v108
	s_waitcnt lgkmcnt(2)
	v_bfe_u32 v108, v107, 16, 1
	v_add3_u32 v107, v107, v108, s31
	v_bfe_u32 v108, v106, 16, 1
	v_add3_u32 v106, v106, v108, s31
	v_lshrrev_b32_e32 v106, 16, v106
	v_and_or_b32 v117, v107, s35, v106
	s_waitcnt lgkmcnt(1)
	v_bfe_u32 v106, v105, 16, 1
	v_add3_u32 v105, v105, v106, s31
	v_bfe_u32 v106, v104, 16, 1
	v_add3_u32 v104, v104, v106, s31
	v_lshrrev_b32_e32 v104, 16, v104
	v_and_or_b32 v118, v105, s35, v104
	s_waitcnt lgkmcnt(0)
	v_bfe_u32 v104, v103, 16, 1
	v_add3_u32 v103, v103, v104, s31
	v_bfe_u32 v104, v102, 16, 1
	v_add3_u32 v102, v102, v104, s31
	v_lshrrev_b32_e32 v102, 16, v102
	v_and_or_b32 v119, v103, s35, v102
	v_ashrrev_i32_e32 v102, 31, v99
	v_mul_lo_u32 v104, s13, v99
	v_mul_lo_u32 v105, s12, v102
	v_mad_u64_u32 v[102:103], s[0:1], s12, v99, 0
	v_add3_u32 v103, v103, v105, v104
	v_lshl_add_u64 v[102:103], v[102:103], 1, s[4:5]
	v_lshl_add_u64 v[102:103], s[10:11], 1, v[102:103]
	v_lshl_add_u64 v[102:103], v[102:103], 0, v[100:101]
	global_store_dwordx4 v[102:103], v[116:119], off sc0 sc1
	s_waitcnt lgkmcnt(0)

; #define GAS __attribute__((address_space(1)))
; #define LAS __attribute__((address_space(3)))
; #define LDS_WAIT() asm volatile("s_waitcnt lgkmcnt(0)" ::: "memory")
; __device__ __forceinline__ unsigned pk2(float lo, float hi) { return f2bf(lo) | (f2bf(hi) << 16); }
; __device__ __forceinline__ void cv_finish(const CvDesc& d, const f32x4 (&wv)[8], LAS float* scr, int lane) {
;     ...
;     for (int j = 0; j < 4; ++j) { const int n = (lane >> 3) + 8 * j; const LAS float* s = scr + (8 * cch) * 33 + n;
;         v4u o; o.x = pk2(s[0 * 33], s[1 * 33]); o.y = pk2(s[2 * 33], s[3 * 33]); o.z = pk2(s[4 * 33], s[5 * 33]); o.w = pk2(s[6 * 33], s[7 * 33]);
;         const int nn = d.n0 + n; const int drow = d.mode ? (d.row_off + (nn >> 7) * 256 + (nn & 127)) : (d.row_off + nn);
;         *(GAS v4u*)(d.WT + (size_t)drow * d.K + d.k0 + 8 * cch) = o; }
;     LDS_WAIT(); asm volatile("" ::: "memory");
.LBB0_141:
	s_waitcnt lgkmcnt(3)
	v_bfe_u32 v129, v108, 16, 1
	v_add3_u32 v108, v108, v129, s31
	v_bfe_u32 v129, v109, 16, 1
	v_lshrrev_b32_e32 v108, 16, v108
	v_add3_u32 v109, v109, v129, s31
	v_and_or_b32 v130, v109, s35, v108
	s_waitcnt lgkmcnt(2)
	v_bfe_u32 v108, v106, 16, 1
	v_add3_u32 v106, v106, v108, s31
	v_bfe_u32 v108, v107, 16, 1
	v_lshrrev_b32_e32 v106, 16, v106
	v_add3_u32 v107, v107, v108, s31
	v_and_or_b32 v131, v107, s35, v106
	s_waitcnt lgkmcnt(1)
	v_bfe_u32 v106, v104, 16, 1
	v_add3_u32 v104, v104, v106, s31
	v_bfe_u32 v106, v105, 16, 1
	v_lshrrev_b32_e32 v104, 16, v104
	v_add3_u32 v105, v105, v106, s31
	v_and_or_b32 v132, v105, s35, v104
	s_waitcnt lgkmcnt(0)
	v_bfe_u32 v104, v102, 16, 1
	v_add3_u32 v102, v102, v104, s31
	v_bfe_u32 v104, v103, 16, 1
	v_lshrrev_b32_e32 v102, 16, v102
	v_add3_u32 v103, v103, v104, s31
	v_and_or_b32 v133, v103, s35, v102
	v_ashrrev_i32_e32 v102, 31, v99
	v_mul_lo_u32 v104, s15, v99
	v_mul_lo_u32 v105, s14, v102
	v_mad_u64_u32 v[102:103], s[16:17], s14, v99, 0
	v_add3_u32 v103, v103, v105, v104
	v_lshl_add_u64 v[102:103], v[102:103], 1, s[10:11]
	s_ashr_i32 s13, s12, 31
	v_lshl_add_u64 v[102:103], s[12:13], 1, v[102:103]
	v_lshl_add_u64 v[102:103], v[102:103], 0, v[100:101]
	global_store_dwordx4 v[102:103], v[130:133], off sc0 sc1
	ds_read2_b32 v[108:109], v113 offset0:8 offset1:41
	ds_read2_b32 v[106:107], v113 offset0:74 offset1:107
	ds_read2_b32 v[104:105], v113 offset0:140 offset1:173
	ds_read2_b32 v[102:103], v113 offset0:206 offset1:239
	s_xor_b64 s[16:17], s[0:1], -1
	v_cndmask_b32_e64 v99, 0, 1, s[16:17]
	v_or_b32_e32 v129, s2, v110
	v_cmp_ne_u32_e64 s[0:1], 1, v99
	s_andn2_b64 vcc, exec, s[16:17]
	s_mov_b64 s[16:17], -1
	s_cbranch_vccnz .LBB0_143
	s_lshl_b32 s16, s2, 1
	s_and_b32 s16, s16, 0xffffff00
	v_and_b32_e32 v99, 0x6f, v129
	v_or_b32_e32 v99, s16, v99
	v_or_b32_e32 v99, s39, v99
	s_mov_b64 s[16:17], 0

; #define GAS __attribute__((address_space(1)))
; #define LAS __attribute__((address_space(3)))
; #define LDS_WAIT() asm volatile("s_waitcnt lgkmcnt(0)" ::: "memory")
; __device__ __forceinline__ unsigned pk2(float lo, float hi) { return f2bf(lo) | (f2bf(hi) << 16); }
; __device__ __forceinline__ void cv_finish(const CvDesc& d, const f32x4 (&wv)[8], LAS float* scr, int lane) {
;     ...
;     for (int j = 0; j < 4; ++j) { const int n = (lane >> 3) + 8 * j; const LAS float* s = scr + (8 * cch) * 33 + n;
;         v4u o; o.x = pk2(s[0 * 33], s[1 * 33]); o.y = pk2(s[2 * 33], s[3 * 33]); o.z = pk2(s[4 * 33], s[5 * 33]); o.w = pk2(s[6 * 33], s[7 * 33]);
;         const int nn = d.n0 + n; const int drow = d.mode ? (d.row_off + (nn >> 7) * 256 + (nn & 127)) : (d.row_off + nn);
;         *(GAS v4u*)(d.WT + (size_t)drow * d.K + d.k0 + 8 * cch) = o; }
;     LDS_WAIT(); asm volatile("" ::: "memory");
.LBB0_145:
	s_waitcnt lgkmcnt(3)
	v_bfe_u32 v129, v108, 16, 1
	v_add3_u32 v108, v108, v129, s31
	v_bfe_u32 v129, v109, 16, 1
	v_lshrrev_b32_e32 v108, 16, v108
	v_add3_u32 v109, v109, v129, s31
	v_and_or_b32 v130, v109, s35, v108
	s_waitcnt lgkmcnt(2)
	v_bfe_u32 v108, v106, 16, 1
	v_add3_u32 v106, v106, v108, s31
	v_bfe_u32 v108, v107, 16, 1
	v_lshrrev_b32_e32 v106, 16, v106
	v_add3_u32 v107, v107, v108, s31
	v_and_or_b32 v131, v107, s35, v106
	s_waitcnt lgkmcnt(1)
	v_bfe_u32 v106, v104, 16, 1
	v_add3_u32 v104, v104, v106, s31
	v_bfe_u32 v106, v105, 16, 1
	v_lshrrev_b32_e32 v104, 16, v104
	v_add3_u32 v105, v105, v106, s31
	v_and_or_b32 v132, v105, s35, v104
	s_waitcnt lgkmcnt(0)
	v_bfe_u32 v104, v102, 16, 1
	v_add3_u32 v102, v102, v104, s31
	v_bfe_u32 v104, v103, 16, 1
	v_lshrrev_b32_e32 v102, 16, v102
	v_add3_u32 v103, v103, v104, s31
	v_and_or_b32 v133, v103, s35, v102
	v_ashrrev_i32_e32 v102, 31, v99
	v_mul_lo_u32 v104, s15, v99
	v_mul_lo_u32 v105, s14, v102
	v_mad_u64_u32 v[102:103], s[16:17], s14, v99, 0
	v_add3_u32 v103, v103, v105, v104
	v_lshl_add_u64 v[102:103], v[102:103], 1, s[10:11]
	v_lshl_add_u64 v[102:103], s[12:13], 1, v[102:103]
	v_lshl_add_u64 v[134:135], v[102:103], 0, v[100:101]
	ds_read2_b32 v[108:109], v113 offset0:16 offset1:49
	ds_read2_b32 v[106:107], v113 offset0:82 offset1:115
	ds_read2_b32 v[104:105], v113 offset0:148 offset1:181
	ds_read2_b32 v[102:103], v113 offset0:214 offset1:247
	v_or_b32_e32 v129, s2, v111
	s_and_b64 vcc, exec, s[0:1]
	s_mov_b64 s[16:17], -1
	global_store_dwordx4 v[134:135], v[130:133], off sc0 sc1
	s_cbranch_vccnz .LBB0_147
	s_lshl_b32 s16, s2, 1
	s_and_b32 s16, s16, 0xffffff00
	v_and_b32_e32 v99, 0x77, v129
	v_or_b32_e32 v99, s16, v99
	v_or_b32_e32 v99, s39, v99
	s_mov_b64 s[16:17], 0

; #define GAS __attribute__((address_space(1)))
; #define LAS __attribute__((address_space(3)))
; #define LDS_WAIT() asm volatile("s_waitcnt lgkmcnt(0)" ::: "memory")
; __device__ __forceinline__ unsigned pk2(float lo, float hi) { return f2bf(lo) | (f2bf(hi) << 16); }
; __device__ __forceinline__ void cv_finish(const CvDesc& d, const f32x4 (&wv)[8], LAS float* scr, int lane) {
;     ...
;     for (int j = 0; j < 4; ++j) { const int n = (lane >> 3) + 8 * j; const LAS float* s = scr + (8 * cch) * 33 + n;
;         v4u o; o.x = pk2(s[0 * 33], s[1 * 33]); o.y = pk2(s[2 * 33], s[3 * 33]); o.z = pk2(s[4 * 33], s[5 * 33]); o.w = pk2(s[6 * 33], s[7 * 33]);
;         const int nn = d.n0 + n; const int drow = d.mode ? (d.row_off + (nn >> 7) * 256 + (nn & 127)) : (d.row_off + nn);
;         *(GAS v4u*)(d.WT + (size_t)drow * d.K + d.k0 + 8 * cch) = o; }
;     LDS_WAIT(); asm volatile("" ::: "memory");
.LBB0_149:
	s_waitcnt lgkmcnt(3)
	v_bfe_u32 v129, v108, 16, 1
	v_add3_u32 v108, v108, v129, s31
	v_bfe_u32 v129, v109, 16, 1
	v_lshrrev_b32_e32 v108, 16, v108
	v_add3_u32 v109, v109, v129, s31
	v_and_or_b32 v130, v109, s35, v108
	s_waitcnt lgkmcnt(2)
	v_bfe_u32 v108, v106, 16, 1
	v_add3_u32 v106, v106, v108, s31
	v_bfe_u32 v108, v107, 16, 1
	v_lshrrev_b32_e32 v106, 16, v106
	v_add3_u32 v107, v107, v108, s31
	v_and_or_b32 v131, v107, s35, v106
	s_waitcnt lgkmcnt(1)
	v_bfe_u32 v106, v104, 16, 1
	v_add3_u32 v104, v104, v106, s31
	v_bfe_u32 v106, v105, 16, 1
	v_lshrrev_b32_e32 v104, 16, v104
	v_add3_u32 v105, v105, v106, s31
	v_and_or_b32 v132, v105, s35, v104
	s_waitcnt lgkmcnt(0)
	v_bfe_u32 v104, v102, 16, 1
	v_add3_u32 v102, v102, v104, s31
	v_bfe_u32 v104, v103, 16, 1
	v_lshrrev_b32_e32 v102, 16, v102
	v_add3_u32 v103, v103, v104, s31
	v_and_or_b32 v133, v103, s35, v102
	v_ashrrev_i32_e32 v102, 31, v99
	v_mul_lo_u32 v104, s15, v99
	v_mul_lo_u32 v105, s14, v102
	v_mad_u64_u32 v[102:103], s[16:17], s14, v99, 0
	v_add3_u32 v103, v103, v105, v104
	v_lshl_add_u64 v[102:103], v[102:103], 1, s[10:11]
	v_lshl_add_u64 v[102:103], s[12:13], 1, v[102:103]
	v_lshl_add_u64 v[134:135], v[102:103], 0, v[100:101]
	ds_read2_b32 v[108:109], v113 offset0:24 offset1:57
	ds_read2_b32 v[106:107], v113 offset0:90 offset1:123
	ds_read2_b32 v[104:105], v113 offset0:156 offset1:189
	ds_read2_b32 v[102:103], v113 offset0:222 offset1:255
	v_or_b32_e32 v129, s2, v112
	s_and_b64 vcc, exec, s[0:1]
	s_mov_b64 s[0:1], -1
	global_store_dwordx4 v[134:135], v[130:133], off sc0 sc1
	s_cbranch_vccnz .LBB0_151
	s_lshl_b32 s0, s2, 1
	s_and_b32 s0, s0, 0xffffff00
	v_and_b32_e32 v99, 0x7f, v129
	v_or_b32_e32 v99, s0, v99
	v_or_b32_e32 v99, s39, v99
	s_mov_b64 s[0:1], 0

; #define GAS __attribute__((address_space(1)))
; #define LAS __attribute__((address_space(3)))
; #define LDS_WAIT() asm volatile("s_waitcnt lgkmcnt(0)" ::: "memory")
; __device__ __forceinline__ unsigned pk2(float lo, float hi) { return f2bf(lo) | (f2bf(hi) << 16); }
; __device__ __forceinline__ void cv_finish(const CvDesc& d, const f32x4 (&wv)[8], LAS float* scr, int lane) {
;     ...
;     for (int j = 0; j < 4; ++j) { const int n = (lane >> 3) + 8 * j; const LAS float* s = scr + (8 * cch) * 33 + n;
;         v4u o; o.x = pk2(s[0 * 33], s[1 * 33]); o.y = pk2(s[2 * 33], s[3 * 33]); o.z = pk2(s[4 * 33], s[5 * 33]); o.w = pk2(s[6 * 33], s[7 * 33]);
;         const int nn = d.n0 + n; const int drow = d.mode ? (d.row_off + (nn >> 7) * 256 + (nn & 127)) : (d.row_off + nn);
;         *(GAS v4u*)(d.WT + (size_t)drow * d.K + d.k0 + 8 * cch) = o; }
;     LDS_WAIT(); asm volatile("" ::: "memory");
; __device__ __forceinline__ void p0_prologue(Frame& F) {
;     ...
;     convert_stream(F, gw < NP0 ? (NP0 - gw + NGW - 1) / NGW : 0, [=](int k) { const int q = gw + k * NGW;
;         if (q < CV_I_IN) return q;
;         if (q < CV_I_IN + CV_I_OUT) return CV_N_IN + (q - CV_I_IN);
;         return cv_deferred_id(q - (CV_I_IN + CV_I_OUT)); });
.LBB0_153:
	s_waitcnt lgkmcnt(3)
	v_bfe_u32 v129, v109, 16, 1
	v_add3_u32 v109, v109, v129, s31
	v_bfe_u32 v129, v108, 16, 1
	v_add3_u32 v108, v108, v129, s31
	v_lshrrev_b32_e32 v108, 16, v108
	v_and_or_b32 v130, v109, s35, v108
	s_waitcnt lgkmcnt(2)
	v_bfe_u32 v108, v107, 16, 1
	v_add3_u32 v107, v107, v108, s31
	v_bfe_u32 v108, v106, 16, 1
	v_add3_u32 v106, v106, v108, s31
	v_lshrrev_b32_e32 v106, 16, v106
	v_and_or_b32 v131, v107, s35, v106
	s_waitcnt lgkmcnt(1)
	v_bfe_u32 v106, v105, 16, 1
	v_add3_u32 v105, v105, v106, s31
	v_bfe_u32 v106, v104, 16, 1
	v_add3_u32 v104, v104, v106, s31
	v_lshrrev_b32_e32 v104, 16, v104
	v_and_or_b32 v132, v105, s35, v104
	s_waitcnt lgkmcnt(0)
	v_bfe_u32 v104, v103, 16, 1
	v_add3_u32 v103, v103, v104, s31
	v_bfe_u32 v104, v102, 16, 1
	v_add3_u32 v102, v102, v104, s31
	v_lshrrev_b32_e32 v102, 16, v102
	v_and_or_b32 v133, v103, s35, v102
	v_ashrrev_i32_e32 v102, 31, v99
	v_mul_lo_u32 v104, s15, v99
	v_mul_lo_u32 v105, s14, v102
	v_mad_u64_u32 v[102:103], s[0:1], s14, v99, 0
	v_add3_u32 v103, v103, v105, v104
	v_lshl_add_u64 v[102:103], v[102:103], 1, s[10:11]
	v_lshl_add_u64 v[102:103], s[12:13], 1, v[102:103]
	v_lshl_add_u64 v[102:103], v[102:103], 0, v[100:101]
	global_store_dwordx4 v[102:103], v[130:133], off sc0 sc1
	s_waitcnt lgkmcnt(0)
	s_add_i32 s0, s34, -3
	s_add_i32 s39, s38, 3
	s_cmp_ge_i32 s0, s20
	s_cbranch_scc1 .LBB0_91
	s_add_i32 s0, s34, -1
	s_cmp_ge_i32 s0, s20
	s_cbranch_scc1 .LBB0_178
	s_add_i32 s2, s33, s36
	s_cmpk_lt_i32 s2, 0x1c00
	s_cbranch_scc1 .LBB0_158
	s_cmpk_gt_u32 s2, 0x23ff
	s_mov_b64 s[0:1], -1
	s_cbranch_scc0 .LBB0_159
	s_add_i32 s0, s2, 0xffffdc00
	s_mul_hi_u32 s1, s0, 0xaaaaaaab
	s_lshr_b32 s1, s1, 15
	s_mul_i32 s10, s1, 0xc000
	s_sub_i32 s0, s0, s10
	s_and_b32 s10, s0, 0x3fff
	s_lshl_b32 s0, s0, 1
	s_lshl_b32 s1, s1, 14
	s_and_b32 s0, s0, 0x18000
	s_or_b32 s1, s1, s10
	s_add_i32 s0, s1, s0
	s_add_i32 s11, s0, 0x4800
	s_cbranch_execnz .LBB0_161
	s_branch .LBB0_160

; #define GAS __attribute__((address_space(1)))
; #define LAS __attribute__((address_space(3)))
; #define LDS_WAIT() asm volatile("s_waitcnt lgkmcnt(0)" ::: "memory")
; __device__ __forceinline__ unsigned pk2(float lo, float hi) { return f2bf(lo) | (f2bf(hi) << 16); }
; __device__ __forceinline__ void cv_finish(const CvDesc& d, const f32x4 (&wv)[8], LAS float* scr, int lane) {
;     ...
;     for (int j = 0; j < 4; ++j) { const int n = (lane >> 3) + 8 * j; const LAS float* s = scr + (8 * cch) * 33 + n;
;         v4u o; o.x = pk2(s[0 * 33], s[1 * 33]); o.y = pk2(s[2 * 33], s[3 * 33]); o.z = pk2(s[4 * 33], s[5 * 33]); o.w = pk2(s[6 * 33], s[7 * 33]);
;         const int nn = d.n0 + n; const int drow = d.mode ? (d.row_off + (nn >> 7) * 256 + (nn & 127)) : (d.row_off + nn);
;         *(GAS v4u*)(d.WT + (size_t)drow * d.K + d.k0 + 8 * cch) = o; }
;     LDS_WAIT(); asm volatile("" ::: "memory");
.LBB0_203:
	s_waitcnt lgkmcnt(3)
	v_bfe_u32 v129, v108, 16, 1
	v_add3_u32 v108, v108, v129, s31
	v_bfe_u32 v129, v109, 16, 1
	v_lshrrev_b32_e32 v108, 16, v108
	v_add3_u32 v109, v109, v129, s31
	v_and_or_b32 v130, v109, s35, v108
	s_waitcnt lgkmcnt(2)
	v_bfe_u32 v108, v106, 16, 1
	v_add3_u32 v106, v106, v108, s31
	v_bfe_u32 v108, v107, 16, 1
	v_lshrrev_b32_e32 v106, 16, v106
	v_add3_u32 v107, v107, v108, s31
	v_and_or_b32 v131, v107, s35, v106
	s_waitcnt lgkmcnt(1)
	v_bfe_u32 v106, v104, 16, 1
	v_add3_u32 v104, v104, v106, s31
	v_bfe_u32 v106, v105, 16, 1
	v_lshrrev_b32_e32 v104, 16, v104
	v_add3_u32 v105, v105, v106, s31
	v_and_or_b32 v132, v105, s35, v104
	s_waitcnt lgkmcnt(0)
	v_bfe_u32 v104, v102, 16, 1
	v_add3_u32 v102, v102, v104, s31
	v_bfe_u32 v104, v103, 16, 1
	v_lshrrev_b32_e32 v102, 16, v102
	v_add3_u32 v103, v103, v104, s31
	v_and_or_b32 v133, v103, s35, v102
	v_ashrrev_i32_e32 v102, 31, v99
	v_mul_lo_u32 v104, s15, v99
	v_mul_lo_u32 v105, s14, v102
	v_mad_u64_u32 v[102:103], s[16:17], s14, v99, 0
	v_add3_u32 v103, v103, v105, v104
	v_lshl_add_u64 v[102:103], v[102:103], 1, s[10:11]
	s_ashr_i32 s13, s12, 31
	v_lshl_add_u64 v[102:103], s[12:13], 1, v[102:103]
	v_lshl_add_u64 v[102:103], v[102:103], 0, v[100:101]
	global_store_dwordx4 v[102:103], v[130:133], off sc0 sc1
	ds_read2_b32 v[108:109], v113 offset0:8 offset1:41
	ds_read2_b32 v[106:107], v113 offset0:74 offset1:107
	ds_read2_b32 v[104:105], v113 offset0:140 offset1:173
	ds_read2_b32 v[102:103], v113 offset0:206 offset1:239
	s_xor_b64 s[16:17], s[0:1], -1
	v_cndmask_b32_e64 v99, 0, 1, s[16:17]
	v_or_b32_e32 v129, s2, v110
	v_cmp_ne_u32_e64 s[0:1], 1, v99
	s_andn2_b64 vcc, exec, s[16:17]
	s_mov_b64 s[16:17], -1
	s_cbranch_vccnz .LBB0_205
	s_lshl_b32 s16, s2, 1
	s_and_b32 s16, s16, 0xffffff00
	v_and_b32_e32 v99, 0x6f, v129
	v_or_b32_e32 v99, s16, v99
	v_or_b32_e32 v99, s40, v99
	s_mov_b64 s[16:17], 0

; #define GAS __attribute__((address_space(1)))
; #define LAS __attribute__((address_space(3)))
; #define LDS_WAIT() asm volatile("s_waitcnt lgkmcnt(0)" ::: "memory")
; __device__ __forceinline__ unsigned pk2(float lo, float hi) { return f2bf(lo) | (f2bf(hi) << 16); }
; __device__ __forceinline__ void cv_finish(const CvDesc& d, const f32x4 (&wv)[8], LAS float* scr, int lane) {
;     ...
;     for (int j = 0; j < 4; ++j) { const int n = (lane >> 3) + 8 * j; const LAS float* s = scr + (8 * cch) * 33 + n;
;         v4u o; o.x = pk2(s[0 * 33], s[1 * 33]); o.y = pk2(s[2 * 33], s[3 * 33]); o.z = pk2(s[4 * 33], s[5 * 33]); o.w = pk2(s[6 * 33], s[7 * 33]);
;         const int nn = d.n0 + n; const int drow = d.mode ? (d.row_off + (nn >> 7) * 256 + (nn & 127)) : (d.row_off + nn);
;         *(GAS v4u*)(d.WT + (size_t)drow * d.K + d.k0 + 8 * cch) = o; }
;     LDS_WAIT(); asm volatile("" ::: "memory");
.LBB0_207:
	s_waitcnt lgkmcnt(3)
	v_bfe_u32 v129, v108, 16, 1
	v_add3_u32 v108, v108, v129, s31
	v_bfe_u32 v129, v109, 16, 1
	v_lshrrev_b32_e32 v108, 16, v108
	v_add3_u32 v109, v109, v129, s31
	v_and_or_b32 v130, v109, s35, v108
	s_waitcnt lgkmcnt(2)
	v_bfe_u32 v108, v106, 16, 1
	v_add3_u32 v106, v106, v108, s31
	v_bfe_u32 v108, v107, 16, 1
	v_lshrrev_b32_e32 v106, 16, v106
	v_add3_u32 v107, v107, v108, s31
	v_and_or_b32 v131, v107, s35, v106
	s_waitcnt lgkmcnt(1)
	v_bfe_u32 v106, v104, 16, 1
	v_add3_u32 v104, v104, v106, s31
	v_bfe_u32 v106, v105, 16, 1
	v_lshrrev_b32_e32 v104, 16, v104
	v_add3_u32 v105, v105, v106, s31
	v_and_or_b32 v132, v105, s35, v104
	s_waitcnt lgkmcnt(0)
	v_bfe_u32 v104, v102, 16, 1
	v_add3_u32 v102, v102, v104, s31
	v_bfe_u32 v104, v103, 16, 1
	v_lshrrev_b32_e32 v102, 16, v102
	v_add3_u32 v103, v103, v104, s31
	v_and_or_b32 v133, v103, s35, v102
	v_ashrrev_i32_e32 v102, 31, v99
	v_mul_lo_u32 v104, s15, v99
	v_mul_lo_u32 v105, s14, v102
	v_mad_u64_u32 v[102:103], s[16:17], s14, v99, 0
	v_add3_u32 v103, v103, v105, v104
	v_lshl_add_u64 v[102:103], v[102:103], 1, s[10:11]
	v_lshl_add_u64 v[102:103], s[12:13], 1, v[102:103]
	v_lshl_add_u64 v[134:135], v[102:103], 0, v[100:101]
	ds_read2_b32 v[108:109], v113 offset0:16 offset1:49
	ds_read2_b32 v[106:107], v113 offset0:82 offset1:115
	ds_read2_b32 v[104:105], v113 offset0:148 offset1:181
	ds_read2_b32 v[102:103], v113 offset0:214 offset1:247
	v_or_b32_e32 v129, s2, v111
	s_and_b64 vcc, exec, s[0:1]
	s_mov_b64 s[16:17], -1
	global_store_dwordx4 v[134:135], v[130:133], off sc0 sc1
	s_cbranch_vccnz .LBB0_209
	s_lshl_b32 s16, s2, 1
	s_and_b32 s16, s16, 0xffffff00
	v_and_b32_e32 v99, 0x77, v129
	v_or_b32_e32 v99, s16, v99
	v_or_b32_e32 v99, s40, v99
	s_mov_b64 s[16:17], 0

; #define GAS __attribute__((address_space(1)))
; #define LAS __attribute__((address_space(3)))
; #define LDS_WAIT() asm volatile("s_waitcnt lgkmcnt(0)" ::: "memory")
; __device__ __forceinline__ unsigned pk2(float lo, float hi) { return f2bf(lo) | (f2bf(hi) << 16); }
; __device__ __forceinline__ void cv_finish(const CvDesc& d, const f32x4 (&wv)[8], LAS float* scr, int lane) {
;     ...
;     for (int j = 0; j < 4; ++j) { const int n = (lane >> 3) + 8 * j; const LAS float* s = scr + (8 * cch) * 33 + n;
;         v4u o; o.x = pk2(s[0 * 33], s[1 * 33]); o.y = pk2(s[2 * 33], s[3 * 33]); o.z = pk2(s[4 * 33], s[5 * 33]); o.w = pk2(s[6 * 33], s[7 * 33]);
;         const int nn = d.n0 + n; const int drow = d.mode ? (d.row_off + (nn >> 7) * 256 + (nn & 127)) : (d.row_off + nn);
;         *(GAS v4u*)(d.WT + (size_t)drow * d.K + d.k0 + 8 * cch) = o; }
;     LDS_WAIT(); asm volatile("" ::: "memory");
.LBB0_211:
	s_waitcnt lgkmcnt(3)
	v_bfe_u32 v129, v108, 16, 1
	v_add3_u32 v108, v108, v129, s31
	v_bfe_u32 v129, v109, 16, 1
	v_lshrrev_b32_e32 v108, 16, v108
	v_add3_u32 v109, v109, v129, s31
	v_and_or_b32 v130, v109, s35, v108
	s_waitcnt lgkmcnt(2)
	v_bfe_u32 v108, v106, 16, 1
	v_add3_u32 v106, v106, v108, s31
	v_bfe_u32 v108, v107, 16, 1
	v_lshrrev_b32_e32 v106, 16, v106
	v_add3_u32 v107, v107, v108, s31
	v_and_or_b32 v131, v107, s35, v106
	s_waitcnt lgkmcnt(1)
	v_bfe_u32 v106, v104, 16, 1
	v_add3_u32 v104, v104, v106, s31
	v_bfe_u32 v106, v105, 16, 1
	v_lshrrev_b32_e32 v104, 16, v104
	v_add3_u32 v105, v105, v106, s31
	v_and_or_b32 v132, v105, s35, v104
	s_waitcnt lgkmcnt(0)
	v_bfe_u32 v104, v102, 16, 1
	v_add3_u32 v102, v102, v104, s31
	v_bfe_u32 v104, v103, 16, 1
	v_lshrrev_b32_e32 v102, 16, v102
	v_add3_u32 v103, v103, v104, s31
	v_and_or_b32 v133, v103, s35, v102
	v_ashrrev_i32_e32 v102, 31, v99
	v_mul_lo_u32 v104, s15, v99
	v_mul_lo_u32 v105, s14, v102
	v_mad_u64_u32 v[102:103], s[16:17], s14, v99, 0
	v_add3_u32 v103, v103, v105, v104
	v_lshl_add_u64 v[102:103], v[102:103], 1, s[10:11]
	v_lshl_add_u64 v[102:103], s[12:13], 1, v[102:103]
	v_lshl_add_u64 v[134:135], v[102:103], 0, v[100:101]
	ds_read2_b32 v[108:109], v113 offset0:24 offset1:57
	ds_read2_b32 v[106:107], v113 offset0:90 offset1:123
	ds_read2_b32 v[104:105], v113 offset0:156 offset1:189
	ds_read2_b32 v[102:103], v113 offset0:222 offset1:255
	v_or_b32_e32 v129, s2, v112
	s_and_b64 vcc, exec, s[0:1]
	s_mov_b64 s[0:1], -1
	global_store_dwordx4 v[134:135], v[130:133], off sc0 sc1
	s_cbranch_vccnz .LBB0_213
	s_lshl_b32 s0, s2, 1
	s_and_b32 s0, s0, 0xffffff00
	v_and_b32_e32 v99, 0x7f, v129
	v_or_b32_e32 v99, s0, v99
	v_or_b32_e32 v99, s40, v99
	s_mov_b64 s[0:1], 0

; #define GAS __attribute__((address_space(1)))
; #define LAS __attribute__((address_space(3)))
; #define LDS_WAIT() asm volatile("s_waitcnt lgkmcnt(0)" ::: "memory")
; __device__ __forceinline__ unsigned pk2(float lo, float hi) { return f2bf(lo) | (f2bf(hi) << 16); }
; __device__ __forceinline__ void cv_finish(const CvDesc& d, const f32x4 (&wv)[8], LAS float* scr, int lane) {
;     ...
;     for (int j = 0; j < 4; ++j) { const int n = (lane >> 3) + 8 * j; const LAS float* s = scr + (8 * cch) * 33 + n;
;         v4u o; o.x = pk2(s[0 * 33], s[1 * 33]); o.y = pk2(s[2 * 33], s[3 * 33]); o.z = pk2(s[4 * 33], s[5 * 33]); o.w = pk2(s[6 * 33], s[7 * 33]);
;         const int nn = d.n0 + n; const int drow = d.mode ? (d.row_off + (nn >> 7) * 256 + (nn & 127)) : (d.row_off + nn);
;         *(GAS v4u*)(d.WT + (size_t)drow * d.K + d.k0 + 8 * cch) = o; }
;     LDS_WAIT(); asm volatile("" ::: "memory");
; __device__ __forceinline__ void p0_prologue(Frame& F) {
;     ...
;     convert_stream(F, gw < NP0 ? (NP0 - gw + NGW - 1) / NGW : 0, [=](int k) { const int q = gw + k * NGW;
;         if (q < CV_I_IN) return q;
;         if (q < CV_I_IN + CV_I_OUT) return CV_N_IN + (q - CV_I_IN);
;         return cv_deferred_id(q - (CV_I_IN + CV_I_OUT)); });
.LBB0_215:
	s_waitcnt lgkmcnt(3)
	v_bfe_u32 v129, v109, 16, 1
	v_add3_u32 v109, v109, v129, s31
	v_bfe_u32 v129, v108, 16, 1
	v_add3_u32 v108, v108, v129, s31
	v_lshrrev_b32_e32 v108, 16, v108
	v_and_or_b32 v130, v109, s35, v108
	s_waitcnt lgkmcnt(2)
	v_bfe_u32 v108, v107, 16, 1
	v_add3_u32 v107, v107, v108, s31
	v_bfe_u32 v108, v106, 16, 1
	v_add3_u32 v106, v106, v108, s31
	v_lshrrev_b32_e32 v106, 16, v106
	v_and_or_b32 v131, v107, s35, v106
	s_waitcnt lgkmcnt(1)
	v_bfe_u32 v106, v105, 16, 1
	v_add3_u32 v105, v105, v106, s31
	v_bfe_u32 v106, v104, 16, 1
	v_add3_u32 v104, v104, v106, s31
	v_lshrrev_b32_e32 v104, 16, v104
	v_and_or_b32 v132, v105, s35, v104
	s_waitcnt lgkmcnt(0)
	v_bfe_u32 v104, v103, 16, 1
	v_add3_u32 v103, v103, v104, s31
	v_bfe_u32 v104, v102, 16, 1
	v_add3_u32 v102, v102, v104, s31
	v_lshrrev_b32_e32 v102, 16, v102
	v_and_or_b32 v133, v103, s35, v102
	v_ashrrev_i32_e32 v102, 31, v99
	v_mul_lo_u32 v104, s15, v99
	v_mul_lo_u32 v105, s14, v102
	v_mad_u64_u32 v[102:103], s[0:1], s14, v99, 0
	v_add3_u32 v103, v103, v105, v104
	v_lshl_add_u64 v[102:103], v[102:103], 1, s[10:11]
	v_lshl_add_u64 v[102:103], s[12:13], 1, v[102:103]
	v_lshl_add_u64 v[102:103], v[102:103], 0, v[100:101]
	global_store_dwordx4 v[102:103], v[130:133], off sc0 sc1
	s_waitcnt lgkmcnt(0)
	s_andn2_b64 vcc, exec, s[4:5]
	s_cbranch_vccnz .LBB0_91
	s_cmp_ge_i32 s34, s20
	s_cbranch_scc1 .LBB0_241
	s_add_i32 s2, s29, s36
	s_cmpk_lt_i32 s2, 0x1c00
	s_cbranch_scc1 .LBB0_221
	s_cmpk_gt_u32 s2, 0x23ff
	s_mov_b64 s[0:1], -1
	s_cbranch_scc0 .LBB0_222
	s_add_i32 s0, s2, 0xffffdc00
	s_mul_hi_u32 s1, s0, 0xaaaaaaab
	s_lshr_b32 s1, s1, 15
	s_mul_i32 s4, s1, 0xc000
	s_sub_i32 s0, s0, s4
	s_and_b32 s4, s0, 0x3fff
	s_lshl_b32 s0, s0, 1
	s_lshl_b32 s1, s1, 14
	s_and_b32 s0, s0, 0x18000
	s_or_b32 s1, s1, s4
	s_add_i32 s0, s1, s0
	s_add_i32 s5, s0, 0x4800
	s_cbranch_execnz .LBB0_224
	s_branch .LBB0_223

; #define GAS __attribute__((address_space(1)))
; #define LAS __attribute__((address_space(3)))
; #define LDS_WAIT() asm volatile("s_waitcnt lgkmcnt(0)" ::: "memory")
; __device__ __forceinline__ unsigned pk2(float lo, float hi) { return f2bf(lo) | (f2bf(hi) << 16); }
; __device__ __forceinline__ void cv_finish(const CvDesc& d, const f32x4 (&wv)[8], LAS float* scr, int lane) {
;     ...
;     for (int j = 0; j < 4; ++j) { const int n = (lane >> 3) + 8 * j; const LAS float* s = scr + (8 * cch) * 33 + n;
;         v4u o; o.x = pk2(s[0 * 33], s[1 * 33]); o.y = pk2(s[2 * 33], s[3 * 33]); o.z = pk2(s[4 * 33], s[5 * 33]); o.w = pk2(s[6 * 33], s[7 * 33]);
;         const int nn = d.n0 + n; const int drow = d.mode ? (d.row_off + (nn >> 7) * 256 + (nn & 127)) : (d.row_off + nn);
;         *(GAS v4u*)(d.WT + (size_t)drow * d.K + d.k0 + 8 * cch) = o; }
;     LDS_WAIT(); asm volatile("" ::: "memory");
.LBB0_266:
	s_waitcnt lgkmcnt(3)
	v_bfe_u32 v115, v108, 16, 1
	v_add3_u32 v108, v108, v115, s31
	v_bfe_u32 v115, v109, 16, 1
	v_lshrrev_b32_e32 v108, 16, v108
	v_add3_u32 v109, v109, v115, s31
	v_and_or_b32 v116, v109, s35, v108
	s_waitcnt lgkmcnt(2)
	v_bfe_u32 v108, v106, 16, 1
	v_add3_u32 v106, v106, v108, s31
	v_bfe_u32 v108, v107, 16, 1
	v_lshrrev_b32_e32 v106, 16, v106
	v_add3_u32 v107, v107, v108, s31
	v_and_or_b32 v117, v107, s35, v106
	s_waitcnt lgkmcnt(1)
	v_bfe_u32 v106, v104, 16, 1
	v_add3_u32 v104, v104, v106, s31
	v_bfe_u32 v106, v105, 16, 1
	v_lshrrev_b32_e32 v104, 16, v104
	v_add3_u32 v105, v105, v106, s31
	v_and_or_b32 v118, v105, s35, v104
	s_waitcnt lgkmcnt(0)
	v_bfe_u32 v104, v102, 16, 1
	v_add3_u32 v102, v102, v104, s31
	v_bfe_u32 v104, v103, 16, 1
	v_lshrrev_b32_e32 v102, 16, v102
	v_add3_u32 v103, v103, v104, s31
	v_and_or_b32 v119, v103, s35, v102
	v_ashrrev_i32_e32 v102, 31, v99
	v_mul_lo_u32 v104, s13, v99
	v_mul_lo_u32 v105, s12, v102
	v_mad_u64_u32 v[102:103], s[14:15], s12, v99, 0
	v_add3_u32 v103, v103, v105, v104
	v_lshl_add_u64 v[102:103], v[102:103], 1, s[4:5]
	s_ashr_i32 s11, s10, 31
	v_lshl_add_u64 v[102:103], s[10:11], 1, v[102:103]
	v_lshl_add_u64 v[102:103], v[102:103], 0, v[100:101]
	global_store_dwordx4 v[102:103], v[116:119], off sc0 sc1
	ds_read2_b32 v[108:109], v113 offset0:8 offset1:41
	ds_read2_b32 v[106:107], v113 offset0:74 offset1:107
	ds_read2_b32 v[104:105], v113 offset0:140 offset1:173
	ds_read2_b32 v[102:103], v113 offset0:206 offset1:239
	s_xor_b64 s[14:15], s[0:1], -1
	v_cndmask_b32_e64 v99, 0, 1, s[14:15]
	v_or_b32_e32 v115, s2, v110
	v_cmp_ne_u32_e64 s[0:1], 1, v99
	s_andn2_b64 vcc, exec, s[14:15]
	s_mov_b64 s[14:15], -1
	s_cbranch_vccnz .LBB0_268
	s_lshl_b32 s14, s2, 1
	s_and_b32 s14, s14, 0xffffff00
	v_and_b32_e32 v99, 0x6f, v115
	v_or_b32_e32 v99, s14, v99
	v_or_b32_e32 v99, s16, v99
	s_mov_b64 s[14:15], 0

; #define GAS __attribute__((address_space(1)))
; #define LAS __attribute__((address_space(3)))
; #define LDS_WAIT() asm volatile("s_waitcnt lgkmcnt(0)" ::: "memory")
; __device__ __forceinline__ unsigned pk2(float lo, float hi) { return f2bf(lo) | (f2bf(hi) << 16); }
; __device__ __forceinline__ void cv_finish(const CvDesc& d, const f32x4 (&wv)[8], LAS float* scr, int lane) {
;     ...
;     for (int j = 0; j < 4; ++j) { const int n = (lane >> 3) + 8 * j; const LAS float* s = scr + (8 * cch) * 33 + n;
;         v4u o; o.x = pk2(s[0 * 33], s[1 * 33]); o.y = pk2(s[2 * 33], s[3 * 33]); o.z = pk2(s[4 * 33], s[5 * 33]); o.w = pk2(s[6 * 33], s[7 * 33]);
;         const int nn = d.n0 + n; const int drow = d.mode ? (d.row_off + (nn >> 7) * 256 + (nn & 127)) : (d.row_off + nn);
;         *(GAS v4u*)(d.WT + (size_t)drow * d.K + d.k0 + 8 * cch) = o; }
;     LDS_WAIT(); asm volatile("" ::: "memory");
.LBB0_270:
	s_waitcnt lgkmcnt(3)
	v_bfe_u32 v115, v108, 16, 1
	v_add3_u32 v108, v108, v115, s31
	v_bfe_u32 v115, v109, 16, 1
	v_lshrrev_b32_e32 v108, 16, v108
	v_add3_u32 v109, v109, v115, s31
	v_and_or_b32 v116, v109, s35, v108
	s_waitcnt lgkmcnt(2)
	v_bfe_u32 v108, v106, 16, 1
	v_add3_u32 v106, v106, v108, s31
	v_bfe_u32 v108, v107, 16, 1
	v_lshrrev_b32_e32 v106, 16, v106
	v_add3_u32 v107, v107, v108, s31
	v_and_or_b32 v117, v107, s35, v106
	s_waitcnt lgkmcnt(1)
	v_bfe_u32 v106, v104, 16, 1
	v_add3_u32 v104, v104, v106, s31
	v_bfe_u32 v106, v105, 16, 1
	v_lshrrev_b32_e32 v104, 16, v104
	v_add3_u32 v105, v105, v106, s31
	v_and_or_b32 v118, v105, s35, v104
	s_waitcnt lgkmcnt(0)
	v_bfe_u32 v104, v102, 16, 1
	v_add3_u32 v102, v102, v104, s31
	v_bfe_u32 v104, v103, 16, 1
	v_lshrrev_b32_e32 v102, 16, v102
	v_add3_u32 v103, v103, v104, s31
	v_and_or_b32 v119, v103, s35, v102
	v_ashrrev_i32_e32 v102, 31, v99
	v_mul_lo_u32 v104, s13, v99
	v_mul_lo_u32 v105, s12, v102
	v_mad_u64_u32 v[102:103], s[14:15], s12, v99, 0
	v_add3_u32 v103, v103, v105, v104
	v_lshl_add_u64 v[102:103], v[102:103], 1, s[4:5]
	v_lshl_add_u64 v[102:103], s[10:11], 1, v[102:103]
	v_lshl_add_u64 v[120:121], v[102:103], 0, v[100:101]
	ds_read2_b32 v[108:109], v113 offset0:16 offset1:49
	ds_read2_b32 v[106:107], v113 offset0:82 offset1:115
	ds_read2_b32 v[104:105], v113 offset0:148 offset1:181
	ds_read2_b32 v[102:103], v113 offset0:214 offset1:247
	v_or_b32_e32 v115, s2, v111
	s_and_b64 vcc, exec, s[0:1]
	s_mov_b64 s[14:15], -1
	global_store_dwordx4 v[120:121], v[116:119], off sc0 sc1
	s_cbranch_vccnz .LBB0_272
	s_lshl_b32 s14, s2, 1
	s_and_b32 s14, s14, 0xffffff00
	v_and_b32_e32 v99, 0x77, v115
	v_or_b32_e32 v99, s14, v99
	v_or_b32_e32 v99, s16, v99
	s_mov_b64 s[14:15], 0

; #define GAS __attribute__((address_space(1)))
; #define LAS __attribute__((address_space(3)))
; #define LDS_WAIT() asm volatile("s_waitcnt lgkmcnt(0)" ::: "memory")
; __device__ __forceinline__ unsigned pk2(float lo, float hi) { return f2bf(lo) | (f2bf(hi) << 16); }
; __device__ __forceinline__ void cv_finish(const CvDesc& d, const f32x4 (&wv)[8], LAS float* scr, int lane) {
;     ...
;     for (int j = 0; j < 4; ++j) { const int n = (lane >> 3) + 8 * j; const LAS float* s = scr + (8 * cch) * 33 + n;
;         v4u o; o.x = pk2(s[0 * 33], s[1 * 33]); o.y = pk2(s[2 * 33], s[3 * 33]); o.z = pk2(s[4 * 33], s[5 * 33]); o.w = pk2(s[6 * 33], s[7 * 33]);
;         const int nn = d.n0 + n; const int drow = d.mode ? (d.row_off + (nn >> 7) * 256 + (nn & 127)) : (d.row_off + nn);
;         *(GAS v4u*)(d.WT + (size_t)drow * d.K + d.k0 + 8 * cch) = o; }
;     LDS_WAIT(); asm volatile("" ::: "memory");
.LBB0_274:
	s_waitcnt lgkmcnt(3)
	v_bfe_u32 v115, v108, 16, 1
	v_add3_u32 v108, v108, v115, s31
	v_bfe_u32 v115, v109, 16, 1
	v_lshrrev_b32_e32 v108, 16, v108
	v_add3_u32 v109, v109, v115, s31
	v_and_or_b32 v116, v109, s35, v108
	s_waitcnt lgkmcnt(2)
	v_bfe_u32 v108, v106, 16, 1
	v_add3_u32 v106, v106, v108, s31
	v_bfe_u32 v108, v107, 16, 1
	v_lshrrev_b32_e32 v106, 16, v106
	v_add3_u32 v107, v107, v108, s31
	v_and_or_b32 v117, v107, s35, v106
	s_waitcnt lgkmcnt(1)
	v_bfe_u32 v106, v104, 16, 1
	v_add3_u32 v104, v104, v106, s31
	v_bfe_u32 v106, v105, 16, 1
	v_lshrrev_b32_e32 v104, 16, v104
	v_add3_u32 v105, v105, v106, s31
	v_and_or_b32 v118, v105, s35, v104
	s_waitcnt lgkmcnt(0)
	v_bfe_u32 v104, v102, 16, 1
	v_add3_u32 v102, v102, v104, s31
	v_bfe_u32 v104, v103, 16, 1
	v_lshrrev_b32_e32 v102, 16, v102
	v_add3_u32 v103, v103, v104, s31
	v_and_or_b32 v119, v103, s35, v102
	v_ashrrev_i32_e32 v102, 31, v99
	v_mul_lo_u32 v104, s13, v99
	v_mul_lo_u32 v105, s12, v102
	v_mad_u64_u32 v[102:103], s[14:15], s12, v99, 0
	v_add3_u32 v103, v103, v105, v104
	v_lshl_add_u64 v[102:103], v[102:103], 1, s[4:5]
	v_lshl_add_u64 v[102:103], s[10:11], 1, v[102:103]
	v_lshl_add_u64 v[120:121], v[102:103], 0, v[100:101]
	ds_read2_b32 v[108:109], v113 offset0:24 offset1:57
	ds_read2_b32 v[106:107], v113 offset0:90 offset1:123
	ds_read2_b32 v[104:105], v113 offset0:156 offset1:189
	ds_read2_b32 v[102:103], v113 offset0:222 offset1:255
	v_or_b32_e32 v115, s2, v112
	s_and_b64 vcc, exec, s[0:1]
	s_mov_b64 s[0:1], -1
	global_store_dwordx4 v[120:121], v[116:119], off sc0 sc1
	s_cbranch_vccnz .LBB0_276
	s_lshl_b32 s0, s2, 1
	s_and_b32 s0, s0, 0xffffff00
	v_and_b32_e32 v99, 0x7f, v115
	v_or_b32_e32 v99, s0, v99
	v_or_b32_e32 v99, s16, v99
	s_mov_b64 s[0:1], 0

; __device__ __forceinline__ void p1_modulate(Frame& F) {
;     ...
;     for (int o = (int)blockIdx.x * 512 + F.tid; o < DEPTH * 3 * 12288 / 4; o += F.G * 512) { const int l = o / (3 * 3072), rn = o % (3 * 3072), r = rn / 3072, n = 4 * (rn % 3072);
;         f32x4 sm = *(const f32x4*)(F.b_mod + (size_t)l * 12288 + n);
; #pragma unroll
;         for (int ks = 0; ks < 16; ++ks) sm += *(const f32x4*)(PART + ((size_t)((l * 16 + ks) * 3 + r)) * 12288 + n);
;         *(f32x4*)(MOD + ((size_t)l * 3 + r) * 12288 + n) = sm; }
.LBB0_333:
	s_waitcnt vmcnt(10)
	v_mul_hi_i32 v6, v4, s11
	v_lshrrev_b32_e32 v7, 31, v6
	v_ashrrev_i32_e32 v6, 11, v6
	v_add_u32_e32 v75, v6, v7
	v_mul_i32_i24_e32 v8, 0x2400, v75
	v_sub_u32_e32 v8, v4, v8
	v_mul_i32_i24_e32 v9, 0x2aab, v8
	s_waitcnt vmcnt(9)
	v_lshrrev_b32_e32 v10, 31, v9
	v_ashrrev_i32_e32 v9, 25, v9
	v_add_u16_e32 v9, v9, v10
	v_bfe_i32 v74, v9, 0, 16
	v_mul_lo_u16_e32 v9, 0xc00, v9
	v_sub_u16_e32 v8, v8, v9
	v_lshlrev_b32_sdwa v8, v5, sext(v8) dst_sel:DWORD dst_unused:UNUSED_PAD src0_sel:DWORD src1_sel:WORD_0
	v_mul_hi_i32_i24_e32 v7, 0xc000, v75
	v_mul_i32_i24_e32 v6, 0xc000, v75
	v_ashrrev_i32_e32 v9, 31, v8
	v_lshl_add_u64 v[6:7], s[82:83], 0, v[6:7]
	v_lshlrev_b64 v[76:77], 2, v[8:9]
	v_lshl_add_u64 v[6:7], v[6:7], 0, v[76:77]
	global_load_dwordx4 v[6:9], v[6:7], off
	v_mad_i32_i24 v12, v75, 48, v74
	s_waitcnt vmcnt(9)
	v_add_u32_e32 v14, 3, v12
	v_add_u32_e32 v16, 6, v12
	v_add_u32_e32 v17, 9, v12
	s_waitcnt vmcnt(8)
	v_add_u32_e32 v20, 12, v12
	v_add_u32_e32 v21, 15, v12
	s_waitcnt vmcnt(7)
	v_add_u32_e32 v24, 18, v12
	v_add_u32_e32 v25, 21, v12
	s_waitcnt vmcnt(6)
	v_add_u32_e32 v28, 24, v12
	v_add_u32_e32 v29, 27, v12
	s_waitcnt vmcnt(5)
	v_add_u32_e32 v32, 30, v12
	v_add_u32_e32 v33, 33, v12
	v_add_u32_e32 v36, 36, v12
	v_add_u32_e32 v37, 39, v12
	v_add_u32_e32 v40, 42, v12
	v_add_u32_e32 v41, 45, v12
	v_lshl_add_u64 v[10:11], s[2:3], 0, v[76:77]
	v_mad_i64_i32 v[12:13], s[16:17], v12, s13, v[10:11]
	v_mad_i64_i32 v[14:15], s[16:17], v14, s13, v[10:11]
	v_mad_i64_i32 v[18:19], s[16:17], v16, s13, v[10:11]
	v_mad_i64_i32 v[22:23], s[16:17], v17, s13, v[10:11]
	v_mad_i64_i32 v[26:27], s[16:17], v20, s13, v[10:11]
	v_mad_i64_i32 v[30:31], s[16:17], v21, s13, v[10:11]
	v_mad_i64_i32 v[34:35], s[16:17], v24, s13, v[10:11]
	v_mad_i64_i32 v[38:39], s[16:17], v25, s13, v[10:11]
	v_mad_i64_i32 v[42:43], s[16:17], v28, s13, v[10:11]
	v_mad_i64_i32 v[46:47], s[16:17], v29, s13, v[10:11]
	v_mad_i64_i32 v[50:51], s[16:17], v32, s13, v[10:11]
	v_mad_i64_i32 v[54:55], s[16:17], v33, s13, v[10:11]
	v_mad_i64_i32 v[58:59], s[16:17], v36, s13, v[10:11]
	v_mad_i64_i32 v[62:63], s[16:17], v37, s13, v[10:11]
	v_mad_i64_i32 v[66:67], s[16:17], v40, s13, v[10:11]
	v_mad_i64_i32 v[70:71], s[16:17], v41, s13, v[10:11]
	global_load_dwordx4 v[10:13], v[12:13], off
	s_nop 0
	global_load_dwordx4 v[14:17], v[14:15], off
	s_nop 0
	global_load_dwordx4 v[18:21], v[18:19], off
	s_nop 0
	global_load_dwordx4 v[22:25], v[22:23], off
	s_nop 0
	global_load_dwordx4 v[26:29], v[26:27], off
	s_nop 0
	global_load_dwordx4 v[30:33], v[30:31], off
	s_nop 0
	global_load_dwordx4 v[34:37], v[34:35], off
	s_nop 0
	global_load_dwordx4 v[38:41], v[38:39], off
	s_nop 0
	global_load_dwordx4 v[42:45], v[42:43], off
	s_nop 0
	global_load_dwordx4 v[46:49], v[46:47], off
	s_nop 0
	global_load_dwordx4 v[50:53], v[50:51], off
	s_nop 0
	global_load_dwordx4 v[54:57], v[54:55], off
	s_nop 0
	global_load_dwordx4 v[58:61], v[58:59], off
	s_nop 0
	global_load_dwordx4 v[62:65], v[62:63], off
	s_nop 0
	global_load_dwordx4 v[66:69], v[66:67], off
	s_nop 0
	global_load_dwordx4 v[70:73], v[70:71], off
	v_mul_hi_i32_i24_e32 v79, 3, v75
	v_mul_i32_i24_e32 v78, 3, v75
	v_ashrrev_i32_e32 v75, 31, v74
	v_lshl_add_u64 v[74:75], v[78:79], 0, v[74:75]
	v_mad_u64_u32 v[78:79], s[16:17], v74, s13, v[2:3]
	v_mov_b32_e32 v74, v79
	v_add_u32_e32 v4, s10, v4
	v_mad_u64_u32 v[74:75], s[16:17], v75, s13, v[74:75]
	v_cmp_lt_i32_e32 vcc, s14, v4
	v_mov_b32_e32 v79, v74
	s_or_b64 s[8:9], vcc, s[8:9]
	v_lshl_add_u64 v[74:75], v[78:79], 0, v[76:77]
	s_waitcnt vmcnt(15)
	v_pk_add_f32 v[8:9], v[8:9], v[12:13]
	v_pk_add_f32 v[6:7], v[6:7], v[10:11]
	s_waitcnt vmcnt(14)
	v_pk_add_f32 v[8:9], v[8:9], v[16:17]
	v_pk_add_f32 v[6:7], v[6:7], v[14:15]
	s_waitcnt vmcnt(13)
	v_pk_add_f32 v[8:9], v[8:9], v[20:21]
	v_pk_add_f32 v[6:7], v[6:7], v[18:19]
	s_waitcnt vmcnt(12)
	v_pk_add_f32 v[8:9], v[8:9], v[24:25]
	v_pk_add_f32 v[6:7], v[6:7], v[22:23]
	s_waitcnt vmcnt(11)
	v_pk_add_f32 v[8:9], v[8:9], v[28:29]
	v_pk_add_f32 v[6:7], v[6:7], v[26:27]
	s_waitcnt vmcnt(10)
	v_pk_add_f32 v[8:9], v[8:9], v[32:33]
	v_pk_add_f32 v[6:7], v[6:7], v[30:31]
	s_waitcnt vmcnt(9)
	v_pk_add_f32 v[8:9], v[8:9], v[36:37]
	v_pk_add_f32 v[6:7], v[6:7], v[34:35]
	s_waitcnt vmcnt(8)
	v_pk_add_f32 v[8:9], v[8:9], v[40:41]
	v_pk_add_f32 v[6:7], v[6:7], v[38:39]
	s_waitcnt vmcnt(7)
	v_pk_add_f32 v[8:9], v[8:9], v[44:45]
	v_pk_add_f32 v[6:7], v[6:7], v[42:43]
	s_waitcnt vmcnt(6)
	v_pk_add_f32 v[8:9], v[8:9], v[48:49]
	v_pk_add_f32 v[6:7], v[6:7], v[46:47]
	s_waitcnt vmcnt(5)
	v_pk_add_f32 v[8:9], v[8:9], v[52:53]
	v_pk_add_f32 v[6:7], v[6:7], v[50:51]
	s_waitcnt vmcnt(4)
	v_pk_add_f32 v[8:9], v[8:9], v[56:57]
	v_pk_add_f32 v[6:7], v[6:7], v[54:55]
	s_waitcnt vmcnt(3)
	v_pk_add_f32 v[8:9], v[8:9], v[60:61]
	v_pk_add_f32 v[6:7], v[6:7], v[58:59]
	s_waitcnt vmcnt(2)
	v_pk_add_f32 v[8:9], v[8:9], v[64:65]
	v_pk_add_f32 v[6:7], v[6:7], v[62:63]
	s_waitcnt vmcnt(1)
	v_pk_add_f32 v[8:9], v[8:9], v[68:69]
	v_pk_add_f32 v[6:7], v[6:7], v[66:67]
	s_waitcnt vmcnt(0)
	v_pk_add_f32 v[8:9], v[8:9], v[72:73]
	v_pk_add_f32 v[6:7], v[6:7], v[70:71]
	global_store_dwordx4 v[74:75], v[6:9], off sc0 sc1
	s_andn2_b64 exec, exec, s[8:9]
	s_cbranch_execnz .LBB0_333

;     __device__ __forceinline__ void operator()(const f32x4 (&acc)[2][2][4][2], const Unit& u, int wr, int wc, int fr, int fq) const {
;     ...
;         if (pn >= 24) {
;             float* base = GF + (size_t)((pn - 24) >> 1) * ((size_t)MROWS * 512) + ((pn - 24) & 1) * 256 + wc * 32 + 4 * fq;
; #pragma unroll
;             for (int ai = 0; ai < 2; ++ai)
; #pragma unroll
;                 for (int m = 0; m < 4; ++m) { float* rowp = base + (size_t)(row0 + ai * HALF + m * 16) * 512;
; #pragma unroll
;                     for (int bj = 0; bj < 2; ++bj)
; #pragma unroll
;                         for (int n = 0; n < 2; ++n) *(f32x4*)(rowp + bj * HALF + n * 16) = acc[ai][bj][m][n]; }
;             return;
.LBB0_421:
	s_and_b64 vcc, exec, s[18:19]
	s_cbranch_vccz .LBB0_429
	s_sub_i32 s11, s46, 24
	s_lshr_b32 s11, s11, 1
	s_mul_hi_u32 s13, s11, 0x2100000
	s_mul_i32 s11, s11, 0x2100000
	v_readlane_b32 s18, v251, 9
	v_readlane_b32 s19, v251, 10
	s_add_u32 s11, s18, s11
	s_addc_u32 s13, s19, s13
	s_lshl_b32 s18, s46, 10
	s_and_b32 s18, s18, 0x400
	s_add_u32 s11, s11, s18
	s_addc_u32 s13, s13, 0
	s_add_u32 s18, s11, s45
	s_addc_u32 s19, s13, 0
	v_mov_b32_e32 v139, v147
	v_ashrrev_i32_e32 v141, 31, v140
	v_lshl_add_u64 v[142:143], s[18:19], 0, v[138:139]
	v_lshlrev_b64 v[148:149], 11, v[140:141]
	v_lshl_add_u64 v[148:149], v[142:143], 0, v[148:149]
	global_store_dwordx4 v[148:149], v[126:129], off sc0 sc1
	global_store_dwordx4 v[148:149], v[122:125], off offset:64 sc0 sc1
	global_store_dwordx4 v[148:149], v[110:113], off offset:512 sc0 sc1
	global_store_dwordx4 v[148:149], v[102:105], off offset:576 sc0 sc1
	s_mov_b32 s11, 0x40000
	s_mov_b64 s[18:19], 0x40000
	v_or_b32_e32 v102, 16, v140
	v_ashrrev_i32_e32 v103, 31, v102
	v_lshlrev_b64 v[102:103], 11, v[102:103]
	v_lshl_add_u64 v[102:103], v[142:143], 0, v[102:103]
	global_store_dwordx4 v[102:103], v[118:121], off sc0 sc1
	global_store_dwordx4 v[102:103], v[114:117], off offset:64 sc0 sc1
	global_store_dwordx4 v[102:103], v[94:97], off offset:512 sc0 sc1
	global_store_dwordx4 v[102:103], v[86:89], off offset:576 sc0 sc1
	s_nop 1
	v_or_b32_e32 v86, 32, v140
	v_ashrrev_i32_e32 v87, 31, v86
	v_lshlrev_b64 v[86:87], 11, v[86:87]
	v_lshl_add_u64 v[86:87], v[142:143], 0, v[86:87]
	global_store_dwordx4 v[86:87], v[106:109], off sc0 sc1
	global_store_dwordx4 v[86:87], v[98:101], off offset:64 sc0 sc1
	global_store_dwordx4 v[86:87], v[78:81], off offset:512 sc0 sc1
	global_store_dwordx4 v[86:87], v[74:77], off offset:576 sc0 sc1
	s_nop 1
	v_or_b32_e32 v74, 48, v140
	v_ashrrev_i32_e32 v75, 31, v74
	v_lshlrev_b64 v[74:75], 11, v[74:75]
	v_lshl_add_u64 v[74:75], v[142:143], 0, v[74:75]
	global_store_dwordx4 v[74:75], v[90:93], off sc0 sc1
	global_store_dwordx4 v[74:75], v[82:85], off offset:64 sc0 sc1
	global_store_dwordx4 v[74:75], v[70:73], off offset:512 sc0 sc1
	global_store_dwordx4 v[74:75], v[66:69], off offset:576 sc0 sc1
	s_nop 1
	v_add_co_u32_e32 v68, vcc, s11, v148
	s_mov_b32 s11, 0x48000
	s_nop 0
	v_addc_co_u32_e32 v69, vcc, 0, v149, vcc
	v_lshl_add_u64 v[66:67], v[148:149], 0, s[18:19]
	global_store_dwordx4 v[68:69], v[62:65], off sc0 sc1
	global_store_dwordx4 v[66:67], v[58:61], off offset:64 sc0 sc1
	global_store_dwordx4 v[66:67], v[46:49], off offset:512 sc0 sc1
	global_store_dwordx4 v[66:67], v[42:45], off offset:576 sc0 sc1
	s_mov_b64 s[18:19], 0x48000
	s_nop 0
	v_add_co_u32_e32 v44, vcc, s11, v148
	v_lshl_add_u64 v[42:43], v[148:149], 0, s[18:19]
	s_nop 0
	v_addc_co_u32_e32 v45, vcc, 0, v149, vcc
	global_store_dwordx4 v[44:45], v[54:57], off sc0 sc1
	global_store_dwordx4 v[42:43], v[50:53], off offset:64 sc0 sc1
	global_store_dwordx4 v[42:43], v[30:33], off offset:512 sc0 sc1
	global_store_dwordx4 v[42:43], v[26:29], off offset:576 sc0 sc1
	s_mov_b64 s[18:19], 0x50000
	s_nop 0
	v_add_co_u32_e32 v28, vcc, 0x50000, v148
	v_lshl_add_u64 v[26:27], v[148:149], 0, s[18:19]
	s_nop 0
	v_addc_co_u32_e32 v29, vcc, 0, v149, vcc
	global_store_dwordx4 v[28:29], v[38:41], off sc0 sc1
	global_store_dwordx4 v[26:27], v[34:37], off offset:64 sc0 sc1
	global_store_dwordx4 v[26:27], v[14:17], off offset:512 sc0 sc1
	global_store_dwordx4 v[26:27], v[10:13], off offset:576 sc0 sc1
	s_mov_b64 s[18:19], 0x58000
	s_nop 0
	v_add_co_u32_e32 v12, vcc, 0x58000, v148
	v_lshl_add_u64 v[10:11], v[148:149], 0, s[18:19]
	s_nop 0
	v_addc_co_u32_e32 v13, vcc, 0, v149, vcc
	global_store_dwordx4 v[12:13], v[22:25], off sc0 sc1
	global_store_dwordx4 v[10:11], v[18:21], off offset:64 sc0 sc1
	global_store_dwordx4 v[10:11], v[6:9], off offset:512 sc0 sc1
	global_store_dwordx4 v[10:11], v[2:5], off offset:576 sc0 sc1
	s_andn2_b64 vcc, exec, s[4:5]
	s_mov_b64 s[4:5], -1
	s_cbranch_vccnz .LBB0_409
	s_branch .LBB0_430

; #define GAS __attribute__((address_space(1)))
; #define LAS __attribute__((address_space(3)))
; #define LDS_WAIT() asm volatile("s_waitcnt lgkmcnt(0)" ::: "memory")
; __device__ __forceinline__ unsigned pk2(float lo, float hi) { return f2bf(lo) | (f2bf(hi) << 16); }
; __device__ __forceinline__ void cv_finish(const CvDesc& d, const f32x4 (&wv)[8], LAS float* scr, int lane) {
;     ...
;     for (int j = 0; j < 4; ++j) { const int n = (lane >> 3) + 8 * j; const LAS float* s = scr + (8 * cch) * 33 + n;
;         v4u o; o.x = pk2(s[0 * 33], s[1 * 33]); o.y = pk2(s[2 * 33], s[3 * 33]); o.z = pk2(s[4 * 33], s[5 * 33]); o.w = pk2(s[6 * 33], s[7 * 33]);
;         const int nn = d.n0 + n; const int drow = d.mode ? (d.row_off + (nn >> 7) * 256 + (nn & 127)) : (d.row_off + nn);
;         *(GAS v4u*)(d.WT + (size_t)drow * d.K + d.k0 + 8 * cch) = o; }
;     LDS_WAIT(); asm volatile("" ::: "memory");
.LBB0_472:
	s_waitcnt lgkmcnt(3)
	v_bfe_u32 v114, v109, 16, 1
	v_add3_u32 v109, v109, v114, s70
	v_bfe_u32 v114, v108, 16, 1
	v_add3_u32 v108, v108, v114, s70
	v_lshrrev_b32_e32 v108, 16, v108
	v_and_or_b32 v114, v109, s33, v108
	s_waitcnt lgkmcnt(2)
	v_bfe_u32 v108, v107, 16, 1
	v_add3_u32 v107, v107, v108, s70
	v_bfe_u32 v108, v106, 16, 1
	v_add3_u32 v106, v106, v108, s70
	v_lshrrev_b32_e32 v106, 16, v106
	v_and_or_b32 v115, v107, s33, v106
	s_waitcnt lgkmcnt(1)
	v_bfe_u32 v106, v105, 16, 1
	v_add3_u32 v105, v105, v106, s70
	v_bfe_u32 v106, v104, 16, 1
	v_add3_u32 v104, v104, v106, s70
	v_lshrrev_b32_e32 v104, 16, v104
	v_and_or_b32 v116, v105, s33, v104
	s_waitcnt lgkmcnt(0)
	v_bfe_u32 v104, v103, 16, 1
	v_add3_u32 v103, v103, v104, s70
	v_bfe_u32 v104, v102, 16, 1
	v_add3_u32 v102, v102, v104, s70
	v_lshrrev_b32_e32 v102, 16, v102
	v_and_or_b32 v117, v103, s33, v102
	v_ashrrev_i32_e32 v102, 31, v99
	v_mul_lo_u32 v104, s9, v99
	v_mul_lo_u32 v105, s8, v102
	v_mad_u64_u32 v[102:103], s[0:1], s8, v99, 0
	v_add3_u32 v103, v103, v105, v104
	v_lshl_add_u64 v[102:103], v[102:103], 1, s[4:5]
	v_lshl_add_u64 v[102:103], s[6:7], 1, v[102:103]
	v_lshl_add_u64 v[102:103], v[102:103], 0, v[146:147]
	global_store_dwordx4 v[102:103], v[114:117], off sc0 sc1
	s_waitcnt lgkmcnt(0)

; #define GAS __attribute__((address_space(1)))
; #define LAS __attribute__((address_space(3)))
; #define LDS_WAIT() asm volatile("s_waitcnt lgkmcnt(0)" ::: "memory")
; __device__ __forceinline__ unsigned pk2(float lo, float hi) { return f2bf(lo) | (f2bf(hi) << 16); }
; __device__ __forceinline__ void cv_finish(const CvDesc& d, const f32x4 (&wv)[8], LAS float* scr, int lane) {
;     ...
;     for (int j = 0; j < 4; ++j) { const int n = (lane >> 3) + 8 * j; const LAS float* s = scr + (8 * cch) * 33 + n;
;         v4u o; o.x = pk2(s[0 * 33], s[1 * 33]); o.y = pk2(s[2 * 33], s[3 * 33]); o.z = pk2(s[4 * 33], s[5 * 33]); o.w = pk2(s[6 * 33], s[7 * 33]);
;         const int nn = d.n0 + n; const int drow = d.mode ? (d.row_off + (nn >> 7) * 256 + (nn & 127)) : (d.row_off + nn);
;         *(GAS v4u*)(d.WT + (size_t)drow * d.K + d.k0 + 8 * cch) = o; }
;     LDS_WAIT(); asm volatile("" ::: "memory");
.LBB0_511:
	s_waitcnt lgkmcnt(3)
	v_bfe_u32 v128, v108, 16, 1
	v_add3_u32 v108, v108, v128, s70
	v_bfe_u32 v128, v109, 16, 1
	v_lshrrev_b32_e32 v108, 16, v108
	v_add3_u32 v109, v109, v128, s70
	v_and_or_b32 v128, v109, s33, v108
	s_waitcnt lgkmcnt(2)
	v_bfe_u32 v108, v106, 16, 1
	v_add3_u32 v106, v106, v108, s70
	v_bfe_u32 v108, v107, 16, 1
	v_lshrrev_b32_e32 v106, 16, v106
	v_add3_u32 v107, v107, v108, s70
	v_and_or_b32 v129, v107, s33, v106
	s_waitcnt lgkmcnt(1)
	v_bfe_u32 v106, v104, 16, 1
	v_add3_u32 v104, v104, v106, s70
	v_bfe_u32 v106, v105, 16, 1
	v_lshrrev_b32_e32 v104, 16, v104
	v_add3_u32 v105, v105, v106, s70
	v_and_or_b32 v130, v105, s33, v104
	s_waitcnt lgkmcnt(0)
	v_bfe_u32 v104, v102, 16, 1
	v_add3_u32 v102, v102, v104, s70
	v_bfe_u32 v104, v103, 16, 1
	v_lshrrev_b32_e32 v102, 16, v102
	v_add3_u32 v103, v103, v104, s70
	v_and_or_b32 v131, v103, s33, v102
	v_ashrrev_i32_e32 v102, 31, v99
	v_mul_lo_u32 v104, s11, v99
	v_mul_lo_u32 v105, s10, v102
	v_mad_u64_u32 v[102:103], s[12:13], s10, v99, 0
	v_add3_u32 v103, v103, v105, v104
	v_lshl_add_u64 v[102:103], v[102:103], 1, s[6:7]
	s_ashr_i32 s9, s8, 31
	v_lshl_add_u64 v[102:103], s[8:9], 1, v[102:103]
	v_lshlrev_b32_e32 v146, 1, v100
	v_lshl_add_u64 v[102:103], v[102:103], 0, v[146:147]
	global_store_dwordx4 v[102:103], v[128:131], off sc0 sc1
	ds_read2_b32 v[108:109], v112 offset0:8 offset1:41
	ds_read2_b32 v[106:107], v112 offset0:74 offset1:107
	ds_read2_b32 v[104:105], v112 offset0:140 offset1:173
	ds_read2_b32 v[102:103], v112 offset0:206 offset1:239
	s_xor_b64 s[12:13], s[0:1], -1
	v_cndmask_b32_e64 v99, 0, 1, s[12:13]
	v_or_b32_e32 v128, s21, v101
	v_cmp_ne_u32_e64 s[0:1], 1, v99
	s_andn2_b64 vcc, exec, s[12:13]
	s_mov_b64 s[12:13], -1
	s_cbranch_vccnz .LBB0_513
	s_lshl_b32 s12, s21, 1
	s_and_b32 s12, s12, 0xffffff00
	v_and_b32_e32 v99, 0x6f, v128
	v_or_b32_e32 v99, s12, v99
	v_or_b32_e32 v99, s22, v99
	s_mov_b64 s[12:13], 0

; #define GAS __attribute__((address_space(1)))
; #define LAS __attribute__((address_space(3)))
; #define LDS_WAIT() asm volatile("s_waitcnt lgkmcnt(0)" ::: "memory")
; __device__ __forceinline__ unsigned pk2(float lo, float hi) { return f2bf(lo) | (f2bf(hi) << 16); }
; __device__ __forceinline__ void cv_finish(const CvDesc& d, const f32x4 (&wv)[8], LAS float* scr, int lane) {
;     ...
;     for (int j = 0; j < 4; ++j) { const int n = (lane >> 3) + 8 * j; const LAS float* s = scr + (8 * cch) * 33 + n;
;         v4u o; o.x = pk2(s[0 * 33], s[1 * 33]); o.y = pk2(s[2 * 33], s[3 * 33]); o.z = pk2(s[4 * 33], s[5 * 33]); o.w = pk2(s[6 * 33], s[7 * 33]);
;         const int nn = d.n0 + n; const int drow = d.mode ? (d.row_off + (nn >> 7) * 256 + (nn & 127)) : (d.row_off + nn);
;         *(GAS v4u*)(d.WT + (size_t)drow * d.K + d.k0 + 8 * cch) = o; }
;     LDS_WAIT(); asm volatile("" ::: "memory");
.LBB0_515:
	s_waitcnt lgkmcnt(3)
	v_bfe_u32 v128, v108, 16, 1
	v_add3_u32 v108, v108, v128, s70
	v_bfe_u32 v128, v109, 16, 1
	v_lshrrev_b32_e32 v108, 16, v108
	v_add3_u32 v109, v109, v128, s70
	v_and_or_b32 v128, v109, s33, v108
	s_waitcnt lgkmcnt(2)
	v_bfe_u32 v108, v106, 16, 1
	v_add3_u32 v106, v106, v108, s70
	v_bfe_u32 v108, v107, 16, 1
	v_lshrrev_b32_e32 v106, 16, v106
	v_add3_u32 v107, v107, v108, s70
	v_and_or_b32 v129, v107, s33, v106
	s_waitcnt lgkmcnt(1)
	v_bfe_u32 v106, v104, 16, 1
	v_add3_u32 v104, v104, v106, s70
	v_bfe_u32 v106, v105, 16, 1
	v_lshrrev_b32_e32 v104, 16, v104
	v_add3_u32 v105, v105, v106, s70
	v_and_or_b32 v130, v105, s33, v104
	s_waitcnt lgkmcnt(0)
	v_bfe_u32 v104, v102, 16, 1
	v_add3_u32 v102, v102, v104, s70
	v_bfe_u32 v104, v103, 16, 1
	v_lshrrev_b32_e32 v102, 16, v102
	v_add3_u32 v103, v103, v104, s70
	v_and_or_b32 v131, v103, s33, v102
	v_ashrrev_i32_e32 v102, 31, v99
	v_mul_lo_u32 v104, s11, v99
	v_mul_lo_u32 v105, s10, v102
	v_mad_u64_u32 v[102:103], s[12:13], s10, v99, 0
	v_add3_u32 v103, v103, v105, v104
	v_lshl_add_u64 v[102:103], v[102:103], 1, s[6:7]
	v_lshl_add_u64 v[102:103], s[8:9], 1, v[102:103]
	v_lshl_add_u64 v[102:103], v[102:103], 0, v[146:147]
	global_store_dwordx4 v[102:103], v[128:131], off sc0 sc1
	ds_read2_b32 v[108:109], v112 offset0:16 offset1:49
	ds_read2_b32 v[106:107], v112 offset0:82 offset1:115
	ds_read2_b32 v[104:105], v112 offset0:148 offset1:181
	ds_read2_b32 v[102:103], v112 offset0:214 offset1:247
	v_or_b32_e32 v128, s21, v110
	s_mov_b64 s[12:13], -1
	s_and_b64 vcc, exec, s[0:1]
	s_cbranch_vccnz .LBB0_517
	s_lshl_b32 s12, s21, 1
	s_and_b32 s12, s12, 0xffffff00
	v_and_b32_e32 v99, 0x77, v128
	v_or_b32_e32 v99, s12, v99
	v_or_b32_e32 v99, s22, v99
	s_mov_b64 s[12:13], 0

; #define GAS __attribute__((address_space(1)))
; #define LAS __attribute__((address_space(3)))
; #define LDS_WAIT() asm volatile("s_waitcnt lgkmcnt(0)" ::: "memory")
; __device__ __forceinline__ unsigned pk2(float lo, float hi) { return f2bf(lo) | (f2bf(hi) << 16); }
; __device__ __forceinline__ void cv_finish(const CvDesc& d, const f32x4 (&wv)[8], LAS float* scr, int lane) {
;     ...
;     for (int j = 0; j < 4; ++j) { const int n = (lane >> 3) + 8 * j; const LAS float* s = scr + (8 * cch) * 33 + n;
;         v4u o; o.x = pk2(s[0 * 33], s[1 * 33]); o.y = pk2(s[2 * 33], s[3 * 33]); o.z = pk2(s[4 * 33], s[5 * 33]); o.w = pk2(s[6 * 33], s[7 * 33]);
;         const int nn = d.n0 + n; const int drow = d.mode ? (d.row_off + (nn >> 7) * 256 + (nn & 127)) : (d.row_off + nn);
;         *(GAS v4u*)(d.WT + (size_t)drow * d.K + d.k0 + 8 * cch) = o; }
;     LDS_WAIT(); asm volatile("" ::: "memory");
.LBB0_519:
	s_waitcnt lgkmcnt(3)
	v_bfe_u32 v128, v108, 16, 1
	v_add3_u32 v108, v108, v128, s70
	v_bfe_u32 v128, v109, 16, 1
	v_lshrrev_b32_e32 v108, 16, v108
	v_add3_u32 v109, v109, v128, s70
	v_and_or_b32 v128, v109, s33, v108
	s_waitcnt lgkmcnt(2)
	v_bfe_u32 v108, v106, 16, 1
	v_add3_u32 v106, v106, v108, s70
	v_bfe_u32 v108, v107, 16, 1
	v_lshrrev_b32_e32 v106, 16, v106
	v_add3_u32 v107, v107, v108, s70
	v_and_or_b32 v129, v107, s33, v106
	s_waitcnt lgkmcnt(1)
	v_bfe_u32 v106, v104, 16, 1
	v_add3_u32 v104, v104, v106, s70
	v_bfe_u32 v106, v105, 16, 1
	v_lshrrev_b32_e32 v104, 16, v104
	v_add3_u32 v105, v105, v106, s70
	v_and_or_b32 v130, v105, s33, v104
	s_waitcnt lgkmcnt(0)
	v_bfe_u32 v104, v102, 16, 1
	v_add3_u32 v102, v102, v104, s70
	v_bfe_u32 v104, v103, 16, 1
	v_lshrrev_b32_e32 v102, 16, v102
	v_add3_u32 v103, v103, v104, s70
	v_and_or_b32 v131, v103, s33, v102
	v_ashrrev_i32_e32 v102, 31, v99
	v_mul_lo_u32 v104, s11, v99
	v_mul_lo_u32 v105, s10, v102
	v_mad_u64_u32 v[102:103], s[12:13], s10, v99, 0
	v_add3_u32 v103, v103, v105, v104
	v_lshl_add_u64 v[102:103], v[102:103], 1, s[6:7]
	v_lshl_add_u64 v[102:103], s[8:9], 1, v[102:103]
	v_lshl_add_u64 v[102:103], v[102:103], 0, v[146:147]
	global_store_dwordx4 v[102:103], v[128:131], off sc0 sc1
	ds_read2_b32 v[108:109], v112 offset0:24 offset1:57
	ds_read2_b32 v[106:107], v112 offset0:90 offset1:123
	ds_read2_b32 v[104:105], v112 offset0:156 offset1:189
	ds_read2_b32 v[102:103], v112 offset0:222 offset1:255
	v_or_b32_e32 v128, s21, v111
	s_mov_b64 s[12:13], -1
	s_and_b64 vcc, exec, s[0:1]
	s_cbranch_vccnz .LBB0_521
	s_lshl_b32 s0, s21, 1
	s_and_b32 s0, s0, 0xffffff00
	v_and_b32_e32 v99, 0x7f, v128
	v_or_b32_e32 v99, s0, v99
	v_or_b32_e32 v99, s22, v99
	s_mov_b64 s[12:13], 0

; #define GAS __attribute__((address_space(1)))
; #define LAS __attribute__((address_space(3)))
; #define LDS_WAIT() asm volatile("s_waitcnt lgkmcnt(0)" ::: "memory")
; __device__ __forceinline__ unsigned pk2(float lo, float hi) { return f2bf(lo) | (f2bf(hi) << 16); }
; __device__ __forceinline__ void cv_finish(const CvDesc& d, const f32x4 (&wv)[8], LAS float* scr, int lane) {
;     ...
;     for (int j = 0; j < 4; ++j) { const int n = (lane >> 3) + 8 * j; const LAS float* s = scr + (8 * cch) * 33 + n;
;         v4u o; o.x = pk2(s[0 * 33], s[1 * 33]); o.y = pk2(s[2 * 33], s[3 * 33]); o.z = pk2(s[4 * 33], s[5 * 33]); o.w = pk2(s[6 * 33], s[7 * 33]);
;         const int nn = d.n0 + n; const int drow = d.mode ? (d.row_off + (nn >> 7) * 256 + (nn & 127)) : (d.row_off + nn);
;         *(GAS v4u*)(d.WT + (size_t)drow * d.K + d.k0 + 8 * cch) = o; }
;     LDS_WAIT(); asm volatile("" ::: "memory");
.LBB0_523:
	s_waitcnt lgkmcnt(3)
	v_bfe_u32 v128, v109, 16, 1
	v_add3_u32 v109, v109, v128, s70
	v_bfe_u32 v128, v108, 16, 1
	v_add3_u32 v108, v108, v128, s70
	v_lshrrev_b32_e32 v108, 16, v108
	v_and_or_b32 v128, v109, s33, v108
	s_waitcnt lgkmcnt(2)
	v_bfe_u32 v108, v107, 16, 1
	v_add3_u32 v107, v107, v108, s70
	v_bfe_u32 v108, v106, 16, 1
	v_add3_u32 v106, v106, v108, s70
	v_lshrrev_b32_e32 v106, 16, v106
	v_and_or_b32 v129, v107, s33, v106
	s_waitcnt lgkmcnt(1)
	v_bfe_u32 v106, v105, 16, 1
	v_add3_u32 v105, v105, v106, s70
	v_bfe_u32 v106, v104, 16, 1
	v_add3_u32 v104, v104, v106, s70
	v_lshrrev_b32_e32 v104, 16, v104
	v_and_or_b32 v130, v105, s33, v104
	s_waitcnt lgkmcnt(0)
	v_bfe_u32 v104, v103, 16, 1
	v_add3_u32 v103, v103, v104, s70
	v_bfe_u32 v104, v102, 16, 1
	v_add3_u32 v102, v102, v104, s70
	v_lshrrev_b32_e32 v102, 16, v102
	v_and_or_b32 v131, v103, s33, v102
	v_ashrrev_i32_e32 v102, 31, v99
	v_mul_lo_u32 v104, s11, v99
	v_mul_lo_u32 v105, s10, v102
	v_mad_u64_u32 v[102:103], s[0:1], s10, v99, 0
	v_add3_u32 v103, v103, v105, v104
	v_lshl_add_u64 v[102:103], v[102:103], 1, s[6:7]
	v_lshl_add_u64 v[102:103], s[8:9], 1, v[102:103]
	v_lshl_add_u64 v[102:103], v[102:103], 0, v[146:147]
	global_store_dwordx4 v[102:103], v[128:131], off sc0 sc1
	s_waitcnt lgkmcnt(0)
	s_add_i32 s0, s20, -3
	s_cmp_ge_i32 s0, s14
	s_cbranch_scc1 .LBB0_473
	s_add_i32 s0, s20, -1
	s_cmp_ge_i32 s0, s14
	s_cbranch_scc1 .LBB0_542
	v_readlane_b32 s0, v249, 44
	s_add_i32 s0, s0, s16
	s_mul_hi_i32 s1, s0, 0x2aaaaaab
	s_lshr_b32 s6, s1, 31
	s_ashr_i32 s1, s1, 13
	s_add_i32 s1, s1, s6
	s_mul_i32 s6, s1, 0xc000
	s_sub_i32 s0, s0, s6
	s_ashr_i32 s6, s0, 31
	s_lshr_b32 s6, s6, 18
	s_add_i32 s6, s0, s6
	s_and_b32 s7, s6, 0xffffc000
	s_sub_i32 s12, s0, s7
	s_lshl_b32 s1, s1, 14
	s_lshl_b32 s0, s6, 1
	s_add_i32 s13, s1, s12
	s_and_b32 s0, s0, 0xffff8000
	s_addk_i32 s13, 0x4800
	s_add_i32 s7, s13, s0
	s_cmpk_gt_i32 s7, 0x37ff
	s_mov_b64 s[10:11], -1
	s_cbranch_scc0 .LBB0_539
	s_cmpk_gt_u32 s7, 0x47ff
	s_cbranch_scc0 .LBB0_536
	s_cmpk_gt_u32 s7, 0xc7ff
	s_cbranch_scc0 .LBB0_533
	s_lshl_b32 s10, s7, 5
	s_cmp_gt_u32 s7, 0x147ff
	s_mov_b64 s[8:9], -1
	s_cbranch_scc0 .LBB0_530
	s_add_i32 s0, s7, 0xfffeb800
	s_lshr_b32 s58, s0, 10
	v_readlane_b32 s40, v249, 0
	s_lshl_b64 s[0:1], s[58:59], 23
	v_readlane_b32 s44, v249, 4
	v_readlane_b32 s45, v249, 5
	s_add_u32 s0, s44, s0
	v_readlane_b32 s41, v249, 1
	v_readlane_b32 s42, v249, 2
	v_readlane_b32 s43, v249, 3
	v_readlane_b32 s46, v249, 6
	v_readlane_b32 s47, v249, 7
	s_addc_u32 s1, s45, s1
	s_and_b32 s21, s12, 0x3c0
	s_and_b32 s6, s10, 0x7e0
	s_mov_b64 s[8:9], 0

; #define GAS __attribute__((address_space(1)))
; #define LAS __attribute__((address_space(3)))
; #define LDS_WAIT() asm volatile("s_waitcnt lgkmcnt(0)" ::: "memory")
; __device__ __forceinline__ unsigned pk2(float lo, float hi) { return f2bf(lo) | (f2bf(hi) << 16); }
; __device__ __forceinline__ void cv_finish(const CvDesc& d, const f32x4 (&wv)[8], LAS float* scr, int lane) {
;     ...
;     for (int j = 0; j < 4; ++j) { const int n = (lane >> 3) + 8 * j; const LAS float* s = scr + (8 * cch) * 33 + n;
;         v4u o; o.x = pk2(s[0 * 33], s[1 * 33]); o.y = pk2(s[2 * 33], s[3 * 33]); o.z = pk2(s[4 * 33], s[5 * 33]); o.w = pk2(s[6 * 33], s[7 * 33]);
;         const int nn = d.n0 + n; const int drow = d.mode ? (d.row_off + (nn >> 7) * 256 + (nn & 127)) : (d.row_off + nn);
;         *(GAS v4u*)(d.WT + (size_t)drow * d.K + d.k0 + 8 * cch) = o; }
;     LDS_WAIT(); asm volatile("" ::: "memory");
.LBB0_561:
	s_waitcnt lgkmcnt(3)
	v_bfe_u32 v128, v108, 16, 1
	v_add3_u32 v108, v108, v128, s70
	v_bfe_u32 v128, v109, 16, 1
	v_lshrrev_b32_e32 v108, 16, v108
	v_add3_u32 v109, v109, v128, s70
	v_and_or_b32 v128, v109, s33, v108
	s_waitcnt lgkmcnt(2)
	v_bfe_u32 v108, v106, 16, 1
	v_add3_u32 v106, v106, v108, s70
	v_bfe_u32 v108, v107, 16, 1
	v_lshrrev_b32_e32 v106, 16, v106
	v_add3_u32 v107, v107, v108, s70
	v_and_or_b32 v129, v107, s33, v106
	s_waitcnt lgkmcnt(1)
	v_bfe_u32 v106, v104, 16, 1
	v_add3_u32 v104, v104, v106, s70
	v_bfe_u32 v106, v105, 16, 1
	v_lshrrev_b32_e32 v104, 16, v104
	v_add3_u32 v105, v105, v106, s70
	v_and_or_b32 v130, v105, s33, v104
	s_waitcnt lgkmcnt(0)
	v_bfe_u32 v104, v102, 16, 1
	v_add3_u32 v102, v102, v104, s70
	v_bfe_u32 v104, v103, 16, 1
	v_lshrrev_b32_e32 v102, 16, v102
	v_add3_u32 v103, v103, v104, s70
	v_and_or_b32 v131, v103, s33, v102
	v_ashrrev_i32_e32 v102, 31, v99
	v_mul_lo_u32 v104, s11, v99
	v_mul_lo_u32 v105, s10, v102
	v_mad_u64_u32 v[102:103], s[12:13], s10, v99, 0
	v_add3_u32 v103, v103, v105, v104
	v_lshl_add_u64 v[102:103], v[102:103], 1, s[6:7]
	s_ashr_i32 s9, s8, 31
	v_lshl_add_u64 v[102:103], s[8:9], 1, v[102:103]
	v_lshl_add_u64 v[102:103], v[102:103], 0, v[146:147]
	global_store_dwordx4 v[102:103], v[128:131], off sc0 sc1
	ds_read2_b32 v[108:109], v112 offset0:8 offset1:41
	ds_read2_b32 v[106:107], v112 offset0:74 offset1:107
	ds_read2_b32 v[104:105], v112 offset0:140 offset1:173
	ds_read2_b32 v[102:103], v112 offset0:206 offset1:239
	s_xor_b64 s[12:13], s[0:1], -1
	v_cndmask_b32_e64 v99, 0, 1, s[12:13]
	v_or_b32_e32 v128, s21, v101
	v_cmp_ne_u32_e64 s[0:1], 1, v99
	s_andn2_b64 vcc, exec, s[12:13]
	s_mov_b64 s[12:13], -1
	s_cbranch_vccnz .LBB0_563
	s_lshl_b32 s12, s21, 1
	s_and_b32 s12, s12, 0xffffff00
	v_and_b32_e32 v99, 0x6f, v128
	v_or_b32_e32 v99, s12, v99
	v_or_b32_e32 v99, s22, v99
	s_mov_b64 s[12:13], 0

; #define GAS __attribute__((address_space(1)))
; #define LAS __attribute__((address_space(3)))
; #define LDS_WAIT() asm volatile("s_waitcnt lgkmcnt(0)" ::: "memory")
; __device__ __forceinline__ unsigned pk2(float lo, float hi) { return f2bf(lo) | (f2bf(hi) << 16); }
; __device__ __forceinline__ void cv_finish(const CvDesc& d, const f32x4 (&wv)[8], LAS float* scr, int lane) {
;     ...
;     for (int j = 0; j < 4; ++j) { const int n = (lane >> 3) + 8 * j; const LAS float* s = scr + (8 * cch) * 33 + n;
;         v4u o; o.x = pk2(s[0 * 33], s[1 * 33]); o.y = pk2(s[2 * 33], s[3 * 33]); o.z = pk2(s[4 * 33], s[5 * 33]); o.w = pk2(s[6 * 33], s[7 * 33]);
;         const int nn = d.n0 + n; const int drow = d.mode ? (d.row_off + (nn >> 7) * 256 + (nn & 127)) : (d.row_off + nn);
;         *(GAS v4u*)(d.WT + (size_t)drow * d.K + d.k0 + 8 * cch) = o; }
;     LDS_WAIT(); asm volatile("" ::: "memory");
.LBB0_573:
	s_waitcnt lgkmcnt(3)
	v_bfe_u32 v128, v109, 16, 1
	v_add3_u32 v109, v109, v128, s70
	v_bfe_u32 v128, v108, 16, 1
	v_add3_u32 v108, v108, v128, s70
	v_lshrrev_b32_e32 v108, 16, v108
	v_and_or_b32 v128, v109, s33, v108
	s_waitcnt lgkmcnt(2)
	v_bfe_u32 v108, v107, 16, 1
	v_add3_u32 v107, v107, v108, s70
	v_bfe_u32 v108, v106, 16, 1
	v_add3_u32 v106, v106, v108, s70
	v_lshrrev_b32_e32 v106, 16, v106
	v_and_or_b32 v129, v107, s33, v106
	s_waitcnt lgkmcnt(1)
	v_bfe_u32 v106, v105, 16, 1
	v_add3_u32 v105, v105, v106, s70
	v_bfe_u32 v106, v104, 16, 1
	v_add3_u32 v104, v104, v106, s70
	v_lshrrev_b32_e32 v104, 16, v104
	v_and_or_b32 v130, v105, s33, v104
	s_waitcnt lgkmcnt(0)
	v_bfe_u32 v104, v103, 16, 1
	v_add3_u32 v103, v103, v104, s70
	v_bfe_u32 v104, v102, 16, 1
	v_add3_u32 v102, v102, v104, s70
	v_lshrrev_b32_e32 v102, 16, v102
	v_and_or_b32 v131, v103, s33, v102
	v_ashrrev_i32_e32 v102, 31, v99
	v_mul_lo_u32 v104, s11, v99
	v_mul_lo_u32 v105, s10, v102
	v_mad_u64_u32 v[102:103], s[0:1], s10, v99, 0
	v_add3_u32 v103, v103, v105, v104
	v_lshl_add_u64 v[102:103], v[102:103], 1, s[6:7]
	v_lshl_add_u64 v[102:103], s[8:9], 1, v[102:103]
	v_lshl_add_u64 v[102:103], v[102:103], 0, v[146:147]
	global_store_dwordx4 v[102:103], v[128:131], off sc0 sc1
	s_waitcnt lgkmcnt(0)
	s_andn2_b64 vcc, exec, s[4:5]
	s_cbranch_vccnz .LBB0_473
	s_cmp_ge_i32 s20, s14
	s_cbranch_scc1 .LBB0_592
	v_readlane_b32 s0, v249, 44
	s_add_i32 s0, s0, s15
	s_mul_hi_i32 s1, s0, 0x2aaaaaab
	s_lshr_b32 s4, s1, 31
	s_ashr_i32 s1, s1, 13
	s_add_i32 s1, s1, s4
	s_mul_i32 s4, s1, 0xc000
	s_sub_i32 s0, s0, s4
	s_ashr_i32 s4, s0, 31
	s_lshr_b32 s4, s4, 18
	s_add_i32 s4, s0, s4
	s_and_b32 s5, s4, 0xffffc000
	s_sub_i32 s10, s0, s5
	s_lshl_b32 s1, s1, 14
	s_lshl_b32 s0, s4, 1
	s_add_i32 s11, s1, s10
	s_and_b32 s0, s0, 0xffff8000
	s_addk_i32 s11, 0x4800
	s_add_i32 s5, s11, s0
	s_cmpk_gt_i32 s5, 0x37ff
	s_mov_b64 s[8:9], -1
	s_cbranch_scc0 .LBB0_589
	s_cmpk_gt_u32 s5, 0x47ff
	s_cbranch_scc0 .LBB0_586
	s_cmpk_gt_u32 s5, 0xc7ff
	s_cbranch_scc0 .LBB0_583
	s_lshl_b32 s8, s5, 5
	s_cmp_gt_u32 s5, 0x147ff
	s_mov_b64 s[6:7], -1
	s_cbranch_scc0 .LBB0_580
	s_add_i32 s0, s5, 0xfffeb800
	s_lshr_b32 s58, s0, 10
	v_readlane_b32 s40, v249, 0
	s_lshl_b64 s[0:1], s[58:59], 23
	v_readlane_b32 s44, v249, 4
	v_readlane_b32 s45, v249, 5
	s_add_u32 s0, s44, s0
	v_readlane_b32 s41, v249, 1
	v_readlane_b32 s42, v249, 2
	v_readlane_b32 s43, v249, 3
	v_readlane_b32 s46, v249, 6
	v_readlane_b32 s47, v249, 7
	s_addc_u32 s1, s45, s1
	s_and_b32 s12, s10, 0x3c0
	s_and_b32 s4, s8, 0x7e0
	s_mov_b64 s[6:7], 0

; #define GAS __attribute__((address_space(1)))
; #define LAS __attribute__((address_space(3)))
; #define LDS_WAIT() asm volatile("s_waitcnt lgkmcnt(0)" ::: "memory")
; __device__ __forceinline__ unsigned pk2(float lo, float hi) { return f2bf(lo) | (f2bf(hi) << 16); }
; __device__ __forceinline__ void cv_finish(const CvDesc& d, const f32x4 (&wv)[8], LAS float* scr, int lane) {
;     ...
;     for (int j = 0; j < 4; ++j) { const int n = (lane >> 3) + 8 * j; const LAS float* s = scr + (8 * cch) * 33 + n;
;         v4u o; o.x = pk2(s[0 * 33], s[1 * 33]); o.y = pk2(s[2 * 33], s[3 * 33]); o.z = pk2(s[4 * 33], s[5 * 33]); o.w = pk2(s[6 * 33], s[7 * 33]);
;         const int nn = d.n0 + n; const int drow = d.mode ? (d.row_off + (nn >> 7) * 256 + (nn & 127)) : (d.row_off + nn);
;         *(GAS v4u*)(d.WT + (size_t)drow * d.K + d.k0 + 8 * cch) = o; }
;     LDS_WAIT(); asm volatile("" ::: "memory");
.LBB0_611:
	s_waitcnt lgkmcnt(3)
	v_bfe_u32 v114, v108, 16, 1
	v_add3_u32 v108, v108, v114, s70
	v_bfe_u32 v114, v109, 16, 1
	v_lshrrev_b32_e32 v108, 16, v108
	v_add3_u32 v109, v109, v114, s70
	v_and_or_b32 v114, v109, s33, v108
	s_waitcnt lgkmcnt(2)
	v_bfe_u32 v108, v106, 16, 1
	v_add3_u32 v106, v106, v108, s70
	v_bfe_u32 v108, v107, 16, 1
	v_lshrrev_b32_e32 v106, 16, v106
	v_add3_u32 v107, v107, v108, s70
	v_and_or_b32 v115, v107, s33, v106
	s_waitcnt lgkmcnt(1)
	v_bfe_u32 v106, v104, 16, 1
	v_add3_u32 v104, v104, v106, s70
	v_bfe_u32 v106, v105, 16, 1
	v_lshrrev_b32_e32 v104, 16, v104
	v_add3_u32 v105, v105, v106, s70
	v_and_or_b32 v116, v105, s33, v104
	s_waitcnt lgkmcnt(0)
	v_bfe_u32 v104, v102, 16, 1
	v_add3_u32 v102, v102, v104, s70
	v_bfe_u32 v104, v103, 16, 1
	v_lshrrev_b32_e32 v102, 16, v102
	v_add3_u32 v103, v103, v104, s70
	v_and_or_b32 v117, v103, s33, v102
	v_ashrrev_i32_e32 v102, 31, v99
	v_mul_lo_u32 v104, s9, v99
	v_mul_lo_u32 v105, s8, v102
	v_mad_u64_u32 v[102:103], s[10:11], s8, v99, 0
	v_add3_u32 v103, v103, v105, v104
	v_lshl_add_u64 v[102:103], v[102:103], 1, s[4:5]
	s_ashr_i32 s7, s6, 31
	v_lshl_add_u64 v[102:103], s[6:7], 1, v[102:103]
	v_lshl_add_u64 v[102:103], v[102:103], 0, v[146:147]
	global_store_dwordx4 v[102:103], v[114:117], off sc0 sc1
	ds_read2_b32 v[108:109], v112 offset0:8 offset1:41
	ds_read2_b32 v[106:107], v112 offset0:74 offset1:107
	ds_read2_b32 v[104:105], v112 offset0:140 offset1:173
	ds_read2_b32 v[102:103], v112 offset0:206 offset1:239
	s_xor_b64 s[10:11], s[0:1], -1
	v_cndmask_b32_e64 v99, 0, 1, s[10:11]
	v_or_b32_e32 v114, s12, v101
	v_cmp_ne_u32_e64 s[0:1], 1, v99
	s_andn2_b64 vcc, exec, s[10:11]
	s_mov_b64 s[10:11], -1
	s_cbranch_vccnz .LBB0_613
	s_lshl_b32 s10, s12, 1
	s_and_b32 s10, s10, 0xffffff00
	v_and_b32_e32 v99, 0x6f, v114
	v_or_b32_e32 v99, s10, v99
	v_or_b32_e32 v99, s13, v99
	s_mov_b64 s[10:11], 0

; #define GAS __attribute__((address_space(1)))
; #define LAS __attribute__((address_space(3)))
; #define LDS_WAIT() asm volatile("s_waitcnt lgkmcnt(0)" ::: "memory")
; __device__ __forceinline__ unsigned pk2(float lo, float hi) { return f2bf(lo) | (f2bf(hi) << 16); }
; __device__ __forceinline__ void cv_finish(const CvDesc& d, const f32x4 (&wv)[8], LAS float* scr, int lane) {
;     ...
;     for (int j = 0; j < 4; ++j) { const int n = (lane >> 3) + 8 * j; const LAS float* s = scr + (8 * cch) * 33 + n;
;         v4u o; o.x = pk2(s[0 * 33], s[1 * 33]); o.y = pk2(s[2 * 33], s[3 * 33]); o.z = pk2(s[4 * 33], s[5 * 33]); o.w = pk2(s[6 * 33], s[7 * 33]);
;         const int nn = d.n0 + n; const int drow = d.mode ? (d.row_off + (nn >> 7) * 256 + (nn & 127)) : (d.row_off + nn);
;         *(GAS v4u*)(d.WT + (size_t)drow * d.K + d.k0 + 8 * cch) = o; }
;     LDS_WAIT(); asm volatile("" ::: "memory");
.LBB0_615:
	s_waitcnt lgkmcnt(3)
	v_bfe_u32 v114, v108, 16, 1
	v_add3_u32 v108, v108, v114, s70
	v_bfe_u32 v114, v109, 16, 1
	v_lshrrev_b32_e32 v108, 16, v108
	v_add3_u32 v109, v109, v114, s70
	v_and_or_b32 v114, v109, s33, v108
	s_waitcnt lgkmcnt(2)
	v_bfe_u32 v108, v106, 16, 1
	v_add3_u32 v106, v106, v108, s70
	v_bfe_u32 v108, v107, 16, 1
	v_lshrrev_b32_e32 v106, 16, v106
	v_add3_u32 v107, v107, v108, s70
	v_and_or_b32 v115, v107, s33, v106
	s_waitcnt lgkmcnt(1)
	v_bfe_u32 v106, v104, 16, 1
	v_add3_u32 v104, v104, v106, s70
	v_bfe_u32 v106, v105, 16, 1
	v_lshrrev_b32_e32 v104, 16, v104
	v_add3_u32 v105, v105, v106, s70
	v_and_or_b32 v116, v105, s33, v104
	s_waitcnt lgkmcnt(0)
	v_bfe_u32 v104, v102, 16, 1
	v_add3_u32 v102, v102, v104, s70
	v_bfe_u32 v104, v103, 16, 1
	v_lshrrev_b32_e32 v102, 16, v102
	v_add3_u32 v103, v103, v104, s70
	v_and_or_b32 v117, v103, s33, v102
	v_ashrrev_i32_e32 v102, 31, v99
	v_mul_lo_u32 v104, s9, v99
	v_mul_lo_u32 v105, s8, v102
	v_mad_u64_u32 v[102:103], s[10:11], s8, v99, 0
	v_add3_u32 v103, v103, v105, v104
	v_lshl_add_u64 v[102:103], v[102:103], 1, s[4:5]
	v_lshl_add_u64 v[102:103], s[6:7], 1, v[102:103]
	v_lshl_add_u64 v[102:103], v[102:103], 0, v[146:147]
	global_store_dwordx4 v[102:103], v[114:117], off sc0 sc1
	ds_read2_b32 v[108:109], v112 offset0:16 offset1:49
	ds_read2_b32 v[106:107], v112 offset0:82 offset1:115
	ds_read2_b32 v[104:105], v112 offset0:148 offset1:181
	ds_read2_b32 v[102:103], v112 offset0:214 offset1:247
	v_or_b32_e32 v114, s12, v110
	s_mov_b64 s[10:11], -1
	s_and_b64 vcc, exec, s[0:1]
	s_cbranch_vccnz .LBB0_617
	s_lshl_b32 s10, s12, 1
	s_and_b32 s10, s10, 0xffffff00
	v_and_b32_e32 v99, 0x77, v114
	v_or_b32_e32 v99, s10, v99
	v_or_b32_e32 v99, s13, v99
	s_mov_b64 s[10:11], 0

; #define GAS __attribute__((address_space(1)))
; #define LAS __attribute__((address_space(3)))
; #define LDS_WAIT() asm volatile("s_waitcnt lgkmcnt(0)" ::: "memory")
; __device__ __forceinline__ unsigned pk2(float lo, float hi) { return f2bf(lo) | (f2bf(hi) << 16); }
; __device__ __forceinline__ void cv_finish(const CvDesc& d, const f32x4 (&wv)[8], LAS float* scr, int lane) {
;     ...
;     for (int j = 0; j < 4; ++j) { const int n = (lane >> 3) + 8 * j; const LAS float* s = scr + (8 * cch) * 33 + n;
;         v4u o; o.x = pk2(s[0 * 33], s[1 * 33]); o.y = pk2(s[2 * 33], s[3 * 33]); o.z = pk2(s[4 * 33], s[5 * 33]); o.w = pk2(s[6 * 33], s[7 * 33]);
;         const int nn = d.n0 + n; const int drow = d.mode ? (d.row_off + (nn >> 7) * 256 + (nn & 127)) : (d.row_off + nn);
;         *(GAS v4u*)(d.WT + (size_t)drow * d.K + d.k0 + 8 * cch) = o; }
;     LDS_WAIT(); asm volatile("" ::: "memory");
.LBB0_619:
	s_waitcnt lgkmcnt(3)
	v_bfe_u32 v114, v108, 16, 1
	v_add3_u32 v108, v108, v114, s70
	v_bfe_u32 v114, v109, 16, 1
	v_lshrrev_b32_e32 v108, 16, v108
	v_add3_u32 v109, v109, v114, s70
	v_and_or_b32 v114, v109, s33, v108
	s_waitcnt lgkmcnt(2)
	v_bfe_u32 v108, v106, 16, 1
	v_add3_u32 v106, v106, v108, s70
	v_bfe_u32 v108, v107, 16, 1
	v_lshrrev_b32_e32 v106, 16, v106
	v_add3_u32 v107, v107, v108, s70
	v_and_or_b32 v115, v107, s33, v106
	s_waitcnt lgkmcnt(1)
	v_bfe_u32 v106, v104, 16, 1
	v_add3_u32 v104, v104, v106, s70
	v_bfe_u32 v106, v105, 16, 1
	v_lshrrev_b32_e32 v104, 16, v104
	v_add3_u32 v105, v105, v106, s70
	v_and_or_b32 v116, v105, s33, v104
	s_waitcnt lgkmcnt(0)
	v_bfe_u32 v104, v102, 16, 1
	v_add3_u32 v102, v102, v104, s70
	v_bfe_u32 v104, v103, 16, 1
	v_lshrrev_b32_e32 v102, 16, v102
	v_add3_u32 v103, v103, v104, s70
	v_and_or_b32 v117, v103, s33, v102
	v_ashrrev_i32_e32 v102, 31, v99
	v_mul_lo_u32 v104, s9, v99
	v_mul_lo_u32 v105, s8, v102
	v_mad_u64_u32 v[102:103], s[10:11], s8, v99, 0
	v_add3_u32 v103, v103, v105, v104
	v_lshl_add_u64 v[102:103], v[102:103], 1, s[4:5]
	v_lshl_add_u64 v[102:103], s[6:7], 1, v[102:103]
	v_lshl_add_u64 v[102:103], v[102:103], 0, v[146:147]
	global_store_dwordx4 v[102:103], v[114:117], off sc0 sc1
	ds_read2_b32 v[108:109], v112 offset0:24 offset1:57
	ds_read2_b32 v[106:107], v112 offset0:90 offset1:123
	ds_read2_b32 v[104:105], v112 offset0:156 offset1:189
	ds_read2_b32 v[102:103], v112 offset0:222 offset1:255
	v_or_b32_e32 v114, s12, v111
	s_mov_b64 s[10:11], -1
	s_and_b64 vcc, exec, s[0:1]
	s_cbranch_vccnz .LBB0_621
	s_lshl_b32 s0, s12, 1
	s_and_b32 s0, s0, 0xffffff00
	v_and_b32_e32 v99, 0x7f, v114
	v_or_b32_e32 v99, s0, v99
	v_or_b32_e32 v99, s13, v99
	s_mov_b64 s[10:11], 0

; __device__ __forceinline__ unsigned pk2(float lo, float hi) { return f2bf(lo) | (f2bf(hi) << 16); }
; __device__ __forceinline__ void conv_rows(Frame& F, int l, int nrows) {
;     ...
;     for (int row = gw; row < nrows; row += NGW) {
;         const int t = row < NLAT ? (row & (SEQ - 1)) : ((row - NLAT) & (CTXL - 1)); const int tl = row < NLAT ? SEQ - 1 : CTXL - 1;
;         const size_t o = (size_t)row * 512 + 8 * F.lane;
;         const v4u z4 = {0u, 0u, 0u, 0u};
;         const v4u x1 = *(const v4u*)(CX + o), c1 = *(const v4u*)(CC + o), b1 = *(const v4u*)(CB + o);
;         const v4u x0 = t > 0 ? *(const v4u*)(CX + o - 512) : z4, c0 = t > 0 ? *(const v4u*)(CC + o - 512) : z4;
;         const v4u x2 = t < tl ? *(const v4u*)(CX + o + 512) : z4, c2 = t < tl ? *(const v4u*)(CC + o + 512) : z4;
;         v4u ov;
; #pragma unroll
;         for (int q = 0; q < 4; ++q) {
;             const float r0 = (bflo(c0[q]) * bflo(x0[q])) * w0[2 * q] + (bflo(c1[q]) * bflo(x1[q])) * w1[2 * q] + (bflo(c2[q]) * bflo(x2[q])) * w2[2 * q];
;             const float r1 = (bfhi(c0[q]) * bfhi(x0[q])) * w0[2 * q + 1] + (bfhi(c1[q]) * bfhi(x1[q])) * w1[2 * q + 1] + (bfhi(c2[q]) * bfhi(x2[q])) * w2[2 * q + 1];
;             ov[q] = pk2(bflo(b1[q]) * r0, bfhi(b1[q]) * r1); }
;         *(v4u*)(MIX + (size_t)row * DM + ATT_W + 8 * F.lane) = ov;
;     }
.LBB0_702:
	s_waitcnt vmcnt(0)
	v_lshlrev_b32_e32 v18, 16, v46
	v_lshlrev_b32_e32 v22, 16, v42
	v_lshlrev_b32_e32 v19, 16, v47
	v_lshlrev_b32_e32 v23, 16, v43
	v_lshlrev_b32_e32 v58, 16, v34
	v_lshlrev_b32_e32 v60, 16, v30
	v_lshlrev_b32_e32 v59, 16, v35
	v_lshlrev_b32_e32 v61, 16, v31
	v_pk_mul_f32 v[18:19], v[22:23], v[18:19]
	v_pk_mul_f32 v[22:23], v[60:61], v[58:59]
	v_pk_mul_f32 v[18:19], v[54:55], v[18:19]
	v_lshlrev_b32_e32 v59, 16, v39
	v_pk_fma_f32 v[18:19], v[56:57], v[22:23], v[18:19]
	v_lshlrev_b32_e32 v23, 16, v51
	v_lshlrev_b32_e32 v22, 16, v50
	v_lshlrev_b32_e32 v58, 16, v38
	v_and_b32_e32 v46, 0xffff0000, v46
	v_and_b32_e32 v42, 0xffff0000, v42
	v_and_b32_e32 v47, 0xffff0000, v47
	v_and_b32_e32 v43, 0xffff0000, v43
	v_pk_mul_f32 v[22:23], v[58:59], v[22:23]
	v_and_b32_e32 v34, 0xffff0000, v34
	v_and_b32_e32 v30, 0xffff0000, v30
	v_and_b32_e32 v35, 0xffff0000, v35
	v_and_b32_e32 v31, 0xffff0000, v31
	v_pk_fma_f32 v[18:19], v[10:11], v[22:23], v[18:19]
	v_pk_mul_f32 v[22:23], v[42:43], v[46:47]
	v_pk_mul_f32 v[30:31], v[30:31], v[34:35]
	v_pk_mul_f32 v[22:23], v[4:5], v[22:23]
	v_and_b32_e32 v35, 0xffff0000, v39
	v_pk_fma_f32 v[22:23], v[8:9], v[30:31], v[22:23]
	v_and_b32_e32 v31, 0xffff0000, v51
	v_and_b32_e32 v30, 0xffff0000, v50
	v_and_b32_e32 v34, 0xffff0000, v38
	v_pk_mul_f32 v[30:31], v[34:35], v[30:31]
	v_lshlrev_b32_e32 v34, 16, v36
	v_pk_fma_f32 v[22:23], v[20:21], v[30:31], v[22:23]
	v_lshlrev_b32_e32 v31, 16, v27
	v_lshlrev_b32_e32 v30, 16, v26
	v_and_b32_e32 v27, 0xffff0000, v27
	v_and_b32_e32 v26, 0xffff0000, v26
	v_pk_mul_f32 v[18:19], v[18:19], v[30:31]
	v_pk_mul_f32 v[22:23], v[22:23], v[26:27]
	v_lshlrev_b32_e32 v26, 16, v48
	v_lshlrev_b32_e32 v30, 16, v44
	v_lshlrev_b32_e32 v27, 16, v49
	v_lshlrev_b32_e32 v31, 16, v45
	v_lshlrev_b32_e32 v38, 16, v32
	v_lshlrev_b32_e32 v35, 16, v37
	v_lshlrev_b32_e32 v39, 16, v33
	v_pk_mul_f32 v[26:27], v[30:31], v[26:27]
	v_pk_mul_f32 v[30:31], v[38:39], v[34:35]
	v_pk_mul_f32 v[26:27], v[2:3], v[26:27]
	v_lshlrev_b32_e32 v35, 16, v41
	v_pk_fma_f32 v[26:27], v[6:7], v[30:31], v[26:27]
	v_lshlrev_b32_e32 v31, 16, v53
	v_lshlrev_b32_e32 v30, 16, v52
	v_lshlrev_b32_e32 v34, 16, v40
	v_and_b32_e32 v42, 0xffff0000, v48
	v_and_b32_e32 v44, 0xffff0000, v44
	v_and_b32_e32 v43, 0xffff0000, v49
	v_and_b32_e32 v45, 0xffff0000, v45
	v_pk_mul_f32 v[30:31], v[34:35], v[30:31]
	v_and_b32_e32 v36, 0xffff0000, v36
	v_and_b32_e32 v32, 0xffff0000, v32
	v_and_b32_e32 v37, 0xffff0000, v37
	v_and_b32_e32 v33, 0xffff0000, v33
	v_pk_fma_f32 v[26:27], v[14:15], v[30:31], v[26:27]
	v_pk_mul_f32 v[30:31], v[44:45], v[42:43]
	v_pk_mul_f32 v[32:33], v[32:33], v[36:37]
	v_pk_mul_f32 v[30:31], v[12:13], v[30:31]
	v_and_b32_e32 v35, 0xffff0000, v41
	v_pk_fma_f32 v[30:31], v[16:17], v[32:33], v[30:31]
	v_and_b32_e32 v33, 0xffff0000, v53
	v_and_b32_e32 v32, 0xffff0000, v52
	v_and_b32_e32 v34, 0xffff0000, v40
	v_pk_mul_f32 v[32:33], v[34:35], v[32:33]
	v_readlane_b32 s4, v253, 46
	v_pk_fma_f32 v[30:31], v[24:25], v[32:33], v[30:31]
	v_lshlrev_b32_e32 v33, 16, v29
	v_lshlrev_b32_e32 v32, 16, v28
	v_and_b32_e32 v29, 0xffff0000, v29
	v_and_b32_e32 v28, 0xffff0000, v28
	v_pk_mul_f32 v[28:29], v[30:31], v[28:29]
	v_pk_mul_f32 v[26:27], v[26:27], v[32:33]
	v_bfe_u32 v1, v29, 16, 1
	v_bfe_u32 v30, v28, 16, 1
	v_bfe_u32 v31, v23, 16, 1
	v_bfe_u32 v32, v22, 16, 1
	v_add3_u32 v22, v22, v32, s70
	v_add3_u32 v23, v23, v31, s70
	v_add3_u32 v28, v28, v30, s70
	v_add3_u32 v1, v29, v1, s70
	v_bfe_u32 v29, v18, 16, 1
	v_bfe_u32 v30, v19, 16, 1
	v_bfe_u32 v31, v26, 16, 1
	v_bfe_u32 v32, v27, 16, 1
	v_add3_u32 v27, v27, v32, s70
	v_add3_u32 v26, v26, v31, s70
	v_add3_u32 v19, v19, v30, s70
	v_add3_u32 v18, v18, v29, s70
	v_lshrrev_b32_e32 v18, 16, v18
	v_lshrrev_b32_e32 v19, 16, v19
	v_lshrrev_b32_e32 v26, 16, v26
	v_lshrrev_b32_e32 v27, 16, v27
	s_add_i32 s7, s7, s4
	v_and_or_b32 v29, v1, s33, v27
	v_and_or_b32 v28, v28, s33, v26
	v_and_or_b32 v27, v23, s33, v19
	v_and_or_b32 v26, v22, s33, v18
	v_lshl_add_u64 v[18:19], s[0:1], 0, v[146:147]
	s_add_u32 s0, s0, s10
	s_addc_u32 s1, s1, s11
	s_add_u32 s2, s2, s12
	s_addc_u32 s3, s3, s13
	s_cmp_lt_i32 s7, s6
	v_readlane_b32 s5, v253, 47
	global_store_dwordx4 v[18:19], v[26:29], off sc0 sc1
	s_cbranch_scc0 .LBB0_712

;     __device__ __forceinline__ void operator()(const f32x4 (&acc)[2][2][4][2], const Unit& u, int wr, int wc, int fr, int fq) const {
;     ...
; #pragma unroll
;         for (int ai = 0; ai < 2; ++ai)
; #pragma unroll
;             for (int m2 = 0; m2 < 4; m2 += 2) { f32x4 xv[2][2][2];
; #pragma unroll
;                 for (int mm = 0; mm < 2; ++mm) { const size_t off = (size_t)(row0 + ai * HALF + (m2 + mm) * 16) * DM + col0;
; #pragma unroll
;                     for (int bj = 0; bj < 2; ++bj)
; #pragma unroll
;                         for (int n = 0; n < 2; ++n) xv[mm][bj][n] = *(const f32x4*)(xin + off + bj * HALF + n * 16); }
; #pragma unroll
;                 for (int mm = 0; mm < 2; ++mm) { const size_t off = (size_t)(row0 + ai * HALF + (m2 + mm) * 16) * DM + col0;
; #pragma unroll
;                     for (int bj = 0; bj < 2; ++bj)
; #pragma unroll
;                         for (int n = 0; n < 2; ++n) *(f32x4*)(Z + off + bj * HALF + n * 16) = xv[mm][bj][n] * ALPHA_RES + gv[bj][n] * acc[ai][bj][m2 + mm][n]; }
;                 asm volatile("" ::: "memory"); }
.LBB0_1040:
	v_lshl_or_b32 v130, s15, 8, v167
	s_cmp_lt_i32 s14, 64
	s_movk_i32 s7, 0x3000
	v_ashrrev_i32_e32 v131, 31, v130
	v_lshl_add_u32 v208, s14, 8, v1
	s_cselect_b32 s7, s7, 0x6000
	s_cselect_b32 s16, s44, s45
	s_cselect_b32 s17, s43, s46
	s_cmp_gt_i32 s14, 31
	v_lshlrev_b64 v[160:161], 2, v[130:131]
	v_ashrrev_i32_e32 v209, 31, v208
	s_cselect_b32 s7, s7, 0
	v_lshl_add_u64 v[162:163], s[16:17], 0, v[160:161]
	v_lshlrev_b64 v[164:165], 13, v[208:209]
	s_lshl_b32 s7, s7, 2
	v_lshl_add_u64 v[130:131], v[162:163], 0, v[164:165]
	global_load_dwordx4 v[148:151], v[130:131], off
	global_load_dwordx4 v[170:173], v[130:131], off offset:64
	global_load_dwordx4 v[174:177], v[130:131], off offset:512
	global_load_dwordx4 v[186:189], v[130:131], off offset:576
	v_or_b32_e32 v130, 16, v208
	s_add_u32 s14, s22, s7
	v_ashrrev_i32_e32 v131, 31, v130
	s_addc_u32 s15, s23, 0
	v_lshlrev_b64 v[210:211], 13, v[130:131]
	v_lshl_add_u64 v[138:139], s[14:15], 0, v[160:161]
	s_mov_b64 s[14:15], 0x104000
	v_lshl_add_u64 v[130:131], v[162:163], 0, v[210:211]
	v_lshl_add_u64 v[140:141], v[138:139], 0, s[14:15]
	s_mov_b32 s7, 0x104000
	global_load_dwordx4 v[192:195], v[130:131], off
	global_load_dwordx4 v[196:199], v[130:131], off offset:64
	global_load_dwordx4 v[200:203], v[130:131], off offset:512
	global_load_dwordx4 v[204:207], v[130:131], off offset:576
	global_load_dwordx4 v[134:137], v[140:141], off offset:64
	s_nop 0
	global_load_dwordx4 v[130:133], v[140:141], off offset:512
	v_add_co_u32_e32 v138, vcc, s7, v138
	v_readlane_b32 s16, v251, 32
	s_nop 0
	v_addc_co_u32_e32 v139, vcc, 0, v139, vcc
	global_load_dwordx4 v[142:145], v[138:139], off
	s_nop 0
	global_load_dwordx4 v[138:141], v[140:141], off offset:576
	v_readlane_b32 s17, v251, 33
	s_mov_b32 s18, 0x3fb504f3
	v_or_b32_e32 v212, 32, v208
	v_lshl_add_u64 v[214:215], s[16:17], 0, v[164:165]
	v_lshl_add_u64 v[214:215], v[214:215], 0, v[160:161]
	v_lshl_add_u64 v[210:211], s[16:17], 0, v[210:211]
	v_lshl_add_u64 v[210:211], v[210:211], 0, v[160:161]
	v_ashrrev_i32_e32 v213, 31, v212
	v_lshlrev_b64 v[212:213], 13, v[212:213]
	v_lshl_add_u64 v[216:217], v[162:163], 0, v[212:213]
	s_mov_b64 s[14:15], 0x100000
	s_andn2_b64 vcc, exec, s[0:1]
	s_mov_b64 s[0:1], -1
	s_mov_b64 s[58:59], s[60:61]
	s_waitcnt vmcnt(0)
	v_pk_mul_f32 v[150:151], v[150:151], s[18:19] op_sel_hi:[1,0]
	v_pk_mul_f32 v[172:173], v[172:173], s[18:19] op_sel_hi:[1,0]
	v_pk_mul_f32 v[170:171], v[170:171], s[18:19] op_sel_hi:[1,0]
	v_pk_mul_f32 v[174:175], v[174:175], s[18:19] op_sel_hi:[1,0]
	v_pk_mul_f32 v[148:149], v[148:149], s[18:19] op_sel_hi:[1,0]
	v_pk_mul_f32 v[176:177], v[176:177], s[18:19] op_sel_hi:[1,0]
	v_pk_mul_f32 v[188:189], v[188:189], s[18:19] op_sel_hi:[1,0]
	v_pk_mul_f32 v[186:187], v[186:187], s[18:19] op_sel_hi:[1,0]
	v_pk_mul_f32 v[192:193], v[192:193], s[18:19] op_sel_hi:[1,0]
	v_pk_mul_f32 v[198:199], v[198:199], s[18:19] op_sel_hi:[1,0]
	v_pk_mul_f32 v[196:197], v[196:197], s[18:19] op_sel_hi:[1,0]
	v_pk_fma_f32 v[128:129], v[128:129], v[136:137], v[172:173]
	v_pk_fma_f32 v[126:127], v[126:127], v[134:135], v[170:171]
	v_pk_fma_f32 v[110:111], v[110:111], v[130:131], v[174:175]
	v_pk_mul_f32 v[194:195], v[194:195], s[18:19] op_sel_hi:[1,0]
	v_pk_mul_f32 v[202:203], v[202:203], s[18:19] op_sel_hi:[1,0]
	v_pk_mul_f32 v[200:201], v[200:201], s[18:19] op_sel_hi:[1,0]
	v_pk_mul_f32 v[206:207], v[206:207], s[18:19] op_sel_hi:[1,0]
	v_pk_mul_f32 v[204:205], v[204:205], s[18:19] op_sel_hi:[1,0]
	v_pk_fma_f32 v[112:113], v[112:113], v[132:133], v[176:177]
	v_pk_fma_f32 v[120:121], v[120:121], v[136:137], v[198:199]
	v_pk_fma_f32 v[118:119], v[118:119], v[134:135], v[196:197]
	v_pk_fma_f32 v[124:125], v[124:125], v[144:145], v[150:151]
	v_pk_fma_f32 v[122:123], v[122:123], v[142:143], v[148:149]
	global_store_dwordx4 v[214:215], v[126:129], off offset:64 sc0 sc1
	global_store_dwordx4 v[214:215], v[110:113], off offset:512 sc0 sc1
	v_pk_fma_f32 v[108:109], v[108:109], v[132:133], v[202:203]
	v_pk_fma_f32 v[106:107], v[106:107], v[130:131], v[200:201]
	v_pk_fma_f32 v[110:111], v[114:115], v[142:143], v[192:193]
	v_pk_fma_f32 v[104:105], v[104:105], v[140:141], v[188:189]
	v_pk_fma_f32 v[102:103], v[102:103], v[138:139], v[186:187]
	v_pk_fma_f32 v[112:113], v[116:117], v[144:145], v[194:195]
	global_store_dwordx4 v[210:211], v[118:121], off offset:64 sc0 sc1
	global_store_dwordx4 v[210:211], v[106:109], off offset:512 sc0 sc1
	v_pk_fma_f32 v[100:101], v[100:101], v[140:141], v[206:207]
	v_pk_fma_f32 v[98:99], v[98:99], v[138:139], v[204:205]
	global_store_dwordx4 v[214:215], v[122:125], off sc0 sc1
	global_store_dwordx4 v[214:215], v[102:105], off offset:576 sc0 sc1
	global_store_dwordx4 v[210:211], v[110:113], off sc0 sc1
	global_store_dwordx4 v[210:211], v[98:101], off offset:576 sc0 sc1
	global_load_dwordx4 v[98:101], v[216:217], off
	global_load_dwordx4 v[102:105], v[216:217], off offset:64
	v_or_b32_e32 v110, 48, v208
	v_ashrrev_i32_e32 v111, 31, v110
	v_lshlrev_b64 v[148:149], 13, v[110:111]
	v_lshl_add_u64 v[126:127], v[162:163], 0, v[148:149]
	global_load_dwordx4 v[106:109], v[216:217], off offset:512
	global_load_dwordx4 v[110:113], v[216:217], off offset:576
	global_load_dwordx4 v[114:117], v[126:127], off
	global_load_dwordx4 v[118:121], v[126:127], off offset:64
	global_load_dwordx4 v[122:125], v[126:127], off offset:512
	s_nop 0
	global_load_dwordx4 v[126:129], v[126:127], off offset:576
	v_lshl_add_u64 v[170:171], s[16:17], 0, v[212:213]
	v_lshl_add_u64 v[150:151], v[164:165], 0, s[14:15]
	v_lshl_add_u64 v[148:149], s[16:17], 0, v[148:149]
	v_lshl_add_u64 v[170:171], v[170:171], 0, v[160:161]
	s_mov_b64 s[14:15], 0x120000
	v_lshl_add_u64 v[148:149], v[148:149], 0, v[160:161]
	v_lshl_add_u64 v[172:173], v[162:163], 0, v[150:151]
	s_waitcnt vmcnt(7)
;     __device__ __forceinline__ void operator()(const f32x4 (&acc)[2][2][4][2], const Unit& u, int wr, int wc, int fr, int fq) const {
;     ...
; #pragma unroll
;         for (int ai = 0; ai < 2; ++ai)
; #pragma unroll
;             for (int m2 = 0; m2 < 4; m2 += 2) { f32x4 xv[2][2][2];
; #pragma unroll
;                 for (int mm = 0; mm < 2; ++mm) { const size_t off = (size_t)(row0 + ai * HALF + (m2 + mm) * 16) * DM + col0;
; #pragma unroll
;                     for (int bj = 0; bj < 2; ++bj)
; #pragma unroll
;                         for (int n = 0; n < 2; ++n) xv[mm][bj][n] = *(const f32x4*)(xin + off + bj * HALF + n * 16); }
; #pragma unroll
;                 for (int mm = 0; mm < 2; ++mm) { const size_t off = (size_t)(row0 + ai * HALF + (m2 + mm) * 16) * DM + col0;
; #pragma unroll
;                     for (int bj = 0; bj < 2; ++bj)
; #pragma unroll
;                         for (int n = 0; n < 2; ++n) *(f32x4*)(Z + off + bj * HALF + n * 16) = xv[mm][bj][n] * ALPHA_RES + gv[bj][n] * acc[ai][bj][m2 + mm][n]; }
;                 asm volatile("" ::: "memory"); }
	v_pk_mul_f32 v[100:101], v[100:101], s[18:19] op_sel_hi:[1,0]
	v_pk_mul_f32 v[98:99], v[98:99], s[18:19] op_sel_hi:[1,0]
	s_waitcnt vmcnt(6)
	v_pk_mul_f32 v[104:105], v[104:105], s[18:19] op_sel_hi:[1,0]
	v_pk_mul_f32 v[102:103], v[102:103], s[18:19] op_sel_hi:[1,0]
	v_pk_fma_f32 v[96:97], v[96:97], v[144:145], v[100:101]
	s_waitcnt vmcnt(3)
	v_pk_mul_f32 v[116:117], v[116:117], s[18:19] op_sel_hi:[1,0]
	v_pk_mul_f32 v[108:109], v[108:109], s[18:19] op_sel_hi:[1,0]
	v_pk_mul_f32 v[106:107], v[106:107], s[18:19] op_sel_hi:[1,0]
	v_pk_mul_f32 v[112:113], v[112:113], s[18:19] op_sel_hi:[1,0]
	v_pk_mul_f32 v[110:111], v[110:111], s[18:19] op_sel_hi:[1,0]
	v_pk_mul_f32 v[114:115], v[114:115], s[18:19] op_sel_hi:[1,0]
	s_waitcnt vmcnt(2)
	v_pk_mul_f32 v[120:121], v[120:121], s[18:19] op_sel_hi:[1,0]
	v_pk_mul_f32 v[118:119], v[118:119], s[18:19] op_sel_hi:[1,0]
	s_waitcnt vmcnt(1)
	v_pk_mul_f32 v[124:125], v[124:125], s[18:19] op_sel_hi:[1,0]
	v_pk_mul_f32 v[122:123], v[122:123], s[18:19] op_sel_hi:[1,0]
	s_waitcnt vmcnt(0)
	v_pk_mul_f32 v[128:129], v[128:129], s[18:19] op_sel_hi:[1,0]
	v_pk_mul_f32 v[126:127], v[126:127], s[18:19] op_sel_hi:[1,0]
	v_pk_fma_f32 v[94:95], v[94:95], v[142:143], v[98:99]
	v_pk_fma_f32 v[92:93], v[92:93], v[136:137], v[104:105]
	v_pk_fma_f32 v[90:91], v[90:91], v[134:135], v[102:103]
	v_pk_fma_f32 v[80:81], v[80:81], v[132:133], v[108:109]
	v_pk_fma_f32 v[78:79], v[78:79], v[130:131], v[106:107]
	v_pk_fma_f32 v[76:77], v[76:77], v[140:141], v[112:113]
	v_pk_fma_f32 v[74:75], v[74:75], v[138:139], v[110:111]
	v_pk_fma_f32 v[88:89], v[88:89], v[144:145], v[116:117]
	v_pk_fma_f32 v[86:87], v[86:87], v[142:143], v[114:115]
	v_pk_fma_f32 v[84:85], v[84:85], v[136:137], v[120:121]
	v_pk_fma_f32 v[82:83], v[82:83], v[134:135], v[118:119]
	v_pk_fma_f32 v[72:73], v[72:73], v[132:133], v[124:125]
	v_pk_fma_f32 v[70:71], v[70:71], v[130:131], v[122:123]
	v_pk_fma_f32 v[68:69], v[68:69], v[140:141], v[128:129]
	v_pk_fma_f32 v[66:67], v[66:67], v[138:139], v[126:127]
	global_store_dwordx4 v[170:171], v[94:97], off sc0 sc1
	global_store_dwordx4 v[170:171], v[90:93], off offset:64 sc0 sc1
	global_store_dwordx4 v[170:171], v[78:81], off offset:512 sc0 sc1
	global_store_dwordx4 v[170:171], v[74:77], off offset:576 sc0 sc1
	global_store_dwordx4 v[148:149], v[86:89], off sc0 sc1
	global_store_dwordx4 v[148:149], v[82:85], off offset:64 sc0 sc1
	global_store_dwordx4 v[148:149], v[70:73], off offset:512 sc0 sc1
	global_store_dwordx4 v[148:149], v[66:69], off offset:576 sc0 sc1
	v_lshl_add_u64 v[98:99], v[164:165], 0, s[14:15]
	v_lshl_add_u64 v[94:95], v[162:163], 0, v[98:99]
	global_load_dwordx4 v[66:69], v[172:173], off
	global_load_dwordx4 v[70:73], v[172:173], off offset:64
	global_load_dwordx4 v[74:77], v[172:173], off offset:512
	global_load_dwordx4 v[78:81], v[172:173], off offset:576
	global_load_dwordx4 v[82:85], v[94:95], off
	global_load_dwordx4 v[86:89], v[94:95], off offset:64
	global_load_dwordx4 v[90:93], v[94:95], off offset:512
	s_nop 0
	global_load_dwordx4 v[94:97], v[94:95], off offset:576
	s_mov_b64 s[14:15], 0x140000
	v_lshl_add_u64 v[102:103], s[16:17], 0, v[150:151]
	v_lshl_add_u64 v[100:101], v[164:165], 0, s[14:15]
	v_lshl_add_u64 v[98:99], s[16:17], 0, v[98:99]
	v_lshl_add_u64 v[102:103], v[102:103], 0, v[160:161]
	s_mov_b64 s[14:15], 0x160000
	v_lshl_add_u64 v[98:99], v[98:99], 0, v[160:161]
	v_lshl_add_u64 v[104:105], v[162:163], 0, v[100:101]
	s_waitcnt vmcnt(7)
	v_pk_mul_f32 v[68:69], v[68:69], s[18:19] op_sel_hi:[1,0]
	v_pk_mul_f32 v[66:67], v[66:67], s[18:19] op_sel_hi:[1,0]
	s_waitcnt vmcnt(6)
	v_pk_mul_f32 v[72:73], v[72:73], s[18:19] op_sel_hi:[1,0]
	v_pk_mul_f32 v[70:71], v[70:71], s[18:19] op_sel_hi:[1,0]
	s_waitcnt vmcnt(5)
	v_pk_mul_f32 v[76:77], v[76:77], s[18:19] op_sel_hi:[1,0]
	v_pk_mul_f32 v[74:75], v[74:75], s[18:19] op_sel_hi:[1,0]
	s_waitcnt vmcnt(4)
	v_pk_mul_f32 v[80:81], v[80:81], s[18:19] op_sel_hi:[1,0]
	v_pk_mul_f32 v[78:79], v[78:79], s[18:19] op_sel_hi:[1,0]
	s_waitcnt vmcnt(3)
	v_pk_mul_f32 v[84:85], v[84:85], s[18:19] op_sel_hi:[1,0]
	v_pk_mul_f32 v[82:83], v[82:83], s[18:19] op_sel_hi:[1,0]
	s_waitcnt vmcnt(2)
	v_pk_mul_f32 v[88:89], v[88:89], s[18:19] op_sel_hi:[1,0]
	v_pk_mul_f32 v[86:87], v[86:87], s[18:19] op_sel_hi:[1,0]
	s_waitcnt vmcnt(1)
	v_pk_mul_f32 v[92:93], v[92:93], s[18:19] op_sel_hi:[1,0]
	v_pk_mul_f32 v[90:91], v[90:91], s[18:19] op_sel_hi:[1,0]
	s_waitcnt vmcnt(0)
;     __device__ __forceinline__ void operator()(const f32x4 (&acc)[2][2][4][2], const Unit& u, int wr, int wc, int fr, int fq) const {
;     ...
; #pragma unroll
;         for (int ai = 0; ai < 2; ++ai)
; #pragma unroll
;             for (int m2 = 0; m2 < 4; m2 += 2) { f32x4 xv[2][2][2];
; #pragma unroll
;                 for (int mm = 0; mm < 2; ++mm) { const size_t off = (size_t)(row0 + ai * HALF + (m2 + mm) * 16) * DM + col0;
; #pragma unroll
;                     for (int bj = 0; bj < 2; ++bj)
; #pragma unroll
;                         for (int n = 0; n < 2; ++n) xv[mm][bj][n] = *(const f32x4*)(xin + off + bj * HALF + n * 16); }
; #pragma unroll
;                 for (int mm = 0; mm < 2; ++mm) { const size_t off = (size_t)(row0 + ai * HALF + (m2 + mm) * 16) * DM + col0;
; #pragma unroll
;                     for (int bj = 0; bj < 2; ++bj)
; #pragma unroll
;                         for (int n = 0; n < 2; ++n) *(f32x4*)(Z + off + bj * HALF + n * 16) = xv[mm][bj][n] * ALPHA_RES + gv[bj][n] * acc[ai][bj][m2 + mm][n]; }
;                 asm volatile("" ::: "memory"); }
	v_pk_mul_f32 v[96:97], v[96:97], s[18:19] op_sel_hi:[1,0]
	v_pk_mul_f32 v[94:95], v[94:95], s[18:19] op_sel_hi:[1,0]
	v_pk_fma_f32 v[64:65], v[64:65], v[144:145], v[68:69]
	v_pk_fma_f32 v[62:63], v[62:63], v[142:143], v[66:67]
	v_pk_fma_f32 v[60:61], v[60:61], v[136:137], v[72:73]
	v_pk_fma_f32 v[58:59], v[58:59], v[134:135], v[70:71]
	v_pk_fma_f32 v[48:49], v[48:49], v[132:133], v[76:77]
	v_pk_fma_f32 v[46:47], v[46:47], v[130:131], v[74:75]
	v_pk_fma_f32 v[44:45], v[44:45], v[140:141], v[80:81]
	v_pk_fma_f32 v[42:43], v[42:43], v[138:139], v[78:79]
	v_pk_fma_f32 v[56:57], v[56:57], v[144:145], v[84:85]
	v_pk_fma_f32 v[54:55], v[54:55], v[142:143], v[82:83]
	v_pk_fma_f32 v[52:53], v[52:53], v[136:137], v[88:89]
	v_pk_fma_f32 v[50:51], v[50:51], v[134:135], v[86:87]
	v_pk_fma_f32 v[40:41], v[40:41], v[132:133], v[92:93]
	v_pk_fma_f32 v[38:39], v[38:39], v[130:131], v[90:91]
	v_pk_fma_f32 v[36:37], v[36:37], v[140:141], v[96:97]
	v_pk_fma_f32 v[34:35], v[34:35], v[138:139], v[94:95]
	global_store_dwordx4 v[102:103], v[62:65], off sc0 sc1
	global_store_dwordx4 v[102:103], v[58:61], off offset:64 sc0 sc1
	global_store_dwordx4 v[102:103], v[46:49], off offset:512 sc0 sc1
	global_store_dwordx4 v[102:103], v[42:45], off offset:576 sc0 sc1
	global_store_dwordx4 v[98:99], v[54:57], off sc0 sc1
	global_store_dwordx4 v[98:99], v[50:53], off offset:64 sc0 sc1
	global_store_dwordx4 v[98:99], v[38:41], off offset:512 sc0 sc1
	global_store_dwordx4 v[98:99], v[34:37], off offset:576 sc0 sc1
	v_lshl_add_u64 v[66:67], v[164:165], 0, s[14:15]
	v_lshl_add_u64 v[62:63], v[162:163], 0, v[66:67]
	global_load_dwordx4 v[34:37], v[104:105], off
	global_load_dwordx4 v[38:41], v[104:105], off offset:64
	global_load_dwordx4 v[42:45], v[104:105], off offset:512
	global_load_dwordx4 v[46:49], v[104:105], off offset:576
	global_load_dwordx4 v[50:53], v[62:63], off
	global_load_dwordx4 v[54:57], v[62:63], off offset:64
	global_load_dwordx4 v[58:61], v[62:63], off offset:512
	s_nop 0
	global_load_dwordx4 v[62:65], v[62:63], off offset:576
	v_lshl_add_u64 v[68:69], s[16:17], 0, v[100:101]
	v_lshl_add_u64 v[66:67], s[16:17], 0, v[66:67]
	v_lshl_add_u64 v[68:69], v[68:69], 0, v[160:161]
	v_lshl_add_u64 v[66:67], v[66:67], 0, v[160:161]
	s_waitcnt vmcnt(7)
	v_pk_mul_f32 v[36:37], v[36:37], s[18:19] op_sel_hi:[1,0]
	v_pk_mul_f32 v[34:35], v[34:35], s[18:19] op_sel_hi:[1,0]
	s_waitcnt vmcnt(6)
	v_pk_mul_f32 v[40:41], v[40:41], s[18:19] op_sel_hi:[1,0]
	v_pk_mul_f32 v[38:39], v[38:39], s[18:19] op_sel_hi:[1,0]
	s_waitcnt vmcnt(5)
	v_pk_mul_f32 v[44:45], v[44:45], s[18:19] op_sel_hi:[1,0]
	v_pk_mul_f32 v[42:43], v[42:43], s[18:19] op_sel_hi:[1,0]
	s_waitcnt vmcnt(4)
	v_pk_mul_f32 v[48:49], v[48:49], s[18:19] op_sel_hi:[1,0]
	v_pk_mul_f32 v[46:47], v[46:47], s[18:19] op_sel_hi:[1,0]
	s_waitcnt vmcnt(3)
	v_pk_mul_f32 v[52:53], v[52:53], s[18:19] op_sel_hi:[1,0]
	v_pk_mul_f32 v[50:51], v[50:51], s[18:19] op_sel_hi:[1,0]
	s_waitcnt vmcnt(2)
	v_pk_mul_f32 v[56:57], v[56:57], s[18:19] op_sel_hi:[1,0]
	v_pk_mul_f32 v[54:55], v[54:55], s[18:19] op_sel_hi:[1,0]
	s_waitcnt vmcnt(1)
	v_pk_mul_f32 v[60:61], v[60:61], s[18:19] op_sel_hi:[1,0]
	v_pk_mul_f32 v[58:59], v[58:59], s[18:19] op_sel_hi:[1,0]
	s_waitcnt vmcnt(0)
	v_pk_mul_f32 v[64:65], v[64:65], s[18:19] op_sel_hi:[1,0]
	v_pk_mul_f32 v[62:63], v[62:63], s[18:19] op_sel_hi:[1,0]
	v_pk_fma_f32 v[32:33], v[32:33], v[144:145], v[36:37]
	v_pk_fma_f32 v[30:31], v[30:31], v[142:143], v[34:35]
	v_pk_fma_f32 v[28:29], v[28:29], v[136:137], v[40:41]
	v_pk_fma_f32 v[26:27], v[26:27], v[134:135], v[38:39]
	v_pk_fma_f32 v[16:17], v[16:17], v[132:133], v[44:45]
	v_pk_fma_f32 v[14:15], v[14:15], v[130:131], v[42:43]
	v_pk_fma_f32 v[12:13], v[12:13], v[140:141], v[48:49]
	v_pk_fma_f32 v[10:11], v[10:11], v[138:139], v[46:47]
	v_pk_fma_f32 v[24:25], v[24:25], v[144:145], v[52:53]
	v_pk_fma_f32 v[22:23], v[22:23], v[142:143], v[50:51]
	v_pk_fma_f32 v[20:21], v[20:21], v[136:137], v[56:57]
	v_pk_fma_f32 v[18:19], v[18:19], v[134:135], v[54:55]
	v_pk_fma_f32 v[8:9], v[8:9], v[132:133], v[60:61]
	v_pk_fma_f32 v[6:7], v[6:7], v[130:131], v[58:59]
	v_pk_fma_f32 v[4:5], v[4:5], v[140:141], v[64:65]
	v_pk_fma_f32 v[2:3], v[2:3], v[138:139], v[62:63]
	global_store_dwordx4 v[68:69], v[30:33], off sc0 sc1
	global_store_dwordx4 v[68:69], v[26:29], off offset:64 sc0 sc1
	global_store_dwordx4 v[68:69], v[14:17], off offset:512 sc0 sc1
	global_store_dwordx4 v[68:69], v[10:13], off offset:576 sc0 sc1
	global_store_dwordx4 v[66:67], v[22:25], off sc0 sc1
	global_store_dwordx4 v[66:67], v[18:21], off offset:64 sc0 sc1
	global_store_dwordx4 v[66:67], v[6:9], off offset:512 sc0 sc1
	global_store_dwordx4 v[66:67], v[2:5], off offset:576 sc0 sc1
	s_cbranch_vccnz .LBB0_1033
	s_andn2_b64 vcc, exec, s[2:3]
	s_cbranch_vccnz .LBB0_1032
	s_barrier
	s_branch .LBB0_1032

; #define GAS __attribute__((address_space(1)))
; #define LAS __attribute__((address_space(3)))
; #define LDS_WAIT() asm volatile("s_waitcnt lgkmcnt(0)" ::: "memory")
; __device__ __forceinline__ unsigned pk2(float lo, float hi) { return f2bf(lo) | (f2bf(hi) << 16); }
; __device__ __forceinline__ void cv_finish(const CvDesc& d, const f32x4 (&wv)[8], LAS float* scr, int lane) {
;     ...
;     for (int j = 0; j < 4; ++j) { const int n = (lane >> 3) + 8 * j; const LAS float* s = scr + (8 * cch) * 33 + n;
;         v4u o; o.x = pk2(s[0 * 33], s[1 * 33]); o.y = pk2(s[2 * 33], s[3 * 33]); o.z = pk2(s[4 * 33], s[5 * 33]); o.w = pk2(s[6 * 33], s[7 * 33]);
;         const int nn = d.n0 + n; const int drow = d.mode ? (d.row_off + (nn >> 7) * 256 + (nn & 127)) : (d.row_off + nn);
;         *(GAS v4u*)(d.WT + (size_t)drow * d.K + d.k0 + 8 * cch) = o; }
;     LDS_WAIT(); asm volatile("" ::: "memory");
.LBB0_1084:
	s_waitcnt lgkmcnt(3)
	v_bfe_u32 v114, v109, 16, 1
	v_add3_u32 v109, v109, v114, s70
	v_bfe_u32 v114, v108, 16, 1
	v_add3_u32 v108, v108, v114, s70
	v_lshrrev_b32_e32 v108, 16, v108
	v_and_or_b32 v114, v109, s33, v108
	s_waitcnt lgkmcnt(2)
	v_bfe_u32 v108, v107, 16, 1
	v_add3_u32 v107, v107, v108, s70
	v_bfe_u32 v108, v106, 16, 1
	v_add3_u32 v106, v106, v108, s70
	v_lshrrev_b32_e32 v106, 16, v106
	v_and_or_b32 v115, v107, s33, v106
	s_waitcnt lgkmcnt(1)
	v_bfe_u32 v106, v105, 16, 1
	v_add3_u32 v105, v105, v106, s70
	v_bfe_u32 v106, v104, 16, 1
	v_add3_u32 v104, v104, v106, s70
	v_lshrrev_b32_e32 v104, 16, v104
	v_and_or_b32 v116, v105, s33, v104
	s_waitcnt lgkmcnt(0)
	v_bfe_u32 v104, v103, 16, 1
	v_add3_u32 v103, v103, v104, s70
	v_bfe_u32 v104, v102, 16, 1
	v_add3_u32 v102, v102, v104, s70
	v_lshrrev_b32_e32 v102, 16, v102
	v_and_or_b32 v117, v103, s33, v102
	v_ashrrev_i32_e32 v102, 31, v99
	v_mul_lo_u32 v104, s7, v99
	v_mul_lo_u32 v105, s6, v102
	v_mad_u64_u32 v[102:103], s[0:1], s6, v99, 0
	v_add3_u32 v103, v103, v105, v104
	v_lshl_add_u64 v[102:103], v[102:103], 1, s[2:3]
	v_lshl_add_u64 v[102:103], s[4:5], 1, v[102:103]
	v_lshl_add_u64 v[102:103], v[102:103], 0, v[146:147]
	global_store_dwordx4 v[102:103], v[114:117], off sc0 sc1
	s_waitcnt lgkmcnt(0)

; #define GAS __attribute__((address_space(1)))
; #define LAS __attribute__((address_space(3)))
; #define LDS_WAIT() asm volatile("s_waitcnt lgkmcnt(0)" ::: "memory")
; __device__ __forceinline__ unsigned pk2(float lo, float hi) { return f2bf(lo) | (f2bf(hi) << 16); }
; __device__ __forceinline__ void cv_finish(const CvDesc& d, const f32x4 (&wv)[8], LAS float* scr, int lane) {
;     ...
;     for (int j = 0; j < 4; ++j) { const int n = (lane >> 3) + 8 * j; const LAS float* s = scr + (8 * cch) * 33 + n;
;         v4u o; o.x = pk2(s[0 * 33], s[1 * 33]); o.y = pk2(s[2 * 33], s[3 * 33]); o.z = pk2(s[4 * 33], s[5 * 33]); o.w = pk2(s[6 * 33], s[7 * 33]);
;         const int nn = d.n0 + n; const int drow = d.mode ? (d.row_off + (nn >> 7) * 256 + (nn & 127)) : (d.row_off + nn);
;         *(GAS v4u*)(d.WT + (size_t)drow * d.K + d.k0 + 8 * cch) = o; }
;     LDS_WAIT(); asm volatile("" ::: "memory");
.LBB0_1123:
	s_waitcnt lgkmcnt(3)
	v_bfe_u32 v128, v108, 16, 1
	v_add3_u32 v108, v108, v128, s70
	v_bfe_u32 v128, v109, 16, 1
	v_lshrrev_b32_e32 v108, 16, v108
	v_add3_u32 v109, v109, v128, s70
	v_and_or_b32 v128, v109, s33, v108
	s_waitcnt lgkmcnt(2)
	v_bfe_u32 v108, v106, 16, 1
	v_add3_u32 v106, v106, v108, s70
	v_bfe_u32 v108, v107, 16, 1
	v_lshrrev_b32_e32 v106, 16, v106
	v_add3_u32 v107, v107, v108, s70
	v_and_or_b32 v129, v107, s33, v106
	s_waitcnt lgkmcnt(1)
	v_bfe_u32 v106, v104, 16, 1
	v_add3_u32 v104, v104, v106, s70
	v_bfe_u32 v106, v105, 16, 1
	v_lshrrev_b32_e32 v104, 16, v104
	v_add3_u32 v105, v105, v106, s70
	v_and_or_b32 v130, v105, s33, v104
	s_waitcnt lgkmcnt(0)
	v_bfe_u32 v104, v102, 16, 1
	v_add3_u32 v102, v102, v104, s70
	v_bfe_u32 v104, v103, 16, 1
	v_lshrrev_b32_e32 v102, 16, v102
	v_add3_u32 v103, v103, v104, s70
	v_and_or_b32 v131, v103, s33, v102
	v_ashrrev_i32_e32 v102, 31, v99
	v_mul_lo_u32 v104, s9, v99
	v_mul_lo_u32 v105, s8, v102
	v_mad_u64_u32 v[102:103], s[10:11], s8, v99, 0
	v_add3_u32 v103, v103, v105, v104
	v_lshl_add_u64 v[102:103], v[102:103], 1, s[4:5]
	s_ashr_i32 s7, s6, 31
	v_lshl_add_u64 v[102:103], s[6:7], 1, v[102:103]
	v_lshlrev_b32_e32 v146, 1, v100
	v_lshl_add_u64 v[102:103], v[102:103], 0, v[146:147]
	global_store_dwordx4 v[102:103], v[128:131], off sc0 sc1
	ds_read2_b32 v[108:109], v112 offset0:8 offset1:41
	ds_read2_b32 v[106:107], v112 offset0:74 offset1:107
	ds_read2_b32 v[104:105], v112 offset0:140 offset1:173
	ds_read2_b32 v[102:103], v112 offset0:206 offset1:239
	s_xor_b64 s[10:11], s[0:1], -1
	v_cndmask_b32_e64 v99, 0, 1, s[10:11]
	v_or_b32_e32 v128, s19, v101
	v_cmp_ne_u32_e64 s[0:1], 1, v99
	s_andn2_b64 vcc, exec, s[10:11]
	s_mov_b64 s[10:11], -1
	s_cbranch_vccnz .LBB0_1125
	s_lshl_b32 s10, s19, 1
	s_and_b32 s10, s10, 0xffffff00
	v_and_b32_e32 v99, 0x6f, v128
	v_or_b32_e32 v99, s10, v99
	v_or_b32_e32 v99, s20, v99
	s_mov_b64 s[10:11], 0

; #define GAS __attribute__((address_space(1)))
; #define LAS __attribute__((address_space(3)))
; #define LDS_WAIT() asm volatile("s_waitcnt lgkmcnt(0)" ::: "memory")
; __device__ __forceinline__ unsigned pk2(float lo, float hi) { return f2bf(lo) | (f2bf(hi) << 16); }
; __device__ __forceinline__ void cv_finish(const CvDesc& d, const f32x4 (&wv)[8], LAS float* scr, int lane) {
;     ...
;     for (int j = 0; j < 4; ++j) { const int n = (lane >> 3) + 8 * j; const LAS float* s = scr + (8 * cch) * 33 + n;
;         v4u o; o.x = pk2(s[0 * 33], s[1 * 33]); o.y = pk2(s[2 * 33], s[3 * 33]); o.z = pk2(s[4 * 33], s[5 * 33]); o.w = pk2(s[6 * 33], s[7 * 33]);
;         const int nn = d.n0 + n; const int drow = d.mode ? (d.row_off + (nn >> 7) * 256 + (nn & 127)) : (d.row_off + nn);
;         *(GAS v4u*)(d.WT + (size_t)drow * d.K + d.k0 + 8 * cch) = o; }
;     LDS_WAIT(); asm volatile("" ::: "memory");
.LBB0_1127:
	s_waitcnt lgkmcnt(3)
	v_bfe_u32 v128, v108, 16, 1
	v_add3_u32 v108, v108, v128, s70
	v_bfe_u32 v128, v109, 16, 1
	v_lshrrev_b32_e32 v108, 16, v108
	v_add3_u32 v109, v109, v128, s70
	v_and_or_b32 v128, v109, s33, v108
	s_waitcnt lgkmcnt(2)
	v_bfe_u32 v108, v106, 16, 1
	v_add3_u32 v106, v106, v108, s70
	v_bfe_u32 v108, v107, 16, 1
	v_lshrrev_b32_e32 v106, 16, v106
	v_add3_u32 v107, v107, v108, s70
	v_and_or_b32 v129, v107, s33, v106
	s_waitcnt lgkmcnt(1)
	v_bfe_u32 v106, v104, 16, 1
	v_add3_u32 v104, v104, v106, s70
	v_bfe_u32 v106, v105, 16, 1
	v_lshrrev_b32_e32 v104, 16, v104
	v_add3_u32 v105, v105, v106, s70
	v_and_or_b32 v130, v105, s33, v104
	s_waitcnt lgkmcnt(0)
	v_bfe_u32 v104, v102, 16, 1
	v_add3_u32 v102, v102, v104, s70
	v_bfe_u32 v104, v103, 16, 1
	v_lshrrev_b32_e32 v102, 16, v102
	v_add3_u32 v103, v103, v104, s70
	v_and_or_b32 v131, v103, s33, v102
	v_ashrrev_i32_e32 v102, 31, v99
	v_mul_lo_u32 v104, s9, v99
	v_mul_lo_u32 v105, s8, v102
	v_mad_u64_u32 v[102:103], s[10:11], s8, v99, 0
	v_add3_u32 v103, v103, v105, v104
	v_lshl_add_u64 v[102:103], v[102:103], 1, s[4:5]
	v_lshl_add_u64 v[102:103], s[6:7], 1, v[102:103]
	v_lshl_add_u64 v[102:103], v[102:103], 0, v[146:147]
	global_store_dwordx4 v[102:103], v[128:131], off sc0 sc1
	ds_read2_b32 v[108:109], v112 offset0:16 offset1:49
	ds_read2_b32 v[106:107], v112 offset0:82 offset1:115
	ds_read2_b32 v[104:105], v112 offset0:148 offset1:181
	ds_read2_b32 v[102:103], v112 offset0:214 offset1:247
	v_or_b32_e32 v128, s19, v110
	s_mov_b64 s[10:11], -1
	s_and_b64 vcc, exec, s[0:1]
	s_cbranch_vccnz .LBB0_1129
	s_lshl_b32 s10, s19, 1
	s_and_b32 s10, s10, 0xffffff00
	v_and_b32_e32 v99, 0x77, v128
	v_or_b32_e32 v99, s10, v99
	v_or_b32_e32 v99, s20, v99
	s_mov_b64 s[10:11], 0

; #define GAS __attribute__((address_space(1)))
; #define LAS __attribute__((address_space(3)))
; #define LDS_WAIT() asm volatile("s_waitcnt lgkmcnt(0)" ::: "memory")
; __device__ __forceinline__ unsigned pk2(float lo, float hi) { return f2bf(lo) | (f2bf(hi) << 16); }
; __device__ __forceinline__ void cv_finish(const CvDesc& d, const f32x4 (&wv)[8], LAS float* scr, int lane) {
;     ...
;     for (int j = 0; j < 4; ++j) { const int n = (lane >> 3) + 8 * j; const LAS float* s = scr + (8 * cch) * 33 + n;
;         v4u o; o.x = pk2(s[0 * 33], s[1 * 33]); o.y = pk2(s[2 * 33], s[3 * 33]); o.z = pk2(s[4 * 33], s[5 * 33]); o.w = pk2(s[6 * 33], s[7 * 33]);
;         const int nn = d.n0 + n; const int drow = d.mode ? (d.row_off + (nn >> 7) * 256 + (nn & 127)) : (d.row_off + nn);
;         *(GAS v4u*)(d.WT + (size_t)drow * d.K + d.k0 + 8 * cch) = o; }
;     LDS_WAIT(); asm volatile("" ::: "memory");
.LBB0_1131:
	s_waitcnt lgkmcnt(3)
	v_bfe_u32 v128, v108, 16, 1
	v_add3_u32 v108, v108, v128, s70
	v_bfe_u32 v128, v109, 16, 1
	v_lshrrev_b32_e32 v108, 16, v108
	v_add3_u32 v109, v109, v128, s70
	v_and_or_b32 v128, v109, s33, v108
	s_waitcnt lgkmcnt(2)
	v_bfe_u32 v108, v106, 16, 1
	v_add3_u32 v106, v106, v108, s70
	v_bfe_u32 v108, v107, 16, 1
	v_lshrrev_b32_e32 v106, 16, v106
	v_add3_u32 v107, v107, v108, s70
	v_and_or_b32 v129, v107, s33, v106
	s_waitcnt lgkmcnt(1)
	v_bfe_u32 v106, v104, 16, 1
	v_add3_u32 v104, v104, v106, s70
	v_bfe_u32 v106, v105, 16, 1
	v_lshrrev_b32_e32 v104, 16, v104
	v_add3_u32 v105, v105, v106, s70
	v_and_or_b32 v130, v105, s33, v104
	s_waitcnt lgkmcnt(0)
	v_bfe_u32 v104, v102, 16, 1
	v_add3_u32 v102, v102, v104, s70
	v_bfe_u32 v104, v103, 16, 1
	v_lshrrev_b32_e32 v102, 16, v102
	v_add3_u32 v103, v103, v104, s70
	v_and_or_b32 v131, v103, s33, v102
	v_ashrrev_i32_e32 v102, 31, v99
	v_mul_lo_u32 v104, s9, v99
	v_mul_lo_u32 v105, s8, v102
	v_mad_u64_u32 v[102:103], s[10:11], s8, v99, 0
	v_add3_u32 v103, v103, v105, v104
	v_lshl_add_u64 v[102:103], v[102:103], 1, s[4:5]
	v_lshl_add_u64 v[102:103], s[6:7], 1, v[102:103]
	v_lshl_add_u64 v[102:103], v[102:103], 0, v[146:147]
	global_store_dwordx4 v[102:103], v[128:131], off sc0 sc1
	ds_read2_b32 v[108:109], v112 offset0:24 offset1:57
	ds_read2_b32 v[106:107], v112 offset0:90 offset1:123
	ds_read2_b32 v[104:105], v112 offset0:156 offset1:189
	ds_read2_b32 v[102:103], v112 offset0:222 offset1:255
	v_or_b32_e32 v128, s19, v111
	s_mov_b64 s[10:11], -1
	s_and_b64 vcc, exec, s[0:1]
	s_cbranch_vccnz .LBB0_1133
	s_lshl_b32 s0, s19, 1
	s_and_b32 s0, s0, 0xffffff00
	v_and_b32_e32 v99, 0x7f, v128
	v_or_b32_e32 v99, s0, v99
	v_or_b32_e32 v99, s20, v99
	s_mov_b64 s[10:11], 0

; #define GAS __attribute__((address_space(1)))
; #define LAS __attribute__((address_space(3)))
; #define LDS_WAIT() asm volatile("s_waitcnt lgkmcnt(0)" ::: "memory")
; __device__ __forceinline__ unsigned pk2(float lo, float hi) { return f2bf(lo) | (f2bf(hi) << 16); }
; __device__ __forceinline__ void cv_finish(const CvDesc& d, const f32x4 (&wv)[8], LAS float* scr, int lane) {
;     ...
;     for (int j = 0; j < 4; ++j) { const int n = (lane >> 3) + 8 * j; const LAS float* s = scr + (8 * cch) * 33 + n;
;         v4u o; o.x = pk2(s[0 * 33], s[1 * 33]); o.y = pk2(s[2 * 33], s[3 * 33]); o.z = pk2(s[4 * 33], s[5 * 33]); o.w = pk2(s[6 * 33], s[7 * 33]);
;         const int nn = d.n0 + n; const int drow = d.mode ? (d.row_off + (nn >> 7) * 256 + (nn & 127)) : (d.row_off + nn);
;         *(GAS v4u*)(d.WT + (size_t)drow * d.K + d.k0 + 8 * cch) = o; }
;     LDS_WAIT(); asm volatile("" ::: "memory");
.LBB0_1135:
	s_waitcnt lgkmcnt(3)
	v_bfe_u32 v128, v109, 16, 1
	v_add3_u32 v109, v109, v128, s70
	v_bfe_u32 v128, v108, 16, 1
	v_add3_u32 v108, v108, v128, s70
	v_lshrrev_b32_e32 v108, 16, v108
	v_and_or_b32 v128, v109, s33, v108
	s_waitcnt lgkmcnt(2)
	v_bfe_u32 v108, v107, 16, 1
	v_add3_u32 v107, v107, v108, s70
	v_bfe_u32 v108, v106, 16, 1
	v_add3_u32 v106, v106, v108, s70
	v_lshrrev_b32_e32 v106, 16, v106
	v_and_or_b32 v129, v107, s33, v106
	s_waitcnt lgkmcnt(1)
	v_bfe_u32 v106, v105, 16, 1
	v_add3_u32 v105, v105, v106, s70
	v_bfe_u32 v106, v104, 16, 1
	v_add3_u32 v104, v104, v106, s70
	v_lshrrev_b32_e32 v104, 16, v104
	v_and_or_b32 v130, v105, s33, v104
	s_waitcnt lgkmcnt(0)
	v_bfe_u32 v104, v103, 16, 1
	v_add3_u32 v103, v103, v104, s70
	v_bfe_u32 v104, v102, 16, 1
	v_add3_u32 v102, v102, v104, s70
	v_lshrrev_b32_e32 v102, 16, v102
	v_and_or_b32 v131, v103, s33, v102
	v_ashrrev_i32_e32 v102, 31, v99
	v_mul_lo_u32 v104, s9, v99
	v_mul_lo_u32 v105, s8, v102
	v_mad_u64_u32 v[102:103], s[0:1], s8, v99, 0
	v_add3_u32 v103, v103, v105, v104
	v_lshl_add_u64 v[102:103], v[102:103], 1, s[4:5]
	v_lshl_add_u64 v[102:103], s[6:7], 1, v[102:103]
	v_lshl_add_u64 v[102:103], v[102:103], 0, v[146:147]
	global_store_dwordx4 v[102:103], v[128:131], off sc0 sc1
	s_waitcnt lgkmcnt(0)
	s_add_i32 s0, s18, -3
	s_cmp_ge_i32 s0, s12
	s_cbranch_scc1 .LBB0_1085
	s_add_i32 s0, s18, -1
	s_cmp_ge_i32 s0, s12
	s_cbranch_scc1 .LBB0_1154
	v_readlane_b32 s0, v249, 44
	s_add_i32 s0, s0, s14
	s_mul_hi_i32 s1, s0, 0x2aaaaaab
	s_lshr_b32 s4, s1, 31
	s_ashr_i32 s1, s1, 13
	s_add_i32 s1, s1, s4
	s_mul_i32 s4, s1, 0xc000
	s_sub_i32 s0, s0, s4
	s_ashr_i32 s4, s0, 31
	s_lshr_b32 s4, s4, 18
	s_add_i32 s4, s0, s4
	s_and_b32 s5, s4, 0xffffc000
	s_sub_i32 s10, s0, s5
	s_lshl_b32 s1, s1, 14
	s_lshl_b32 s0, s4, 1
	s_add_i32 s11, s1, s10
	s_and_b32 s0, s0, 0xffff8000
	s_addk_i32 s11, 0x4800
	s_add_i32 s5, s11, s0
	s_cmpk_gt_i32 s5, 0x37ff
	s_mov_b64 s[8:9], -1
	s_cbranch_scc0 .LBB0_1151
	s_cmpk_gt_u32 s5, 0x47ff
	s_cbranch_scc0 .LBB0_1148
	s_cmpk_gt_u32 s5, 0xc7ff
	s_cbranch_scc0 .LBB0_1145
	s_lshl_b32 s8, s5, 5
	s_cmp_gt_u32 s5, 0x147ff
	s_mov_b64 s[6:7], -1
	s_cbranch_scc0 .LBB0_1142
	s_add_i32 s0, s5, 0xfffeb800
	s_lshr_b32 s58, s0, 10
	v_readlane_b32 s40, v249, 0
	s_lshl_b64 s[0:1], s[58:59], 23
	v_readlane_b32 s44, v249, 4
	v_readlane_b32 s45, v249, 5
	s_add_u32 s0, s44, s0
	v_readlane_b32 s41, v249, 1
	v_readlane_b32 s42, v249, 2
	v_readlane_b32 s43, v249, 3
	v_readlane_b32 s46, v249, 6
	v_readlane_b32 s47, v249, 7
	s_addc_u32 s1, s45, s1
	s_and_b32 s19, s10, 0x3c0
	s_and_b32 s4, s8, 0x7e0
	s_mov_b64 s[6:7], 0

; #define GAS __attribute__((address_space(1)))
; #define LAS __attribute__((address_space(3)))
; __device__ __forceinline__ unsigned pk2(float lo, float hi) { return f2bf(lo) | (f2bf(hi) << 16); }
; __device__ __forceinline__ void cv_finish(const CvDesc& d, const f32x4 (&wv)[8], LAS float* scr, int lane) {
;     ...
; #pragma unroll
;     for (int j = 0; j < 4; ++j) { const int n = (lane >> 3) + 8 * j; const LAS float* s = scr + (8 * cch) * 33 + n;
;         v4u o; o.x = pk2(s[0 * 33], s[1 * 33]); o.y = pk2(s[2 * 33], s[3 * 33]); o.z = pk2(s[4 * 33], s[5 * 33]); o.w = pk2(s[6 * 33], s[7 * 33]);
;         const int nn = d.n0 + n; const int drow = d.mode ? (d.row_off + (nn >> 7) * 256 + (nn & 127)) : (d.row_off + nn);
;         *(GAS v4u*)(d.WT + (size_t)drow * d.K + d.k0 + 8 * cch) = o; }
.LBB0_1173:
	s_waitcnt lgkmcnt(3)
	v_bfe_u32 v128, v108, 16, 1
	v_add3_u32 v108, v108, v128, s70
	v_bfe_u32 v128, v109, 16, 1
	v_lshrrev_b32_e32 v108, 16, v108
	v_add3_u32 v109, v109, v128, s70
	v_and_or_b32 v128, v109, s33, v108
	s_waitcnt lgkmcnt(2)
	v_bfe_u32 v108, v106, 16, 1
	v_add3_u32 v106, v106, v108, s70
	v_bfe_u32 v108, v107, 16, 1
	v_lshrrev_b32_e32 v106, 16, v106
	v_add3_u32 v107, v107, v108, s70
	v_and_or_b32 v129, v107, s33, v106
	s_waitcnt lgkmcnt(1)
	v_bfe_u32 v106, v104, 16, 1
	v_add3_u32 v104, v104, v106, s70
	v_bfe_u32 v106, v105, 16, 1
	v_lshrrev_b32_e32 v104, 16, v104
	v_add3_u32 v105, v105, v106, s70
	v_and_or_b32 v130, v105, s33, v104
	s_waitcnt lgkmcnt(0)
	v_bfe_u32 v104, v102, 16, 1
	v_add3_u32 v102, v102, v104, s70
	v_bfe_u32 v104, v103, 16, 1
	v_lshrrev_b32_e32 v102, 16, v102
	v_add3_u32 v103, v103, v104, s70
	v_and_or_b32 v131, v103, s33, v102
	v_ashrrev_i32_e32 v102, 31, v99
	v_mul_lo_u32 v104, s9, v99
	v_mul_lo_u32 v105, s8, v102
	v_mad_u64_u32 v[102:103], s[10:11], s8, v99, 0
	v_add3_u32 v103, v103, v105, v104
	v_lshl_add_u64 v[102:103], v[102:103], 1, s[4:5]
	s_ashr_i32 s7, s6, 31
	v_lshl_add_u64 v[102:103], s[6:7], 1, v[102:103]
	v_lshl_add_u64 v[102:103], v[102:103], 0, v[146:147]
	global_store_dwordx4 v[102:103], v[128:131], off sc0 sc1
	ds_read2_b32 v[108:109], v112 offset0:8 offset1:41
	ds_read2_b32 v[106:107], v112 offset0:74 offset1:107
	ds_read2_b32 v[104:105], v112 offset0:140 offset1:173
	ds_read2_b32 v[102:103], v112 offset0:206 offset1:239
	s_xor_b64 s[10:11], s[0:1], -1
	v_cndmask_b32_e64 v99, 0, 1, s[10:11]
	v_or_b32_e32 v128, s19, v101
	v_cmp_ne_u32_e64 s[0:1], 1, v99
	s_andn2_b64 vcc, exec, s[10:11]
	s_mov_b64 s[10:11], -1
	s_cbranch_vccnz .LBB0_1175
	s_lshl_b32 s10, s19, 1
	s_and_b32 s10, s10, 0xffffff00
	v_and_b32_e32 v99, 0x6f, v128
	v_or_b32_e32 v99, s10, v99
	v_or_b32_e32 v99, s20, v99
	s_mov_b64 s[10:11], 0

; #define GAS __attribute__((address_space(1)))
; #define LAS __attribute__((address_space(3)))
; #define LDS_WAIT() asm volatile("s_waitcnt lgkmcnt(0)" ::: "memory")
; __device__ __forceinline__ unsigned pk2(float lo, float hi) { return f2bf(lo) | (f2bf(hi) << 16); }
; __device__ __forceinline__ CvDesc cv_desc(const Frame& F, int it) {
;     bf16* WIN = (bf16*)(F.ws + WS_WIN); bf16* WOUT = (bf16*)(F.ws + WS_WOUT); bf16* WGU = (bf16*)(F.ws + WS_WGU); bf16* WD = (bf16*)(F.ws + WS_WD);
;     int r = it;
;     if (r < CV_N_IN) { const int l = r / CV_I_IN, i = r % CV_I_IN; return CvDesc{F.w_in + (size_t)l * DM * PROJ_W, WIN + (size_t)l * PROJ_W * DM, DM, PROJ_W, 0, 0, 64 * (i / (PROJ_W / 32)), 32 * (i % (PROJ_W / 32))}; } r -= CV_N_IN;
;     if (r < CV_N_OUT) { const int l = r / CV_I_OUT, i = r % CV_I_OUT; return CvDesc{F.w_out + (size_t)l * DM * DM, WOUT + (size_t)l * DM * DM, DM, DM, 0, 0, 64 * (i / (DM / 32)), 32 * (i % (DM / 32))}; } r -= CV_N_OUT;
;     if (r < CV_N_G) { const int le = r / CV_I_GU, i = r % CV_I_GU; return CvDesc{F.w_gate + (size_t)le * DM * EFF, WGU + (size_t)le * 2048 * DM, DM, EFF, 0, 1, 64 * (i / (EFF / 32)), 32 * (i % (EFF / 32))}; } r -= CV_N_G;
;     if (r < CV_N_G) { const int le = r / CV_I_GU, i = r % CV_I_GU; return CvDesc{F.w_up + (size_t)le * DM * EFF, WGU + (size_t)le * 2048 * DM, DM, EFF, 128, 1, 64 * (i / (EFF / 32)), 32 * (i % (EFF / 32))}; } r -= CV_N_G;
;     { const int le = r / CV_I_DN, i = r % CV_I_DN; return CvDesc{F.w_down + (size_t)le * EFF * DM, WD + (size_t)le * DM * EFF, EFF, DM, 0, 0, 64 * (i / (DM / 32)), 32 * (i % (DM / 32))}; }
; __device__ __forceinline__ void cv_finish(const CvDesc& d, const f32x4 (&wv)[8], LAS float* scr, int lane) {
;     ...
;     for (int j = 0; j < 4; ++j) { const int n = (lane >> 3) + 8 * j; const LAS float* s = scr + (8 * cch) * 33 + n;
;         v4u o; o.x = pk2(s[0 * 33], s[1 * 33]); o.y = pk2(s[2 * 33], s[3 * 33]); o.z = pk2(s[4 * 33], s[5 * 33]); o.w = pk2(s[6 * 33], s[7 * 33]);
;         const int nn = d.n0 + n; const int drow = d.mode ? (d.row_off + (nn >> 7) * 256 + (nn & 127)) : (d.row_off + nn);
;         *(GAS v4u*)(d.WT + (size_t)drow * d.K + d.k0 + 8 * cch) = o; }
;     LDS_WAIT(); asm volatile("" ::: "memory");
.LBB0_1185:
	s_waitcnt lgkmcnt(3)
	v_bfe_u32 v128, v109, 16, 1
	v_add3_u32 v109, v109, v128, s70
	v_bfe_u32 v128, v108, 16, 1
	v_add3_u32 v108, v108, v128, s70
	v_lshrrev_b32_e32 v108, 16, v108
	v_and_or_b32 v128, v109, s33, v108
	s_waitcnt lgkmcnt(2)
	v_bfe_u32 v108, v107, 16, 1
	v_add3_u32 v107, v107, v108, s70
	v_bfe_u32 v108, v106, 16, 1
	v_add3_u32 v106, v106, v108, s70
	v_lshrrev_b32_e32 v106, 16, v106
	v_and_or_b32 v129, v107, s33, v106
	s_waitcnt lgkmcnt(1)
	v_bfe_u32 v106, v105, 16, 1
	v_add3_u32 v105, v105, v106, s70
	v_bfe_u32 v106, v104, 16, 1
	v_add3_u32 v104, v104, v106, s70
	v_lshrrev_b32_e32 v104, 16, v104
	v_and_or_b32 v130, v105, s33, v104
	s_waitcnt lgkmcnt(0)
	v_bfe_u32 v104, v103, 16, 1
	v_add3_u32 v103, v103, v104, s70
	v_bfe_u32 v104, v102, 16, 1
	v_add3_u32 v102, v102, v104, s70
	v_lshrrev_b32_e32 v102, 16, v102
	v_and_or_b32 v131, v103, s33, v102
	v_ashrrev_i32_e32 v102, 31, v99
	v_mul_lo_u32 v104, s9, v99
	v_mul_lo_u32 v105, s8, v102
	v_mad_u64_u32 v[102:103], s[0:1], s8, v99, 0
	v_add3_u32 v103, v103, v105, v104
	v_lshl_add_u64 v[102:103], v[102:103], 1, s[4:5]
	v_lshl_add_u64 v[102:103], s[6:7], 1, v[102:103]
	v_lshl_add_u64 v[102:103], v[102:103], 0, v[146:147]
	global_store_dwordx4 v[102:103], v[128:131], off sc0 sc1
	s_waitcnt lgkmcnt(0)
	s_andn2_b64 vcc, exec, s[2:3]
	s_cbranch_vccnz .LBB0_1085
	s_cmp_ge_i32 s18, s12
	s_cbranch_scc1 .LBB0_1204
	v_readlane_b32 s0, v249, 44
	s_add_i32 s0, s0, s13
	s_mul_hi_i32 s1, s0, 0x2aaaaaab
	s_lshr_b32 s2, s1, 31
	s_ashr_i32 s1, s1, 13
	s_add_i32 s1, s1, s2
	s_mul_i32 s2, s1, 0xc000
	s_sub_i32 s0, s0, s2
	s_ashr_i32 s2, s0, 31
	s_lshr_b32 s2, s2, 18
	s_add_i32 s2, s0, s2
	s_and_b32 s3, s2, 0xffffc000
	s_sub_i32 s8, s0, s3
	s_lshl_b32 s1, s1, 14
	s_lshl_b32 s0, s2, 1
	s_add_i32 s9, s1, s8
	s_and_b32 s0, s0, 0xffff8000
	s_addk_i32 s9, 0x4800
	s_add_i32 s3, s9, s0
	s_cmpk_gt_i32 s3, 0x37ff
	s_mov_b64 s[6:7], -1
	s_cbranch_scc0 .LBB0_1201
	s_cmpk_gt_u32 s3, 0x47ff
	s_cbranch_scc0 .LBB0_1198
	s_cmpk_gt_u32 s3, 0xc7ff
	s_cbranch_scc0 .LBB0_1195
	s_lshl_b32 s6, s3, 5
	s_cmp_gt_u32 s3, 0x147ff
	s_mov_b64 s[4:5], -1
	s_cbranch_scc0 .LBB0_1192
	s_add_i32 s0, s3, 0xfffeb800
	s_lshr_b32 s58, s0, 10
	v_readlane_b32 s40, v249, 0
	s_lshl_b64 s[0:1], s[58:59], 23
	v_readlane_b32 s44, v249, 4
	v_readlane_b32 s45, v249, 5
	s_add_u32 s0, s44, s0
	v_readlane_b32 s41, v249, 1
	v_readlane_b32 s42, v249, 2
	v_readlane_b32 s43, v249, 3
	v_readlane_b32 s46, v249, 6
	v_readlane_b32 s47, v249, 7
	s_addc_u32 s1, s45, s1
	s_and_b32 s10, s8, 0x3c0
	s_and_b32 s2, s6, 0x7e0
	s_mov_b64 s[4:5], 0

; #define GAS __attribute__((address_space(1)))
; #define LAS __attribute__((address_space(3)))
; __device__ __forceinline__ unsigned pk2(float lo, float hi) { return f2bf(lo) | (f2bf(hi) << 16); }
; __device__ __forceinline__ void cv_finish(const CvDesc& d, const f32x4 (&wv)[8], LAS float* scr, int lane) {
;     ...
; #pragma unroll
;     for (int j = 0; j < 4; ++j) { const int n = (lane >> 3) + 8 * j; const LAS float* s = scr + (8 * cch) * 33 + n;
;         v4u o; o.x = pk2(s[0 * 33], s[1 * 33]); o.y = pk2(s[2 * 33], s[3 * 33]); o.z = pk2(s[4 * 33], s[5 * 33]); o.w = pk2(s[6 * 33], s[7 * 33]);
;         const int nn = d.n0 + n; const int drow = d.mode ? (d.row_off + (nn >> 7) * 256 + (nn & 127)) : (d.row_off + nn);
;         *(GAS v4u*)(d.WT + (size_t)drow * d.K + d.k0 + 8 * cch) = o; }
.LBB0_1223:
	s_waitcnt lgkmcnt(3)
	v_bfe_u32 v114, v108, 16, 1
	v_add3_u32 v108, v108, v114, s70
	v_bfe_u32 v114, v109, 16, 1
	v_lshrrev_b32_e32 v108, 16, v108
	v_add3_u32 v109, v109, v114, s70
	v_and_or_b32 v114, v109, s33, v108
	s_waitcnt lgkmcnt(2)
	v_bfe_u32 v108, v106, 16, 1
	v_add3_u32 v106, v106, v108, s70
	v_bfe_u32 v108, v107, 16, 1
	v_lshrrev_b32_e32 v106, 16, v106
	v_add3_u32 v107, v107, v108, s70
	v_and_or_b32 v115, v107, s33, v106
	s_waitcnt lgkmcnt(1)
	v_bfe_u32 v106, v104, 16, 1
	v_add3_u32 v104, v104, v106, s70
	v_bfe_u32 v106, v105, 16, 1
	v_lshrrev_b32_e32 v104, 16, v104
	v_add3_u32 v105, v105, v106, s70
	v_and_or_b32 v116, v105, s33, v104
	s_waitcnt lgkmcnt(0)
	v_bfe_u32 v104, v102, 16, 1
	v_add3_u32 v102, v102, v104, s70
	v_bfe_u32 v104, v103, 16, 1
	v_lshrrev_b32_e32 v102, 16, v102
	v_add3_u32 v103, v103, v104, s70
	v_and_or_b32 v117, v103, s33, v102
	v_ashrrev_i32_e32 v102, 31, v99
	v_mul_lo_u32 v104, s7, v99
	v_mul_lo_u32 v105, s6, v102
	v_mad_u64_u32 v[102:103], s[8:9], s6, v99, 0
	v_add3_u32 v103, v103, v105, v104
	v_lshl_add_u64 v[102:103], v[102:103], 1, s[2:3]
	s_ashr_i32 s5, s4, 31
	v_lshl_add_u64 v[102:103], s[4:5], 1, v[102:103]
	v_lshl_add_u64 v[102:103], v[102:103], 0, v[146:147]
	global_store_dwordx4 v[102:103], v[114:117], off sc0 sc1
	ds_read2_b32 v[108:109], v112 offset0:8 offset1:41
	ds_read2_b32 v[106:107], v112 offset0:74 offset1:107
	ds_read2_b32 v[104:105], v112 offset0:140 offset1:173
	ds_read2_b32 v[102:103], v112 offset0:206 offset1:239
	s_xor_b64 s[8:9], s[0:1], -1
	v_cndmask_b32_e64 v99, 0, 1, s[8:9]
	v_or_b32_e32 v114, s10, v101
	v_cmp_ne_u32_e64 s[0:1], 1, v99
	s_andn2_b64 vcc, exec, s[8:9]
	s_mov_b64 s[8:9], -1
	s_cbranch_vccnz .LBB0_1225
	s_lshl_b32 s8, s10, 1
	s_and_b32 s8, s8, 0xffffff00
	v_and_b32_e32 v99, 0x6f, v114
	v_or_b32_e32 v99, s8, v99
	v_or_b32_e32 v99, s11, v99
	s_mov_b64 s[8:9], 0

; #define GAS __attribute__((address_space(1)))
; #define LAS __attribute__((address_space(3)))
; __device__ __forceinline__ unsigned pk2(float lo, float hi) { return f2bf(lo) | (f2bf(hi) << 16); }
; __device__ __forceinline__ void cv_finish(const CvDesc& d, const f32x4 (&wv)[8], LAS float* scr, int lane) {
;     ...
; #pragma unroll
;     for (int j = 0; j < 4; ++j) { const int n = (lane >> 3) + 8 * j; const LAS float* s = scr + (8 * cch) * 33 + n;
;         v4u o; o.x = pk2(s[0 * 33], s[1 * 33]); o.y = pk2(s[2 * 33], s[3 * 33]); o.z = pk2(s[4 * 33], s[5 * 33]); o.w = pk2(s[6 * 33], s[7 * 33]);
;         const int nn = d.n0 + n; const int drow = d.mode ? (d.row_off + (nn >> 7) * 256 + (nn & 127)) : (d.row_off + nn);
;         *(GAS v4u*)(d.WT + (size_t)drow * d.K + d.k0 + 8 * cch) = o; }
.LBB0_1227:
	s_waitcnt lgkmcnt(3)
	v_bfe_u32 v114, v108, 16, 1
	v_add3_u32 v108, v108, v114, s70
	v_bfe_u32 v114, v109, 16, 1
	v_lshrrev_b32_e32 v108, 16, v108
	v_add3_u32 v109, v109, v114, s70
	v_and_or_b32 v114, v109, s33, v108
	s_waitcnt lgkmcnt(2)
	v_bfe_u32 v108, v106, 16, 1
	v_add3_u32 v106, v106, v108, s70
	v_bfe_u32 v108, v107, 16, 1
	v_lshrrev_b32_e32 v106, 16, v106
	v_add3_u32 v107, v107, v108, s70
	v_and_or_b32 v115, v107, s33, v106
	s_waitcnt lgkmcnt(1)
	v_bfe_u32 v106, v104, 16, 1
	v_add3_u32 v104, v104, v106, s70
	v_bfe_u32 v106, v105, 16, 1
	v_lshrrev_b32_e32 v104, 16, v104
	v_add3_u32 v105, v105, v106, s70
	v_and_or_b32 v116, v105, s33, v104
	s_waitcnt lgkmcnt(0)
	v_bfe_u32 v104, v102, 16, 1
	v_add3_u32 v102, v102, v104, s70
	v_bfe_u32 v104, v103, 16, 1
	v_lshrrev_b32_e32 v102, 16, v102
	v_add3_u32 v103, v103, v104, s70
	v_and_or_b32 v117, v103, s33, v102
	v_ashrrev_i32_e32 v102, 31, v99
	v_mul_lo_u32 v104, s7, v99
	v_mul_lo_u32 v105, s6, v102
	v_mad_u64_u32 v[102:103], s[8:9], s6, v99, 0
	v_add3_u32 v103, v103, v105, v104
	v_lshl_add_u64 v[102:103], v[102:103], 1, s[2:3]
	v_lshl_add_u64 v[102:103], s[4:5], 1, v[102:103]
	v_lshl_add_u64 v[102:103], v[102:103], 0, v[146:147]
	global_store_dwordx4 v[102:103], v[114:117], off sc0 sc1
	ds_read2_b32 v[108:109], v112 offset0:16 offset1:49
	ds_read2_b32 v[106:107], v112 offset0:82 offset1:115
	ds_read2_b32 v[104:105], v112 offset0:148 offset1:181
	ds_read2_b32 v[102:103], v112 offset0:214 offset1:247
	v_or_b32_e32 v114, s10, v110
	s_mov_b64 s[8:9], -1
	s_and_b64 vcc, exec, s[0:1]
	s_cbranch_vccnz .LBB0_1229
	s_lshl_b32 s8, s10, 1
	s_and_b32 s8, s8, 0xffffff00
	v_and_b32_e32 v99, 0x77, v114
	v_or_b32_e32 v99, s8, v99
	v_or_b32_e32 v99, s11, v99
	s_mov_b64 s[8:9], 0

; #define GAS __attribute__((address_space(1)))
; #define LAS __attribute__((address_space(3)))
; __device__ __forceinline__ unsigned pk2(float lo, float hi) { return f2bf(lo) | (f2bf(hi) << 16); }
; __device__ __forceinline__ void cv_finish(const CvDesc& d, const f32x4 (&wv)[8], LAS float* scr, int lane) {
;     ...
; #pragma unroll
;     for (int j = 0; j < 4; ++j) { const int n = (lane >> 3) + 8 * j; const LAS float* s = scr + (8 * cch) * 33 + n;
;         v4u o; o.x = pk2(s[0 * 33], s[1 * 33]); o.y = pk2(s[2 * 33], s[3 * 33]); o.z = pk2(s[4 * 33], s[5 * 33]); o.w = pk2(s[6 * 33], s[7 * 33]);
;         const int nn = d.n0 + n; const int drow = d.mode ? (d.row_off + (nn >> 7) * 256 + (nn & 127)) : (d.row_off + nn);
;         *(GAS v4u*)(d.WT + (size_t)drow * d.K + d.k0 + 8 * cch) = o; }
.LBB0_1231:
	s_waitcnt lgkmcnt(3)
	v_bfe_u32 v114, v108, 16, 1
	v_add3_u32 v108, v108, v114, s70
	v_bfe_u32 v114, v109, 16, 1
	v_lshrrev_b32_e32 v108, 16, v108
	v_add3_u32 v109, v109, v114, s70
	v_and_or_b32 v114, v109, s33, v108
	s_waitcnt lgkmcnt(2)
	v_bfe_u32 v108, v106, 16, 1
	v_add3_u32 v106, v106, v108, s70
	v_bfe_u32 v108, v107, 16, 1
	v_lshrrev_b32_e32 v106, 16, v106
	v_add3_u32 v107, v107, v108, s70
	v_and_or_b32 v115, v107, s33, v106
	s_waitcnt lgkmcnt(1)
	v_bfe_u32 v106, v104, 16, 1
	v_add3_u32 v104, v104, v106, s70
	v_bfe_u32 v106, v105, 16, 1
	v_lshrrev_b32_e32 v104, 16, v104
	v_add3_u32 v105, v105, v106, s70
	v_and_or_b32 v116, v105, s33, v104
	s_waitcnt lgkmcnt(0)
	v_bfe_u32 v104, v102, 16, 1
	v_add3_u32 v102, v102, v104, s70
	v_bfe_u32 v104, v103, 16, 1
	v_lshrrev_b32_e32 v102, 16, v102
	v_add3_u32 v103, v103, v104, s70
	v_and_or_b32 v117, v103, s33, v102
	v_ashrrev_i32_e32 v102, 31, v99
	v_mul_lo_u32 v104, s7, v99
	v_mul_lo_u32 v105, s6, v102
	v_mad_u64_u32 v[102:103], s[8:9], s6, v99, 0
	v_add3_u32 v103, v103, v105, v104
	v_lshl_add_u64 v[102:103], v[102:103], 1, s[2:3]
	v_lshl_add_u64 v[102:103], s[4:5], 1, v[102:103]
	v_lshl_add_u64 v[102:103], v[102:103], 0, v[146:147]
	global_store_dwordx4 v[102:103], v[114:117], off sc0 sc1
	ds_read2_b32 v[108:109], v112 offset0:24 offset1:57
	ds_read2_b32 v[106:107], v112 offset0:90 offset1:123
	ds_read2_b32 v[104:105], v112 offset0:156 offset1:189
	ds_read2_b32 v[102:103], v112 offset0:222 offset1:255
	v_or_b32_e32 v114, s10, v111
	s_mov_b64 s[8:9], -1
	s_and_b64 vcc, exec, s[0:1]
	s_cbranch_vccnz .LBB0_1233
	s_lshl_b32 s0, s10, 1
	s_and_b32 s0, s0, 0xffffff00
	v_and_b32_e32 v99, 0x7f, v114
	v_or_b32_e32 v99, s0, v99
	v_or_b32_e32 v99, s11, v99
	s_mov_b64 s[8:9], 0

; #define GAS __attribute__((address_space(1)))
; #define LAS __attribute__((address_space(3)))
; __device__ __forceinline__ unsigned pk2(float lo, float hi) { return f2bf(lo) | (f2bf(hi) << 16); }
; __device__ __forceinline__ void cv_finish(const CvDesc& d, const f32x4 (&wv)[8], LAS float* scr, int lane) {
;     ...
; #pragma unroll
;     for (int j = 0; j < 4; ++j) { const int n = (lane >> 3) + 8 * j; const LAS float* s = scr + (8 * cch) * 33 + n;
;         v4u o; o.x = pk2(s[0 * 33], s[1 * 33]); o.y = pk2(s[2 * 33], s[3 * 33]); o.z = pk2(s[4 * 33], s[5 * 33]); o.w = pk2(s[6 * 33], s[7 * 33]);
;         const int nn = d.n0 + n; const int drow = d.mode ? (d.row_off + (nn >> 7) * 256 + (nn & 127)) : (d.row_off + nn);
;         *(GAS v4u*)(d.WT + (size_t)drow * d.K + d.k0 + 8 * cch) = o; }
.LBB0_1795:
	s_waitcnt lgkmcnt(3)
	v_bfe_u32 v128, v108, 16, 1
	v_add3_u32 v108, v108, v128, s70
	v_bfe_u32 v128, v109, 16, 1
	v_lshrrev_b32_e32 v108, 16, v108
	v_add3_u32 v109, v109, v128, s70
	v_and_or_b32 v128, v109, s33, v108
	s_waitcnt lgkmcnt(2)
	v_bfe_u32 v108, v106, 16, 1
	v_add3_u32 v106, v106, v108, s70
	v_bfe_u32 v108, v107, 16, 1
	v_lshrrev_b32_e32 v106, 16, v106
	v_add3_u32 v107, v107, v108, s70
	v_and_or_b32 v129, v107, s33, v106
	s_waitcnt lgkmcnt(1)
	v_bfe_u32 v106, v104, 16, 1
	v_add3_u32 v104, v104, v106, s70
	v_bfe_u32 v106, v105, 16, 1
	v_lshrrev_b32_e32 v104, 16, v104
	v_add3_u32 v105, v105, v106, s70
	v_and_or_b32 v130, v105, s33, v104
	s_waitcnt lgkmcnt(0)
	v_bfe_u32 v104, v102, 16, 1
	v_add3_u32 v102, v102, v104, s70
	v_bfe_u32 v104, v103, 16, 1
	v_lshrrev_b32_e32 v102, 16, v102
	v_add3_u32 v103, v103, v104, s70
	v_and_or_b32 v131, v103, s33, v102
	v_ashrrev_i32_e32 v102, 31, v99
	v_mul_lo_u32 v104, s9, v99
	v_mul_lo_u32 v105, s8, v102
	v_mad_u64_u32 v[102:103], s[10:11], s8, v99, 0
	v_add3_u32 v103, v103, v105, v104
	v_lshl_add_u64 v[102:103], v[102:103], 1, s[4:5]
	s_ashr_i32 s7, s6, 31
	v_lshl_add_u64 v[102:103], s[6:7], 1, v[102:103]
	v_lshlrev_b32_e32 v146, 1, v100
	v_lshl_add_u64 v[102:103], v[102:103], 0, v[146:147]
	global_store_dwordx4 v[102:103], v[128:131], off sc0 sc1
	ds_read2_b32 v[108:109], v112 offset0:8 offset1:41
	ds_read2_b32 v[106:107], v112 offset0:74 offset1:107
	ds_read2_b32 v[104:105], v112 offset0:140 offset1:173
	ds_read2_b32 v[102:103], v112 offset0:206 offset1:239
	s_xor_b64 s[10:11], s[0:1], -1
	v_cndmask_b32_e64 v99, 0, 1, s[10:11]
	v_or_b32_e32 v128, s15, v101
	v_cmp_ne_u32_e64 s[0:1], 1, v99
	s_andn2_b64 vcc, exec, s[10:11]
	s_mov_b64 s[10:11], -1
	s_cbranch_vccnz .LBB0_1797
	s_lshl_b32 s10, s15, 1
	s_and_b32 s10, s10, 0xffffff00
	v_and_b32_e32 v99, 0x6f, v128
	v_or_b32_e32 v99, s10, v99
	v_or_b32_e32 v99, s16, v99
	s_mov_b64 s[10:11], 0

; #define GAS __attribute__((address_space(1)))
; #define LAS __attribute__((address_space(3)))
; __device__ __forceinline__ unsigned pk2(float lo, float hi) { return f2bf(lo) | (f2bf(hi) << 16); }
; __device__ __forceinline__ void cv_finish(const CvDesc& d, const f32x4 (&wv)[8], LAS float* scr, int lane) {
;     ...
; #pragma unroll
;     for (int j = 0; j < 4; ++j) { const int n = (lane >> 3) + 8 * j; const LAS float* s = scr + (8 * cch) * 33 + n;
;         v4u o; o.x = pk2(s[0 * 33], s[1 * 33]); o.y = pk2(s[2 * 33], s[3 * 33]); o.z = pk2(s[4 * 33], s[5 * 33]); o.w = pk2(s[6 * 33], s[7 * 33]);
;         const int nn = d.n0 + n; const int drow = d.mode ? (d.row_off + (nn >> 7) * 256 + (nn & 127)) : (d.row_off + nn);
;         *(GAS v4u*)(d.WT + (size_t)drow * d.K + d.k0 + 8 * cch) = o; }
.LBB0_1799:
	s_waitcnt lgkmcnt(3)
	v_bfe_u32 v128, v108, 16, 1
	v_add3_u32 v108, v108, v128, s70
	v_bfe_u32 v128, v109, 16, 1
	v_lshrrev_b32_e32 v108, 16, v108
	v_add3_u32 v109, v109, v128, s70
	v_and_or_b32 v128, v109, s33, v108
	s_waitcnt lgkmcnt(2)
	v_bfe_u32 v108, v106, 16, 1
	v_add3_u32 v106, v106, v108, s70
	v_bfe_u32 v108, v107, 16, 1
	v_lshrrev_b32_e32 v106, 16, v106
	v_add3_u32 v107, v107, v108, s70
	v_and_or_b32 v129, v107, s33, v106
	s_waitcnt lgkmcnt(1)
	v_bfe_u32 v106, v104, 16, 1
	v_add3_u32 v104, v104, v106, s70
	v_bfe_u32 v106, v105, 16, 1
	v_lshrrev_b32_e32 v104, 16, v104
	v_add3_u32 v105, v105, v106, s70
	v_and_or_b32 v130, v105, s33, v104
	s_waitcnt lgkmcnt(0)
	v_bfe_u32 v104, v102, 16, 1
	v_add3_u32 v102, v102, v104, s70
	v_bfe_u32 v104, v103, 16, 1
	v_lshrrev_b32_e32 v102, 16, v102
	v_add3_u32 v103, v103, v104, s70
	v_and_or_b32 v131, v103, s33, v102
	v_ashrrev_i32_e32 v102, 31, v99
	v_mul_lo_u32 v104, s9, v99
	v_mul_lo_u32 v105, s8, v102
	v_mad_u64_u32 v[102:103], s[10:11], s8, v99, 0
	v_add3_u32 v103, v103, v105, v104
	v_lshl_add_u64 v[102:103], v[102:103], 1, s[4:5]
	v_lshl_add_u64 v[102:103], s[6:7], 1, v[102:103]
	v_lshl_add_u64 v[102:103], v[102:103], 0, v[146:147]
	global_store_dwordx4 v[102:103], v[128:131], off sc0 sc1
	ds_read2_b32 v[108:109], v112 offset0:16 offset1:49
	ds_read2_b32 v[106:107], v112 offset0:82 offset1:115
	ds_read2_b32 v[104:105], v112 offset0:148 offset1:181
	ds_read2_b32 v[102:103], v112 offset0:214 offset1:247
	v_or_b32_e32 v128, s15, v110
	s_mov_b64 s[10:11], -1
	s_and_b64 vcc, exec, s[0:1]
	s_cbranch_vccnz .LBB0_1801
	s_lshl_b32 s10, s15, 1
	s_and_b32 s10, s10, 0xffffff00
	v_and_b32_e32 v99, 0x77, v128
	v_or_b32_e32 v99, s10, v99
	v_or_b32_e32 v99, s16, v99
	s_mov_b64 s[10:11], 0

; #define GAS __attribute__((address_space(1)))
; #define LAS __attribute__((address_space(3)))
; __device__ __forceinline__ unsigned pk2(float lo, float hi) { return f2bf(lo) | (f2bf(hi) << 16); }
; __device__ __forceinline__ void cv_finish(const CvDesc& d, const f32x4 (&wv)[8], LAS float* scr, int lane) {
;     ...
; #pragma unroll
;     for (int j = 0; j < 4; ++j) { const int n = (lane >> 3) + 8 * j; const LAS float* s = scr + (8 * cch) * 33 + n;
;         v4u o; o.x = pk2(s[0 * 33], s[1 * 33]); o.y = pk2(s[2 * 33], s[3 * 33]); o.z = pk2(s[4 * 33], s[5 * 33]); o.w = pk2(s[6 * 33], s[7 * 33]);
;         const int nn = d.n0 + n; const int drow = d.mode ? (d.row_off + (nn >> 7) * 256 + (nn & 127)) : (d.row_off + nn);
;         *(GAS v4u*)(d.WT + (size_t)drow * d.K + d.k0 + 8 * cch) = o; }
.LBB0_1803:
	s_waitcnt lgkmcnt(3)
	v_bfe_u32 v128, v108, 16, 1
	v_add3_u32 v108, v108, v128, s70
	v_bfe_u32 v128, v109, 16, 1
	v_lshrrev_b32_e32 v108, 16, v108
	v_add3_u32 v109, v109, v128, s70
	v_and_or_b32 v128, v109, s33, v108
	s_waitcnt lgkmcnt(2)
	v_bfe_u32 v108, v106, 16, 1
	v_add3_u32 v106, v106, v108, s70
	v_bfe_u32 v108, v107, 16, 1
	v_lshrrev_b32_e32 v106, 16, v106
	v_add3_u32 v107, v107, v108, s70
	v_and_or_b32 v129, v107, s33, v106
	s_waitcnt lgkmcnt(1)
	v_bfe_u32 v106, v104, 16, 1
	v_add3_u32 v104, v104, v106, s70
	v_bfe_u32 v106, v105, 16, 1
	v_lshrrev_b32_e32 v104, 16, v104
	v_add3_u32 v105, v105, v106, s70
	v_and_or_b32 v130, v105, s33, v104
	s_waitcnt lgkmcnt(0)
	v_bfe_u32 v104, v102, 16, 1
	v_add3_u32 v102, v102, v104, s70
	v_bfe_u32 v104, v103, 16, 1
	v_lshrrev_b32_e32 v102, 16, v102
	v_add3_u32 v103, v103, v104, s70
	v_and_or_b32 v131, v103, s33, v102
	v_ashrrev_i32_e32 v102, 31, v99
	v_mul_lo_u32 v104, s9, v99
	v_mul_lo_u32 v105, s8, v102
	v_mad_u64_u32 v[102:103], s[10:11], s8, v99, 0
	v_add3_u32 v103, v103, v105, v104
	v_lshl_add_u64 v[102:103], v[102:103], 1, s[4:5]
	v_lshl_add_u64 v[102:103], s[6:7], 1, v[102:103]
	v_lshl_add_u64 v[102:103], v[102:103], 0, v[146:147]
	global_store_dwordx4 v[102:103], v[128:131], off sc0 sc1
	ds_read2_b32 v[108:109], v112 offset0:24 offset1:57
	ds_read2_b32 v[106:107], v112 offset0:90 offset1:123
	ds_read2_b32 v[104:105], v112 offset0:156 offset1:189
	ds_read2_b32 v[102:103], v112 offset0:222 offset1:255
	v_or_b32_e32 v128, s15, v111
	s_mov_b64 s[10:11], -1
	s_and_b64 vcc, exec, s[0:1]
	s_cbranch_vccnz .LBB0_1805
	s_lshl_b32 s0, s15, 1
	s_and_b32 s0, s0, 0xffffff00
	v_and_b32_e32 v99, 0x7f, v128
	v_or_b32_e32 v99, s0, v99
	v_or_b32_e32 v99, s16, v99
	s_mov_b64 s[10:11], 0

; #define GAS __attribute__((address_space(1)))
; #define LAS __attribute__((address_space(3)))
; #define LDS_WAIT() asm volatile("s_waitcnt lgkmcnt(0)" ::: "memory")
; __device__ __forceinline__ unsigned pk2(float lo, float hi) { return f2bf(lo) | (f2bf(hi) << 16); }
; __device__ __forceinline__ CvDesc cv_desc(const Frame& F, int it) {
;     bf16* WIN = (bf16*)(F.ws + WS_WIN); bf16* WOUT = (bf16*)(F.ws + WS_WOUT); bf16* WGU = (bf16*)(F.ws + WS_WGU); bf16* WD = (bf16*)(F.ws + WS_WD);
;     int r = it;
;     if (r < CV_N_IN) { const int l = r / CV_I_IN, i = r % CV_I_IN; return CvDesc{F.w_in + (size_t)l * DM * PROJ_W, WIN + (size_t)l * PROJ_W * DM, DM, PROJ_W, 0, 0, 64 * (i / (PROJ_W / 32)), 32 * (i % (PROJ_W / 32))}; } r -= CV_N_IN;
;     if (r < CV_N_OUT) { const int l = r / CV_I_OUT, i = r % CV_I_OUT; return CvDesc{F.w_out + (size_t)l * DM * DM, WOUT + (size_t)l * DM * DM, DM, DM, 0, 0, 64 * (i / (DM / 32)), 32 * (i % (DM / 32))}; } r -= CV_N_OUT;
;     if (r < CV_N_G) { const int le = r / CV_I_GU, i = r % CV_I_GU; return CvDesc{F.w_gate + (size_t)le * DM * EFF, WGU + (size_t)le * 2048 * DM, DM, EFF, 0, 1, 64 * (i / (EFF / 32)), 32 * (i % (EFF / 32))}; } r -= CV_N_G;
;     if (r < CV_N_G) { const int le = r / CV_I_GU, i = r % CV_I_GU; return CvDesc{F.w_up + (size_t)le * DM * EFF, WGU + (size_t)le * 2048 * DM, DM, EFF, 128, 1, 64 * (i / (EFF / 32)), 32 * (i % (EFF / 32))}; } r -= CV_N_G;
;     { const int le = r / CV_I_DN, i = r % CV_I_DN; return CvDesc{F.w_down + (size_t)le * EFF * DM, WD + (size_t)le * DM * EFF, EFF, DM, 0, 0, 64 * (i / (DM / 32)), 32 * (i % (DM / 32))}; }
; __device__ __forceinline__ void cv_finish(const CvDesc& d, const f32x4 (&wv)[8], LAS float* scr, int lane) {
;     ...
;     for (int j = 0; j < 4; ++j) { const int n = (lane >> 3) + 8 * j; const LAS float* s = scr + (8 * cch) * 33 + n;
;         v4u o; o.x = pk2(s[0 * 33], s[1 * 33]); o.y = pk2(s[2 * 33], s[3 * 33]); o.z = pk2(s[4 * 33], s[5 * 33]); o.w = pk2(s[6 * 33], s[7 * 33]);
;         const int nn = d.n0 + n; const int drow = d.mode ? (d.row_off + (nn >> 7) * 256 + (nn & 127)) : (d.row_off + nn);
;         *(GAS v4u*)(d.WT + (size_t)drow * d.K + d.k0 + 8 * cch) = o; }
;     LDS_WAIT(); asm volatile("" ::: "memory");
.LBB0_1807:
	s_waitcnt lgkmcnt(3)
	v_bfe_u32 v128, v109, 16, 1
	v_add3_u32 v109, v109, v128, s70
	v_bfe_u32 v128, v108, 16, 1
	v_add3_u32 v108, v108, v128, s70
	v_lshrrev_b32_e32 v108, 16, v108
	v_and_or_b32 v128, v109, s33, v108
	s_waitcnt lgkmcnt(2)
	v_bfe_u32 v108, v107, 16, 1
	v_add3_u32 v107, v107, v108, s70
	v_bfe_u32 v108, v106, 16, 1
	v_add3_u32 v106, v106, v108, s70
	v_lshrrev_b32_e32 v106, 16, v106
	v_and_or_b32 v129, v107, s33, v106
	s_waitcnt lgkmcnt(1)
	v_bfe_u32 v106, v105, 16, 1
	v_add3_u32 v105, v105, v106, s70
	v_bfe_u32 v106, v104, 16, 1
	v_add3_u32 v104, v104, v106, s70
	v_lshrrev_b32_e32 v104, 16, v104
	v_and_or_b32 v130, v105, s33, v104
	s_waitcnt lgkmcnt(0)
	v_bfe_u32 v104, v103, 16, 1
	v_add3_u32 v103, v103, v104, s70
	v_bfe_u32 v104, v102, 16, 1
	v_add3_u32 v102, v102, v104, s70
	v_lshrrev_b32_e32 v102, 16, v102
	v_and_or_b32 v131, v103, s33, v102
	v_ashrrev_i32_e32 v102, 31, v99
	v_mul_lo_u32 v104, s9, v99
	v_mul_lo_u32 v105, s8, v102
	v_mad_u64_u32 v[102:103], s[0:1], s8, v99, 0
	v_add3_u32 v103, v103, v105, v104
	v_lshl_add_u64 v[102:103], v[102:103], 1, s[4:5]
	v_lshl_add_u64 v[102:103], s[6:7], 1, v[102:103]
	v_lshl_add_u64 v[102:103], v[102:103], 0, v[146:147]
	global_store_dwordx4 v[102:103], v[128:131], off sc0 sc1
	s_waitcnt lgkmcnt(0)
	s_add_i32 s0, s14, -3
	s_cmp_ge_i32 s0, s13
	s_cbranch_scc1 .LBB0_1757
	s_add_i32 s0, s14, -1
	s_cmp_ge_i32 s0, s13
	s_cbranch_scc1 .LBB0_1826
	v_readlane_b32 s0, v253, 62
	s_add_i32 s11, s0, s12
	s_cmpk_lt_i32 s11, 0x1c00
	s_movk_i32 s0, 0x2400
	s_cselect_b32 s0, 0x1c00, s0
	s_add_i32 s5, s11, s0
	s_cmpk_gt_i32 s5, 0x37ff
	s_mov_b64 s[8:9], -1
	s_cbranch_scc0 .LBB0_1823
	s_cmpk_gt_u32 s5, 0x47ff
	s_cbranch_scc0 .LBB0_1820
	s_cmpk_gt_u32 s5, 0xc7ff
	s_cbranch_scc0 .LBB0_1817
	s_lshl_b32 s8, s5, 5
	s_cmp_gt_u32 s5, 0x147ff
	s_mov_b64 s[6:7], -1
	s_cbranch_scc0 .LBB0_1814
	s_add_i32 s0, s5, 0xfffeb800
	s_lshr_b32 s58, s0, 10
	v_readlane_b32 s16, v249, 0
	s_lshl_b64 s[0:1], s[58:59], 23
	v_readlane_b32 s20, v249, 4
	v_readlane_b32 s21, v249, 5
	s_add_u32 s0, s20, s0
	v_readlane_b32 s17, v249, 1
	v_readlane_b32 s18, v249, 2
	v_readlane_b32 s19, v249, 3
	v_readlane_b32 s22, v249, 6
	v_readlane_b32 s23, v249, 7
	s_addc_u32 s1, s21, s1
	s_and_b32 s10, s11, 0x3c0
	s_and_b32 s4, s8, 0x7e0
	s_mov_b64 s[6:7], 0

; #define GAS __attribute__((address_space(1)))
; #define LAS __attribute__((address_space(3)))
; __device__ __forceinline__ unsigned pk2(float lo, float hi) { return f2bf(lo) | (f2bf(hi) << 16); }
; __device__ __forceinline__ void cv_finish(const CvDesc& d, const f32x4 (&wv)[8], LAS float* scr, int lane) {
;     ...
; #pragma unroll
;     for (int j = 0; j < 4; ++j) { const int n = (lane >> 3) + 8 * j; const LAS float* s = scr + (8 * cch) * 33 + n;
;         v4u o; o.x = pk2(s[0 * 33], s[1 * 33]); o.y = pk2(s[2 * 33], s[3 * 33]); o.z = pk2(s[4 * 33], s[5 * 33]); o.w = pk2(s[6 * 33], s[7 * 33]);
;         const int nn = d.n0 + n; const int drow = d.mode ? (d.row_off + (nn >> 7) * 256 + (nn & 127)) : (d.row_off + nn);
;         *(GAS v4u*)(d.WT + (size_t)drow * d.K + d.k0 + 8 * cch) = o; }
.LBB0_1845:
	s_waitcnt lgkmcnt(3)
	v_bfe_u32 v128, v108, 16, 1
	v_add3_u32 v108, v108, v128, s70
	v_bfe_u32 v128, v109, 16, 1
	v_lshrrev_b32_e32 v108, 16, v108
	v_add3_u32 v109, v109, v128, s70
	v_and_or_b32 v128, v109, s33, v108
	s_waitcnt lgkmcnt(2)
	v_bfe_u32 v108, v106, 16, 1
	v_add3_u32 v106, v106, v108, s70
	v_bfe_u32 v108, v107, 16, 1
	v_lshrrev_b32_e32 v106, 16, v106
	v_add3_u32 v107, v107, v108, s70
	v_and_or_b32 v129, v107, s33, v106
	s_waitcnt lgkmcnt(1)
	v_bfe_u32 v106, v104, 16, 1
	v_add3_u32 v104, v104, v106, s70
	v_bfe_u32 v106, v105, 16, 1
	v_lshrrev_b32_e32 v104, 16, v104
	v_add3_u32 v105, v105, v106, s70
	v_and_or_b32 v130, v105, s33, v104
	s_waitcnt lgkmcnt(0)
	v_bfe_u32 v104, v102, 16, 1
	v_add3_u32 v102, v102, v104, s70
	v_bfe_u32 v104, v103, 16, 1
	v_lshrrev_b32_e32 v102, 16, v102
	v_add3_u32 v103, v103, v104, s70
	v_and_or_b32 v131, v103, s33, v102
	v_ashrrev_i32_e32 v102, 31, v99
	v_mul_lo_u32 v104, s9, v99
	v_mul_lo_u32 v105, s8, v102
	v_mad_u64_u32 v[102:103], s[10:11], s8, v99, 0
	v_add3_u32 v103, v103, v105, v104
	v_lshl_add_u64 v[102:103], v[102:103], 1, s[4:5]
	s_ashr_i32 s7, s6, 31
	v_lshl_add_u64 v[102:103], s[6:7], 1, v[102:103]
	v_lshl_add_u64 v[102:103], v[102:103], 0, v[146:147]
	global_store_dwordx4 v[102:103], v[128:131], off sc0 sc1
	ds_read2_b32 v[108:109], v112 offset0:8 offset1:41
	ds_read2_b32 v[106:107], v112 offset0:74 offset1:107
	ds_read2_b32 v[104:105], v112 offset0:140 offset1:173
	ds_read2_b32 v[102:103], v112 offset0:206 offset1:239
	s_xor_b64 s[10:11], s[0:1], -1
	v_cndmask_b32_e64 v99, 0, 1, s[10:11]
	v_or_b32_e32 v128, s15, v101
	v_cmp_ne_u32_e64 s[0:1], 1, v99
	s_andn2_b64 vcc, exec, s[10:11]
	s_mov_b64 s[10:11], -1
	s_cbranch_vccnz .LBB0_1847
	s_lshl_b32 s10, s15, 1
	s_and_b32 s10, s10, 0xffffff00
	v_and_b32_e32 v99, 0x6f, v128
	v_or_b32_e32 v99, s10, v99
	v_or_b32_e32 v99, s16, v99
	s_mov_b64 s[10:11], 0

; #define GAS __attribute__((address_space(1)))
; #define LAS __attribute__((address_space(3)))
; #define LDS_WAIT() asm volatile("s_waitcnt lgkmcnt(0)" ::: "memory")
; __device__ __forceinline__ unsigned pk2(float lo, float hi) { return f2bf(lo) | (f2bf(hi) << 16); }
; __device__ __forceinline__ CvDesc cv_desc(const Frame& F, int it) {
;     bf16* WIN = (bf16*)(F.ws + WS_WIN); bf16* WOUT = (bf16*)(F.ws + WS_WOUT); bf16* WGU = (bf16*)(F.ws + WS_WGU); bf16* WD = (bf16*)(F.ws + WS_WD);
;     int r = it;
;     if (r < CV_N_IN) { const int l = r / CV_I_IN, i = r % CV_I_IN; return CvDesc{F.w_in + (size_t)l * DM * PROJ_W, WIN + (size_t)l * PROJ_W * DM, DM, PROJ_W, 0, 0, 64 * (i / (PROJ_W / 32)), 32 * (i % (PROJ_W / 32))}; } r -= CV_N_IN;
;     if (r < CV_N_OUT) { const int l = r / CV_I_OUT, i = r % CV_I_OUT; return CvDesc{F.w_out + (size_t)l * DM * DM, WOUT + (size_t)l * DM * DM, DM, DM, 0, 0, 64 * (i / (DM / 32)), 32 * (i % (DM / 32))}; } r -= CV_N_OUT;
;     if (r < CV_N_G) { const int le = r / CV_I_GU, i = r % CV_I_GU; return CvDesc{F.w_gate + (size_t)le * DM * EFF, WGU + (size_t)le * 2048 * DM, DM, EFF, 0, 1, 64 * (i / (EFF / 32)), 32 * (i % (EFF / 32))}; } r -= CV_N_G;
;     if (r < CV_N_G) { const int le = r / CV_I_GU, i = r % CV_I_GU; return CvDesc{F.w_up + (size_t)le * DM * EFF, WGU + (size_t)le * 2048 * DM, DM, EFF, 128, 1, 64 * (i / (EFF / 32)), 32 * (i % (EFF / 32))}; } r -= CV_N_G;
;     { const int le = r / CV_I_DN, i = r % CV_I_DN; return CvDesc{F.w_down + (size_t)le * EFF * DM, WD + (size_t)le * DM * EFF, EFF, DM, 0, 0, 64 * (i / (DM / 32)), 32 * (i % (DM / 32))}; }
; __device__ __forceinline__ void cv_finish(const CvDesc& d, const f32x4 (&wv)[8], LAS float* scr, int lane) {
;     ...
;     for (int j = 0; j < 4; ++j) { const int n = (lane >> 3) + 8 * j; const LAS float* s = scr + (8 * cch) * 33 + n;
;         v4u o; o.x = pk2(s[0 * 33], s[1 * 33]); o.y = pk2(s[2 * 33], s[3 * 33]); o.z = pk2(s[4 * 33], s[5 * 33]); o.w = pk2(s[6 * 33], s[7 * 33]);
;         const int nn = d.n0 + n; const int drow = d.mode ? (d.row_off + (nn >> 7) * 256 + (nn & 127)) : (d.row_off + nn);
;         *(GAS v4u*)(d.WT + (size_t)drow * d.K + d.k0 + 8 * cch) = o; }
;     LDS_WAIT(); asm volatile("" ::: "memory");
.LBB0_1857:
	s_waitcnt lgkmcnt(3)
	v_bfe_u32 v128, v109, 16, 1
	v_add3_u32 v109, v109, v128, s70
	v_bfe_u32 v128, v108, 16, 1
	v_add3_u32 v108, v108, v128, s70
	v_lshrrev_b32_e32 v108, 16, v108
	v_and_or_b32 v128, v109, s33, v108
	s_waitcnt lgkmcnt(2)
	v_bfe_u32 v108, v107, 16, 1
	v_add3_u32 v107, v107, v108, s70
	v_bfe_u32 v108, v106, 16, 1
	v_add3_u32 v106, v106, v108, s70
	v_lshrrev_b32_e32 v106, 16, v106
	v_and_or_b32 v129, v107, s33, v106
	s_waitcnt lgkmcnt(1)
	v_bfe_u32 v106, v105, 16, 1
	v_add3_u32 v105, v105, v106, s70
	v_bfe_u32 v106, v104, 16, 1
	v_add3_u32 v104, v104, v106, s70
	v_lshrrev_b32_e32 v104, 16, v104
	v_and_or_b32 v130, v105, s33, v104
	s_waitcnt lgkmcnt(0)
	v_bfe_u32 v104, v103, 16, 1
	v_add3_u32 v103, v103, v104, s70
	v_bfe_u32 v104, v102, 16, 1
	v_add3_u32 v102, v102, v104, s70
	v_lshrrev_b32_e32 v102, 16, v102
	v_and_or_b32 v131, v103, s33, v102
	v_ashrrev_i32_e32 v102, 31, v99
	v_mul_lo_u32 v104, s9, v99
	v_mul_lo_u32 v105, s8, v102
	v_mad_u64_u32 v[102:103], s[0:1], s8, v99, 0
	v_add3_u32 v103, v103, v105, v104
	v_lshl_add_u64 v[102:103], v[102:103], 1, s[4:5]
	v_lshl_add_u64 v[102:103], s[6:7], 1, v[102:103]
	v_lshl_add_u64 v[102:103], v[102:103], 0, v[146:147]
	global_store_dwordx4 v[102:103], v[128:131], off sc0 sc1
	s_waitcnt lgkmcnt(0)
	s_andn2_b64 vcc, exec, s[2:3]
	s_cbranch_vccnz .LBB0_1757
	s_cmp_ge_i32 s14, s13
	s_cbranch_scc1 .LBB0_1876
	v_readlane_b32 s0, v253, 61
	s_add_i32 s9, s0, s12
	s_cmpk_lt_i32 s9, 0x1c00
	s_movk_i32 s0, 0x2400
	s_cselect_b32 s0, 0x1c00, s0
	s_add_i32 s3, s9, s0
	s_cmpk_gt_i32 s3, 0x37ff
	s_mov_b64 s[6:7], -1
	s_cbranch_scc0 .LBB0_1873
	s_cmpk_gt_u32 s3, 0x47ff
	s_cbranch_scc0 .LBB0_1870
	s_cmpk_gt_u32 s3, 0xc7ff
	s_cbranch_scc0 .LBB0_1867
	s_lshl_b32 s6, s3, 5
	s_cmp_gt_u32 s3, 0x147ff
	s_mov_b64 s[4:5], -1
	s_cbranch_scc0 .LBB0_1864
	s_add_i32 s0, s3, 0xfffeb800
	s_lshr_b32 s58, s0, 10
	v_readlane_b32 s16, v249, 0
	s_lshl_b64 s[0:1], s[58:59], 23
	v_readlane_b32 s20, v249, 4
	v_readlane_b32 s21, v249, 5
	s_add_u32 s0, s20, s0
	v_readlane_b32 s17, v249, 1
	v_readlane_b32 s18, v249, 2
	v_readlane_b32 s19, v249, 3
	v_readlane_b32 s22, v249, 6
	v_readlane_b32 s23, v249, 7
	s_addc_u32 s1, s21, s1
	s_and_b32 s8, s9, 0x3c0
	s_and_b32 s2, s6, 0x7e0
	s_mov_b64 s[4:5], 0

; __device__ __forceinline__ unsigned cvt_pk_bf16(float lo, float hi) { unsigned r; asm volatile("v_cvt_pk_bf16_f32 %0, %1, %2" : "=v"(r) : "v"(lo), "v"(hi)); return r; }
; __device__ __forceinline__ float silu_f(float a) { return a * __builtin_amdgcn_rcpf(1.0f + __expf(-a)); }
;     __device__ __forceinline__ void operator()(const f32x4 (&acc)[2][2][4][2], const Unit& u, int wr, int wc, int fr, int fq) const {
;         const int row0 = u.pm * BM + wr * 64 + fr, col0 = (u.pn & 7) * 128 + wc * 32 + 8 * fq;
; #pragma unroll
;         for (int ai = 0; ai < 2; ++ai)
; #pragma unroll
;             for (int m = 0; m < 4; ++m) { bf16_t* rowp = H + (size_t)(row0 + ai * HALF + m * 16) * EFF + col0;
;                 const f32x4 g0 = acc[ai][0][m][0], g1 = acc[ai][0][m][1], u0 = acc[ai][1][m][0], u1 = acc[ai][1][m][1];
;                 f32x4 h0, h1;
; #pragma unroll
;                 for (int j = 0; j < 4; ++j) { h0[j] = silu_f(g0[j]) * u0[j]; h1[j] = silu_f(g1[j]) * u1[j]; }
;                 u32x4 w; w.x = cvt_pk_bf16(h0[0], h0[1]); w.y = cvt_pk_bf16(h0[2], h0[3]); w.z = cvt_pk_bf16(h1[0], h1[1]); w.w = cvt_pk_bf16(h1[2], h1[3]);
;                 *(u32x4*)rowp = w; }
;     }
.LBB0_1983:
	v_lshl_add_u32 v134, s27, 8, v157
	v_ashrrev_i32_e32 v135, 31, v134
	v_lshlrev_b64 v[138:139], 11, v[134:135]
	v_mul_f32_e32 v135, 0xbfb8aa3b, v126
	v_exp_f32_e32 v135, v135
	s_lshl_b32 s0, s30, 7
	s_and_b32 s0, s0, 0x380
	v_or_b32_e32 v136, s0, v137
	v_add_f32_e32 v135, 1.0, v135
	v_rcp_f32_e32 v135, v135
	v_readlane_b32 s0, v252, 30
	v_readlane_b32 s1, v252, 31
	v_lshlrev_b32_e32 v146, 1, v136
	v_mul_f32_e32 v126, v126, v135
	v_mul_f32_e32 v122, v126, v122
	v_mul_f32_e32 v126, 0xbfb8aa3b, v118
	v_exp_f32_e32 v126, v126
	v_lshl_add_u64 v[138:139], s[0:1], 0, v[138:139]
	v_add_f32_e32 v126, 1.0, v126
	v_rcp_f32_e32 v126, v126
	s_nop 0
	v_mul_f32_e32 v118, v118, v126
	v_mul_f32_e32 v118, v118, v114
	v_mul_f32_e32 v114, 0xbfb8aa3b, v127
	v_exp_f32_e32 v114, v114
	s_nop 0
	v_add_f32_e32 v114, 1.0, v114
	v_rcp_f32_e32 v114, v114
	s_nop 0
	v_mul_f32_e32 v114, v127, v114
	v_mul_f32_e32 v123, v114, v123
	v_mul_f32_e32 v114, 0xbfb8aa3b, v119
	v_exp_f32_e32 v114, v114
	s_nop 0
	v_add_f32_e32 v114, 1.0, v114
	v_rcp_f32_e32 v114, v114
	s_nop 0
	v_mul_f32_e32 v114, v119, v114
	v_mul_f32_e32 v119, v114, v115
	v_mul_f32_e32 v114, 0xbfb8aa3b, v128
	v_exp_f32_e32 v114, v114
	s_nop 0
	v_add_f32_e32 v114, 1.0, v114
	v_rcp_f32_e32 v114, v114
	s_nop 0
	v_mul_f32_e32 v114, v128, v114
	v_mul_f32_e32 v124, v114, v124
	v_mul_f32_e32 v114, 0xbfb8aa3b, v120
	v_exp_f32_e32 v114, v114
	s_nop 0
	v_add_f32_e32 v114, 1.0, v114
	v_rcp_f32_e32 v114, v114
	s_nop 0
	v_mul_f32_e32 v114, v120, v114
	v_mul_f32_e32 v120, v114, v116
	v_mul_f32_e32 v114, 0xbfb8aa3b, v129
	v_exp_f32_e32 v114, v114
	v_cvt_pk_bf16_f32 v116, v122, v123
	s_nop 0
	v_add_f32_e32 v114, 1.0, v114
	v_rcp_f32_e32 v114, v114
	s_nop 0
	v_mul_f32_e32 v114, v129, v114
	v_mul_f32_e32 v125, v114, v125
	v_mul_f32_e32 v114, 0xbfb8aa3b, v121
	v_exp_f32_e32 v114, v114
	s_nop 0
	v_add_f32_e32 v114, 1.0, v114
	v_rcp_f32_e32 v114, v114
	s_nop 0
	v_mul_f32_e32 v114, v121, v114
	v_mul_f32_e32 v121, v114, v117
	v_lshl_add_u64 v[114:115], v[138:139], 0, v[146:147]
	v_cvt_pk_bf16_f32 v117, v124, v125
	v_cvt_pk_bf16_f32 v118, v118, v119
	v_cvt_pk_bf16_f32 v119, v120, v121
	global_store_dwordx4 v[114:115], v[116:119], off sc0 sc1
	s_nop 1
	v_mul_f32_e32 v118, 0xbfb8aa3b, v110
	v_exp_f32_e32 v118, v118
	v_or_b32_e32 v116, 16, v134
	v_ashrrev_i32_e32 v117, 31, v116
	v_lshlrev_b64 v[116:117], 11, v[116:117]
	v_add_f32_e32 v118, 1.0, v118
	v_rcp_f32_e32 v118, v118
	v_lshl_add_u64 v[116:117], s[0:1], 0, v[116:117]
	v_mul_f32_e32 v110, v110, v118
	v_mul_f32_e32 v106, v110, v106
	v_mul_f32_e32 v110, 0xbfb8aa3b, v102
	v_exp_f32_e32 v110, v110
	s_nop 0
	v_add_f32_e32 v110, 1.0, v110
	v_rcp_f32_e32 v110, v110
	s_nop 0
	v_mul_f32_e32 v102, v102, v110
	v_mul_f32_e32 v110, v102, v98
	v_mul_f32_e32 v98, 0xbfb8aa3b, v111
	v_mul_f32_e32 v102, 0xbfb8aa3b, v103
	v_exp_f32_e32 v98, v98
	v_exp_f32_e32 v102, v102
	v_add_f32_e32 v98, 1.0, v98
	v_add_f32_e32 v102, 1.0, v102
	v_rcp_f32_e32 v98, v98
	v_rcp_f32_e32 v102, v102
	v_mul_f32_e32 v98, v111, v98
	v_mul_f32_e32 v102, v103, v102
	v_mul_f32_e32 v98, v98, v107
	v_mul_f32_e32 v107, v102, v99
	v_mul_f32_e32 v102, 0xbfb8aa3b, v104
	v_exp_f32_e32 v102, v102
	v_mul_f32_e32 v99, 0xbfb8aa3b, v112
	v_exp_f32_e32 v99, v99
	v_cvt_pk_bf16_f32 v98, v106, v98
	v_add_f32_e32 v102, 1.0, v102
	v_rcp_f32_e32 v102, v102
	v_add_f32_e32 v99, 1.0, v99
	v_rcp_f32_e32 v99, v99
	v_mul_f32_e32 v102, v104, v102
	v_mul_f32_e32 v104, v102, v100
	v_mul_f32_e32 v100, 0xbfb8aa3b, v113
	v_exp_f32_e32 v100, v100
	v_mul_f32_e32 v102, 0xbfb8aa3b, v105
	v_exp_f32_e32 v102, v102
	v_mul_f32_e32 v99, v112, v99
	v_add_f32_e32 v100, 1.0, v100
	v_rcp_f32_e32 v100, v100
	v_add_f32_e32 v102, 1.0, v102
	v_rcp_f32_e32 v102, v102
	v_mul_f32_e32 v99, v99, v108
	v_mul_f32_e32 v100, v113, v100
	v_mul_f32_e32 v100, v100, v109
	v_mul_f32_e32 v102, v105, v102
	v_mul_f32_e32 v101, v102, v101
	v_lshl_add_u64 v[102:103], v[116:117], 0, v[146:147]
	v_cvt_pk_bf16_f32 v99, v99, v100
	v_cvt_pk_bf16_f32 v100, v110, v107
	v_cvt_pk_bf16_f32 v101, v104, v101
	global_store_dwordx4 v[102:103], v[98:101], off sc0 sc1
	s_nop 1
	v_mul_f32_e32 v100, 0xbfb8aa3b, v94
	v_exp_f32_e32 v100, v100
	v_or_b32_e32 v98, 32, v134
	v_ashrrev_i32_e32 v99, 31, v98
	v_lshlrev_b64 v[98:99], 11, v[98:99]
	v_add_f32_e32 v100, 1.0, v100
	v_rcp_f32_e32 v100, v100
	v_lshl_add_u64 v[98:99], s[0:1], 0, v[98:99]
	v_mul_f32_e32 v94, v94, v100
	v_mul_f32_e32 v90, v94, v90
	v_mul_f32_e32 v94, 0xbfb8aa3b, v86
	v_exp_f32_e32 v94, v94
	s_nop 0
	v_add_f32_e32 v94, 1.0, v94
	v_rcp_f32_e32 v94, v94
	s_nop 0
	v_mul_f32_e32 v86, v86, v94
	v_mul_f32_e32 v94, v86, v82
	v_mul_f32_e32 v82, 0xbfb8aa3b, v95
	v_mul_f32_e32 v86, 0xbfb8aa3b, v87
	v_exp_f32_e32 v82, v82
	v_exp_f32_e32 v86, v86
	v_add_f32_e32 v82, 1.0, v82
	v_add_f32_e32 v86, 1.0, v86
	v_rcp_f32_e32 v82, v82
	v_rcp_f32_e32 v86, v86
	v_mul_f32_e32 v82, v95, v82
	v_mul_f32_e32 v86, v87, v86
	v_mul_f32_e32 v82, v82, v91
	v_mul_f32_e32 v91, v86, v83
	v_mul_f32_e32 v86, 0xbfb8aa3b, v88
	v_exp_f32_e32 v86, v86
	v_mul_f32_e32 v83, 0xbfb8aa3b, v96
	v_exp_f32_e32 v83, v83
	v_cvt_pk_bf16_f32 v82, v90, v82
	v_add_f32_e32 v86, 1.0, v86
	v_rcp_f32_e32 v86, v86
	v_add_f32_e32 v83, 1.0, v83
	v_rcp_f32_e32 v83, v83
	v_mul_f32_e32 v86, v88, v86
	v_mul_f32_e32 v88, v86, v84
	v_mul_f32_e32 v84, 0xbfb8aa3b, v97
	v_exp_f32_e32 v84, v84
	v_mul_f32_e32 v86, 0xbfb8aa3b, v89
	v_exp_f32_e32 v86, v86
	v_mul_f32_e32 v83, v96, v83
	v_add_f32_e32 v84, 1.0, v84
	v_rcp_f32_e32 v84, v84
	v_add_f32_e32 v86, 1.0, v86
	v_rcp_f32_e32 v86, v86
	v_mul_f32_e32 v83, v83, v92
	v_mul_f32_e32 v84, v97, v84
	v_mul_f32_e32 v84, v84, v93
	v_mul_f32_e32 v86, v89, v86
; __device__ __forceinline__ unsigned cvt_pk_bf16(float lo, float hi) { unsigned r; asm volatile("v_cvt_pk_bf16_f32 %0, %1, %2" : "=v"(r) : "v"(lo), "v"(hi)); return r; }
; __device__ __forceinline__ float silu_f(float a) { return a * __builtin_amdgcn_rcpf(1.0f + __expf(-a)); }
;     __device__ __forceinline__ void operator()(const f32x4 (&acc)[2][2][4][2], const Unit& u, int wr, int wc, int fr, int fq) const {
;         const int row0 = u.pm * BM + wr * 64 + fr, col0 = (u.pn & 7) * 128 + wc * 32 + 8 * fq;
; #pragma unroll
;         for (int ai = 0; ai < 2; ++ai)
; #pragma unroll
;             for (int m = 0; m < 4; ++m) { bf16_t* rowp = H + (size_t)(row0 + ai * HALF + m * 16) * EFF + col0;
;                 const f32x4 g0 = acc[ai][0][m][0], g1 = acc[ai][0][m][1], u0 = acc[ai][1][m][0], u1 = acc[ai][1][m][1];
;                 f32x4 h0, h1;
; #pragma unroll
;                 for (int j = 0; j < 4; ++j) { h0[j] = silu_f(g0[j]) * u0[j]; h1[j] = silu_f(g1[j]) * u1[j]; }
;                 u32x4 w; w.x = cvt_pk_bf16(h0[0], h0[1]); w.y = cvt_pk_bf16(h0[2], h0[3]); w.z = cvt_pk_bf16(h1[0], h1[1]); w.w = cvt_pk_bf16(h1[2], h1[3]);
;                 *(u32x4*)rowp = w; }
;     }
	v_mul_f32_e32 v85, v86, v85
	v_lshl_add_u64 v[86:87], v[98:99], 0, v[146:147]
	v_cvt_pk_bf16_f32 v83, v83, v84
	v_cvt_pk_bf16_f32 v84, v94, v91
	v_cvt_pk_bf16_f32 v85, v88, v85
	global_store_dwordx4 v[86:87], v[82:85], off sc0 sc1
	s_nop 1
	v_mul_f32_e32 v84, 0xbfb8aa3b, v78
	v_exp_f32_e32 v84, v84
	v_or_b32_e32 v82, 48, v134
	v_ashrrev_i32_e32 v83, 31, v82
	v_lshlrev_b64 v[82:83], 11, v[82:83]
	v_add_f32_e32 v84, 1.0, v84
	v_rcp_f32_e32 v84, v84
	v_lshl_add_u64 v[82:83], s[0:1], 0, v[82:83]
	s_mov_b32 s0, 0x40000
	v_mul_f32_e32 v78, v78, v84
	v_mul_f32_e32 v74, v78, v74
	v_mul_f32_e32 v78, 0xbfb8aa3b, v70
	v_exp_f32_e32 v78, v78
	s_nop 0
	v_add_f32_e32 v78, 1.0, v78
	v_rcp_f32_e32 v78, v78
	s_nop 0
	v_mul_f32_e32 v70, v70, v78
	v_mul_f32_e32 v78, v70, v66
	v_mul_f32_e32 v66, 0xbfb8aa3b, v79
	v_mul_f32_e32 v70, 0xbfb8aa3b, v71
	v_exp_f32_e32 v66, v66
	v_exp_f32_e32 v70, v70
	v_add_f32_e32 v66, 1.0, v66
	v_add_f32_e32 v70, 1.0, v70
	v_rcp_f32_e32 v66, v66
	v_rcp_f32_e32 v70, v70
	v_mul_f32_e32 v66, v79, v66
	v_mul_f32_e32 v70, v71, v70
	v_mul_f32_e32 v66, v66, v75
	v_mul_f32_e32 v75, v70, v67
	v_mul_f32_e32 v70, 0xbfb8aa3b, v72
	v_exp_f32_e32 v70, v70
	v_mul_f32_e32 v67, 0xbfb8aa3b, v80
	v_exp_f32_e32 v67, v67
	v_cvt_pk_bf16_f32 v66, v74, v66
	v_add_f32_e32 v70, 1.0, v70
	v_rcp_f32_e32 v70, v70
	v_add_f32_e32 v67, 1.0, v67
	v_rcp_f32_e32 v67, v67
	v_mul_f32_e32 v70, v72, v70
	v_mul_f32_e32 v72, v70, v68
	v_mul_f32_e32 v68, 0xbfb8aa3b, v81
	v_mul_f32_e32 v70, 0xbfb8aa3b, v73
	v_exp_f32_e32 v68, v68
	v_exp_f32_e32 v70, v70
	v_mul_f32_e32 v67, v80, v67
	v_mul_f32_e32 v67, v67, v76
	v_add_f32_e32 v68, 1.0, v68
	v_add_f32_e32 v70, 1.0, v70
	v_rcp_f32_e32 v68, v68
	v_rcp_f32_e32 v70, v70
	v_mul_f32_e32 v68, v81, v68
	v_mul_f32_e32 v70, v73, v70
	v_mul_f32_e32 v68, v68, v77
	v_mul_f32_e32 v69, v70, v69
	v_lshl_add_u64 v[70:71], v[82:83], 0, v[146:147]
	v_cvt_pk_bf16_f32 v67, v67, v68
	v_cvt_pk_bf16_f32 v68, v78, v75
	v_cvt_pk_bf16_f32 v69, v72, v69
	global_store_dwordx4 v[70:71], v[66:69], off sc0 sc1
	s_nop 1
	v_mul_f32_e32 v66, 0xbfb8aa3b, v62
	v_exp_f32_e32 v66, v66
	s_nop 0
	v_add_f32_e32 v66, 1.0, v66
	v_rcp_f32_e32 v66, v66
	s_nop 0
	v_mul_f32_e32 v62, v62, v66
	v_mul_f32_e32 v58, v62, v58
	v_mul_f32_e32 v62, 0xbfb8aa3b, v54
	v_exp_f32_e32 v62, v62
	s_nop 0
	v_add_f32_e32 v62, 1.0, v62
	v_rcp_f32_e32 v62, v62
	s_nop 0
	v_mul_f32_e32 v54, v54, v62
	v_mul_f32_e32 v54, v54, v50
	v_mul_f32_e32 v50, 0xbfb8aa3b, v63
	v_exp_f32_e32 v50, v50
	s_nop 0
	v_add_f32_e32 v50, 1.0, v50
	v_rcp_f32_e32 v50, v50
	s_nop 0
	v_mul_f32_e32 v50, v63, v50
	v_mul_f32_e32 v50, v50, v59
	v_mul_f32_e32 v59, 0xbfb8aa3b, v55
	v_exp_f32_e32 v59, v59
	v_cvt_pk_bf16_f32 v50, v58, v50
	s_nop 0
	v_add_f32_e32 v59, 1.0, v59
	v_rcp_f32_e32 v59, v59
	s_nop 0
	v_mul_f32_e32 v55, v55, v59
	v_mul_f32_e32 v59, 0xbfb8aa3b, v56
	v_exp_f32_e32 v59, v59
	v_mul_f32_e32 v55, v55, v51
	v_mul_f32_e32 v51, 0xbfb8aa3b, v64
	v_exp_f32_e32 v51, v51
	v_add_f32_e32 v59, 1.0, v59
	v_rcp_f32_e32 v59, v59
	v_add_f32_e32 v51, 1.0, v51
	v_rcp_f32_e32 v51, v51
	v_mul_f32_e32 v56, v56, v59
	v_mul_f32_e32 v56, v56, v52
	v_mul_f32_e32 v52, 0xbfb8aa3b, v65
	v_exp_f32_e32 v52, v52
	v_mul_f32_e32 v59, 0xbfb8aa3b, v57
	v_exp_f32_e32 v59, v59
	v_mul_f32_e32 v51, v64, v51
	v_add_f32_e32 v52, 1.0, v52
	v_rcp_f32_e32 v52, v52
	v_add_f32_e32 v59, 1.0, v59
	v_rcp_f32_e32 v59, v59
	v_mul_f32_e32 v51, v51, v60
	v_mul_f32_e32 v52, v65, v52
	v_mul_f32_e32 v52, v52, v61
	v_mul_f32_e32 v57, v57, v59
	v_cvt_pk_bf16_f32 v51, v51, v52
	v_cvt_pk_bf16_f32 v52, v54, v55
	v_add_co_u32_e32 v54, vcc, s0, v114
	v_mul_f32_e32 v53, v57, v53
	s_nop 0
	v_addc_co_u32_e32 v55, vcc, 0, v115, vcc
	v_cvt_pk_bf16_f32 v53, v56, v53
	global_store_dwordx4 v[54:55], v[50:53], off sc0 sc1
	s_mov_b32 s0, 0x48000
	s_nop 0
	v_mul_f32_e32 v50, 0xbfb8aa3b, v46
	v_exp_f32_e32 v50, v50
	s_nop 0
	v_add_f32_e32 v50, 1.0, v50
	v_rcp_f32_e32 v50, v50
	s_nop 0
	v_mul_f32_e32 v46, v46, v50
	v_mul_f32_e32 v42, v46, v42
	v_mul_f32_e32 v46, 0xbfb8aa3b, v38
	v_exp_f32_e32 v46, v46
	s_nop 0
	v_add_f32_e32 v46, 1.0, v46
	v_rcp_f32_e32 v46, v46
	s_nop 0
	v_mul_f32_e32 v38, v38, v46
	v_mul_f32_e32 v38, v38, v34
	v_mul_f32_e32 v34, 0xbfb8aa3b, v47
	v_exp_f32_e32 v34, v34
	s_nop 0
	v_add_f32_e32 v34, 1.0, v34
	v_rcp_f32_e32 v34, v34
	s_nop 0
	v_mul_f32_e32 v34, v47, v34
	v_mul_f32_e32 v34, v34, v43
	v_mul_f32_e32 v43, 0xbfb8aa3b, v39
	v_exp_f32_e32 v43, v43
	v_cvt_pk_bf16_f32 v34, v42, v34
	s_nop 0
	v_add_f32_e32 v43, 1.0, v43
	v_rcp_f32_e32 v43, v43
	s_nop 0
	v_mul_f32_e32 v39, v39, v43
; __device__ __forceinline__ unsigned cvt_pk_bf16(float lo, float hi) { unsigned r; asm volatile("v_cvt_pk_bf16_f32 %0, %1, %2" : "=v"(r) : "v"(lo), "v"(hi)); return r; }
; __device__ __forceinline__ float silu_f(float a) { return a * __builtin_amdgcn_rcpf(1.0f + __expf(-a)); }
;     __device__ __forceinline__ void operator()(const f32x4 (&acc)[2][2][4][2], const Unit& u, int wr, int wc, int fr, int fq) const {
;         const int row0 = u.pm * BM + wr * 64 + fr, col0 = (u.pn & 7) * 128 + wc * 32 + 8 * fq;
; #pragma unroll
;         for (int ai = 0; ai < 2; ++ai)
; #pragma unroll
;             for (int m = 0; m < 4; ++m) { bf16_t* rowp = H + (size_t)(row0 + ai * HALF + m * 16) * EFF + col0;
;                 const f32x4 g0 = acc[ai][0][m][0], g1 = acc[ai][0][m][1], u0 = acc[ai][1][m][0], u1 = acc[ai][1][m][1];
;                 f32x4 h0, h1;
; #pragma unroll
;                 for (int j = 0; j < 4; ++j) { h0[j] = silu_f(g0[j]) * u0[j]; h1[j] = silu_f(g1[j]) * u1[j]; }
;                 u32x4 w; w.x = cvt_pk_bf16(h0[0], h0[1]); w.y = cvt_pk_bf16(h0[2], h0[3]); w.z = cvt_pk_bf16(h1[0], h1[1]); w.w = cvt_pk_bf16(h1[2], h1[3]);
;                 *(u32x4*)rowp = w; }
;     }
	v_mul_f32_e32 v43, 0xbfb8aa3b, v40
	v_exp_f32_e32 v43, v43
	v_mul_f32_e32 v39, v39, v35
	v_mul_f32_e32 v35, 0xbfb8aa3b, v48
	v_exp_f32_e32 v35, v35
	v_add_f32_e32 v43, 1.0, v43
	v_rcp_f32_e32 v43, v43
	v_add_f32_e32 v35, 1.0, v35
	v_rcp_f32_e32 v35, v35
	v_mul_f32_e32 v40, v40, v43
	v_mul_f32_e32 v40, v40, v36
	v_mul_f32_e32 v36, 0xbfb8aa3b, v49
	v_exp_f32_e32 v36, v36
	v_mul_f32_e32 v43, 0xbfb8aa3b, v41
	v_exp_f32_e32 v43, v43
	v_mul_f32_e32 v35, v48, v35
	v_add_f32_e32 v36, 1.0, v36
	v_rcp_f32_e32 v36, v36
	v_add_f32_e32 v43, 1.0, v43
	v_rcp_f32_e32 v43, v43
	v_mul_f32_e32 v35, v35, v44
	v_mul_f32_e32 v36, v49, v36
	v_mul_f32_e32 v36, v36, v45
	v_mul_f32_e32 v41, v41, v43
	v_cvt_pk_bf16_f32 v35, v35, v36
	v_cvt_pk_bf16_f32 v36, v38, v39
	v_add_co_u32_e32 v38, vcc, s0, v114
	v_mul_f32_e32 v37, v41, v37
	s_nop 0
	v_addc_co_u32_e32 v39, vcc, 0, v115, vcc
	v_cvt_pk_bf16_f32 v37, v40, v37
	global_store_dwordx4 v[38:39], v[34:37], off sc0 sc1
	s_mov_b32 s0, 0x50000
	s_nop 0
	v_mul_f32_e32 v34, 0xbfb8aa3b, v30
	v_exp_f32_e32 v34, v34
	s_nop 0
	v_add_f32_e32 v34, 1.0, v34
	v_rcp_f32_e32 v34, v34
	s_nop 0
	v_mul_f32_e32 v30, v30, v34
	v_mul_f32_e32 v26, v30, v26
	v_mul_f32_e32 v30, 0xbfb8aa3b, v22
	v_exp_f32_e32 v30, v30
	s_nop 0
	v_add_f32_e32 v30, 1.0, v30
	v_rcp_f32_e32 v30, v30
	s_nop 0
	v_mul_f32_e32 v22, v22, v30
	v_mul_f32_e32 v22, v22, v18
	v_mul_f32_e32 v18, 0xbfb8aa3b, v31
	v_exp_f32_e32 v18, v18
	s_nop 0
	v_add_f32_e32 v18, 1.0, v18
	v_rcp_f32_e32 v18, v18
	s_nop 0
	v_mul_f32_e32 v18, v31, v18
	v_mul_f32_e32 v18, v18, v27
	v_mul_f32_e32 v27, 0xbfb8aa3b, v23
	v_exp_f32_e32 v27, v27
	v_cvt_pk_bf16_f32 v18, v26, v18
	s_nop 0
	v_add_f32_e32 v27, 1.0, v27
	v_rcp_f32_e32 v27, v27
	s_nop 0
	v_mul_f32_e32 v23, v23, v27
	v_mul_f32_e32 v27, 0xbfb8aa3b, v24
	v_exp_f32_e32 v27, v27
	v_mul_f32_e32 v23, v23, v19
	v_mul_f32_e32 v19, 0xbfb8aa3b, v32
	v_exp_f32_e32 v19, v19
	v_add_f32_e32 v27, 1.0, v27
	v_rcp_f32_e32 v27, v27
	v_add_f32_e32 v19, 1.0, v19
	v_rcp_f32_e32 v19, v19
	v_mul_f32_e32 v24, v24, v27
	v_mul_f32_e32 v24, v24, v20
	v_mul_f32_e32 v20, 0xbfb8aa3b, v33
	v_exp_f32_e32 v20, v20
	v_mul_f32_e32 v27, 0xbfb8aa3b, v25
	v_exp_f32_e32 v27, v27
	v_mul_f32_e32 v19, v32, v19
	v_add_f32_e32 v20, 1.0, v20
	v_rcp_f32_e32 v20, v20
	v_add_f32_e32 v27, 1.0, v27
	v_rcp_f32_e32 v27, v27
	v_mul_f32_e32 v19, v19, v28
	v_mul_f32_e32 v20, v33, v20
	v_mul_f32_e32 v20, v20, v29
	v_mul_f32_e32 v25, v25, v27
	v_cvt_pk_bf16_f32 v19, v19, v20
	v_cvt_pk_bf16_f32 v20, v22, v23
	v_add_co_u32_e32 v22, vcc, s0, v114
	v_mul_f32_e32 v21, v25, v21
	s_nop 0
	v_addc_co_u32_e32 v23, vcc, 0, v115, vcc
	v_cvt_pk_bf16_f32 v21, v24, v21
	global_store_dwordx4 v[22:23], v[18:21], off sc0 sc1
	s_mov_b64 s[0:1], -1
	s_nop 0
	v_mul_f32_e32 v18, 0xbfb8aa3b, v14
	v_exp_f32_e32 v18, v18
	s_nop 0
	v_add_f32_e32 v18, 1.0, v18
	v_rcp_f32_e32 v18, v18
	s_nop 0
	v_mul_f32_e32 v14, v14, v18
	v_mul_f32_e32 v10, v14, v10
	v_mul_f32_e32 v14, 0xbfb8aa3b, v6
	v_exp_f32_e32 v14, v14
	s_nop 0
	v_add_f32_e32 v14, 1.0, v14
	v_rcp_f32_e32 v14, v14
	s_nop 0
	v_mul_f32_e32 v6, v6, v14
	v_mul_f32_e32 v6, v6, v2
	v_mul_f32_e32 v2, 0xbfb8aa3b, v15
	v_exp_f32_e32 v2, v2
	s_nop 0
	v_add_f32_e32 v2, 1.0, v2
	v_rcp_f32_e32 v2, v2
	s_nop 0
	v_mul_f32_e32 v2, v15, v2
	v_mul_f32_e32 v2, v2, v11
	v_mul_f32_e32 v11, 0xbfb8aa3b, v7
	v_exp_f32_e32 v11, v11
	v_cvt_pk_bf16_f32 v2, v10, v2
	s_nop 0
	v_add_f32_e32 v11, 1.0, v11
	v_rcp_f32_e32 v11, v11
	s_nop 0
	v_mul_f32_e32 v7, v7, v11
	v_mul_f32_e32 v11, 0xbfb8aa3b, v8
	v_exp_f32_e32 v11, v11
	v_mul_f32_e32 v7, v7, v3
	v_mul_f32_e32 v3, 0xbfb8aa3b, v16
	v_exp_f32_e32 v3, v3
	v_add_f32_e32 v11, 1.0, v11
	v_rcp_f32_e32 v11, v11
	v_add_f32_e32 v3, 1.0, v3
	v_rcp_f32_e32 v3, v3
	v_mul_f32_e32 v8, v8, v11
	v_mul_f32_e32 v8, v8, v4
	v_mul_f32_e32 v4, 0xbfb8aa3b, v17
	v_exp_f32_e32 v4, v4
	v_mul_f32_e32 v11, 0xbfb8aa3b, v9
	v_exp_f32_e32 v11, v11
	v_mul_f32_e32 v3, v16, v3
	v_add_f32_e32 v4, 1.0, v4
	v_rcp_f32_e32 v4, v4
	v_add_f32_e32 v11, 1.0, v11
	v_rcp_f32_e32 v11, v11
	v_mul_f32_e32 v3, v3, v12
	v_mul_f32_e32 v4, v17, v4
	v_mul_f32_e32 v4, v4, v13
	v_cvt_pk_bf16_f32 v3, v3, v4
	v_cvt_pk_bf16_f32 v4, v6, v7
	v_add_co_u32_e32 v6, vcc, 0x58000, v114
	v_mul_f32_e32 v9, v9, v11
	s_nop 0
	v_addc_co_u32_e32 v7, vcc, 0, v115, vcc
	v_mul_f32_e32 v5, v9, v5
	s_and_b64 vcc, exec, s[40:41]
	v_cvt_pk_bf16_f32 v5, v8, v5
	global_store_dwordx4 v[6:7], v[2:5], off sc0 sc1
	s_cbranch_vccnz .LBB0_1968
	s_andn2_b64 vcc, exec, s[2:3]
	s_cbranch_vccnz .LBB0_1967
	s_barrier
	s_branch .LBB0_1967

; __device__ __forceinline__ unsigned cvt_pk_bf16(float lo, float hi) { unsigned r; asm volatile("v_cvt_pk_bf16_f32 %0, %1, %2" : "=v"(r) : "v"(lo), "v"(hi)); return r; }
;     __device__ __forceinline__ void operator()(const f32x4 (&acc)[2][2][4][2], const Unit& u, int wr, int wc, int fr, int fq) const {
;         const int row0 = u.pm * BM + wr * 64 + fr, col0 = (u.pn & 7) * BM + wc * 32 + 8 * fq;
; #pragma unroll
;         for (int ai = 0; ai < 2; ++ai)
; #pragma unroll
;             for (int m = 0; m < 4; ++m) { bf16_t* rowp = Y + (size_t)(row0 + ai * HALF + m * 16) * DM + col0;
; #pragma unroll
;                 for (int bj = 0; bj < 2; ++bj) { const f32x4 v0 = acc[ai][bj][m][0], v1 = acc[ai][bj][m][1];
;                     u32x4 w; w.x = cvt_pk_bf16(v0[0], v0[1]); w.y = cvt_pk_bf16(v0[2], v0[3]); w.z = cvt_pk_bf16(v1[0], v1[1]); w.w = cvt_pk_bf16(v1[2], v1[3]);
;                     *(u32x4*)(rowp + bj * HALF) = w; } }
;     }
.LBB0_2252:
	v_lshl_add_u32 v148, s41, 8, v1
	s_lshl_b32 s7, s40, 8
	s_and_b32 s7, s7, 0x700
	v_ashrrev_i32_e32 v149, 31, v148
	v_readlane_b32 s14, v251, 63
	v_or_b32_e32 v146, s7, v145
	v_lshlrev_b64 v[142:143], 12, v[148:149]
	v_readlane_b32 s15, v252, 0
	v_lshlrev_b32_e32 v146, 1, v146
	v_cvt_pk_bf16_f32 v126, v126, v127
	v_cvt_pk_bf16_f32 v127, v128, v129
	v_cvt_pk_bf16_f32 v128, v122, v123
	v_cvt_pk_bf16_f32 v129, v124, v125
	s_nop 0
	v_lshl_add_u64 v[142:143], s[14:15], 0, v[142:143]
	v_lshl_add_u64 v[142:143], v[142:143], 0, v[146:147]
	global_store_dwordx4 v[142:143], v[126:129], off sc0 sc1
	v_cvt_pk_bf16_f32 v114, v114, v115
	v_cvt_pk_bf16_f32 v115, v116, v117
	v_cvt_pk_bf16_f32 v116, v106, v107
	v_or_b32_e32 v106, 16, v148
	v_ashrrev_i32_e32 v107, 31, v106
	v_lshlrev_b64 v[106:107], 12, v[106:107]
	v_lshl_add_u64 v[106:107], s[14:15], 0, v[106:107]
	v_cvt_pk_bf16_f32 v117, v108, v109
	global_store_dwordx4 v[142:143], v[114:117], off offset:256 sc0 sc1
	s_mov_b32 s7, 0x80000
	s_nop 0
	v_lshl_add_u64 v[114:115], v[106:107], 0, v[146:147]
	v_cvt_pk_bf16_f32 v106, v118, v119
	v_cvt_pk_bf16_f32 v107, v120, v121
	v_cvt_pk_bf16_f32 v108, v110, v111
	v_cvt_pk_bf16_f32 v109, v112, v113
	global_store_dwordx4 v[114:115], v[106:109], off sc0 sc1
	v_cvt_pk_bf16_f32 v98, v98, v99
	v_cvt_pk_bf16_f32 v99, v100, v101
	v_cvt_pk_bf16_f32 v100, v90, v91
	v_or_b32_e32 v90, 32, v148
	v_ashrrev_i32_e32 v91, 31, v90
	v_lshlrev_b64 v[90:91], 12, v[90:91]
	v_lshl_add_u64 v[90:91], s[14:15], 0, v[90:91]
	v_cvt_pk_bf16_f32 v101, v92, v93
	global_store_dwordx4 v[114:115], v[98:101], off offset:256 sc0 sc1
	s_nop 1
	v_lshl_add_u64 v[98:99], v[90:91], 0, v[146:147]
	v_cvt_pk_bf16_f32 v90, v102, v103
	v_cvt_pk_bf16_f32 v91, v104, v105
	v_cvt_pk_bf16_f32 v92, v94, v95
	v_cvt_pk_bf16_f32 v93, v96, v97
	global_store_dwordx4 v[98:99], v[90:93], off sc0 sc1
	v_cvt_pk_bf16_f32 v86, v86, v87
	v_cvt_pk_bf16_f32 v87, v88, v89
	v_cvt_pk_bf16_f32 v88, v78, v79
	v_or_b32_e32 v78, 48, v148
	v_ashrrev_i32_e32 v79, 31, v78
	v_lshlrev_b64 v[78:79], 12, v[78:79]
	v_lshl_add_u64 v[78:79], s[14:15], 0, v[78:79]
	v_cvt_pk_bf16_f32 v89, v80, v81
	global_store_dwordx4 v[98:99], v[86:89], off offset:256 sc0 sc1
	s_mov_b64 s[14:15], 0x80000
	s_nop 0
	v_lshl_add_u64 v[86:87], v[78:79], 0, v[146:147]
	v_cvt_pk_bf16_f32 v78, v82, v83
	v_cvt_pk_bf16_f32 v79, v84, v85
	v_cvt_pk_bf16_f32 v80, v74, v75
	v_cvt_pk_bf16_f32 v81, v76, v77
	global_store_dwordx4 v[86:87], v[78:81], off sc0 sc1
	v_cvt_pk_bf16_f32 v70, v70, v71
	v_cvt_pk_bf16_f32 v71, v72, v73
	v_cvt_pk_bf16_f32 v72, v66, v67
	v_cvt_pk_bf16_f32 v73, v68, v69
	global_store_dwordx4 v[86:87], v[70:73], off offset:256 sc0 sc1
	v_cvt_pk_bf16_f32 v62, v62, v63
	v_cvt_pk_bf16_f32 v63, v64, v65
	v_cvt_pk_bf16_f32 v64, v58, v59
	v_add_co_u32_e32 v58, vcc, s7, v142
	v_lshl_add_u64 v[66:67], v[142:143], 0, s[14:15]
	s_nop 0
	v_addc_co_u32_e32 v59, vcc, 0, v143, vcc
	s_mov_b32 s7, 0x90000
	v_cvt_pk_bf16_f32 v65, v60, v61
	global_store_dwordx4 v[58:59], v[62:65], off sc0 sc1
	v_cvt_pk_bf16_f32 v50, v50, v51
	v_cvt_pk_bf16_f32 v51, v52, v53
	v_cvt_pk_bf16_f32 v52, v42, v43
	v_cvt_pk_bf16_f32 v53, v44, v45
	global_store_dwordx4 v[66:67], v[50:53], off offset:256 sc0 sc1
	s_mov_b64 s[14:15], 0x90000
	v_cvt_pk_bf16_f32 v42, v54, v55
	v_cvt_pk_bf16_f32 v43, v56, v57
	v_cvt_pk_bf16_f32 v44, v46, v47
	v_add_co_u32_e32 v46, vcc, s7, v142
	v_lshl_add_u64 v[50:51], v[142:143], 0, s[14:15]
	s_nop 0
	v_addc_co_u32_e32 v47, vcc, 0, v143, vcc
	s_mov_b32 s7, 0xa0000
	v_cvt_pk_bf16_f32 v45, v48, v49
	global_store_dwordx4 v[46:47], v[42:45], off sc0 sc1
	v_cvt_pk_bf16_f32 v34, v34, v35
	v_cvt_pk_bf16_f32 v35, v36, v37
	v_cvt_pk_bf16_f32 v36, v26, v27
	v_cvt_pk_bf16_f32 v37, v28, v29
	global_store_dwordx4 v[50:51], v[34:37], off offset:256 sc0 sc1
	s_mov_b64 s[14:15], 0xa0000
	v_cvt_pk_bf16_f32 v26, v38, v39
	v_cvt_pk_bf16_f32 v27, v40, v41
	v_cvt_pk_bf16_f32 v28, v30, v31
	v_add_co_u32_e32 v30, vcc, s7, v142
	v_lshl_add_u64 v[34:35], v[142:143], 0, s[14:15]
	s_nop 0
	v_addc_co_u32_e32 v31, vcc, 0, v143, vcc
	s_mov_b32 s7, 0xb0000
	v_cvt_pk_bf16_f32 v29, v32, v33
	global_store_dwordx4 v[30:31], v[26:29], off sc0 sc1
	v_cvt_pk_bf16_f32 v18, v18, v19
	v_cvt_pk_bf16_f32 v19, v20, v21
	v_cvt_pk_bf16_f32 v20, v10, v11
	v_cvt_pk_bf16_f32 v21, v12, v13
	global_store_dwordx4 v[34:35], v[18:21], off offset:256 sc0 sc1
	v_cvt_pk_bf16_f32 v10, v22, v23
	v_cvt_pk_bf16_f32 v11, v24, v25
	v_cvt_pk_bf16_f32 v12, v14, v15
	v_add_co_u32_e32 v14, vcc, s7, v142
	s_mov_b64 s[14:15], 0xb0000
	s_nop 0
	v_addc_co_u32_e32 v15, vcc, 0, v143, vcc
	v_lshl_add_u64 v[18:19], v[142:143], 0, s[14:15]
	s_andn2_b64 vcc, exec, s[0:1]
	s_mov_b64 s[0:1], -1
	v_cvt_pk_bf16_f32 v13, v16, v17
	global_store_dwordx4 v[14:15], v[10:13], off sc0 sc1
	v_cvt_pk_bf16_f32 v6, v6, v7
	v_cvt_pk_bf16_f32 v7, v8, v9
	v_cvt_pk_bf16_f32 v8, v2, v3
	v_cvt_pk_bf16_f32 v9, v4, v5
	global_store_dwordx4 v[18:19], v[6:9], off offset:256 sc0 sc1
	s_cbranch_vccnz .LBB0_2239
	s_andn2_b64 vcc, exec, s[2:3]
	s_cbranch_vccnz .LBB0_2238
	s_barrier
	s_branch .LBB0_2238

; __device__ __forceinline__ void ln_norm_only(f32x4 (&v)[8]) {
;     float s = 0.f;
; #pragma unroll
;     for (int j = 0; j < 8; ++j) s += (v[j][0] + v[j][1]) + (v[j][2] + v[j][3]);
;     const float mean = wave_sum(s) * (1.0f / DM); float q = 0.f;
; #pragma unroll
;     for (int j = 0; j < 8; ++j) { v[j] = v[j] - mean; q += (v[j][0] * v[j][0] + v[j][1] * v[j][1]) + (v[j][2] * v[j][2] + v[j][3] * v[j][3]); }
;     const float rstd = 1.0f / sqrtf(wave_sum(q) * (1.0f / DM) + LN_EPS);
.LBB0_2525:
	v_mov_b32_e32 v106, v58
	v_mov_b32_e32 v107, v62
	v_mov_b32_e32 v110, v59
	v_mov_b32_e32 v111, v63
	v_pk_add_f32 v[106:107], v[106:107], v[110:111]
	v_mov_b32_e32 v110, v60
	v_mov_b32_e32 v111, v64
	v_mov_b32_e32 v112, v61
	v_mov_b32_e32 v113, v65
	v_pk_add_f32 v[110:111], v[110:111], v[112:113]
	v_mov_b32_e32 v112, v50
	v_pk_add_f32 v[106:107], v[106:107], v[110:111]
	v_mov_b32_e32 v110, v51
	v_mov_b32_e32 v111, v52
	v_mov_b32_e32 v113, v53
	v_pk_add_f32 v[110:111], v[110:111], v[112:113]
	v_add_f32_e32 v107, 0, v107
	v_pk_add_f32 v[110:111], v[110:111], v[110:111] op_sel_hi:[0,1]
	v_add_f32_e32 v107, v106, v107
	v_add_f32_e32 v113, v46, v47
	v_add_f32_e32 v115, v48, v49
	v_mov_b32_e32 v112, v54
	v_mov_b32_e32 v114, v55
	v_mov_b32_e32 v110, v56
	v_mov_b32_e32 v106, v57
	v_pk_add_f32 v[112:113], v[112:113], v[114:115]
	v_pk_add_f32 v[106:107], v[110:111], v[106:107]
	v_mov_b32_e32 v110, v43
	v_pk_add_f32 v[106:107], v[112:113], v[106:107]
	v_mov_b32_e32 v111, v44
	v_mov_b32_e32 v112, v42
	v_mov_b32_e32 v113, v45
	v_pk_add_f32 v[110:111], v[110:111], v[112:113]
	v_pk_add_f32 v[106:107], v[106:107], v[106:107] op_sel_hi:[0,1]
	v_pk_add_f32 v[110:111], v[110:111], v[110:111] op_sel_hi:[0,1]
	v_add_f32_e32 v113, v38, v39
	v_add_f32_e32 v115, v40, v41
	v_mov_b32_e32 v112, v34
	v_mov_b32_e32 v114, v35
	v_mov_b32_e32 v110, v36
	v_mov_b32_e32 v106, v37
	v_pk_add_f32 v[112:113], v[112:113], v[114:115]
	v_pk_add_f32 v[106:107], v[110:111], v[106:107]
	s_lshl_b32 s9, s9, 11
	v_pk_add_f32 v[106:107], v[112:113], v[106:107]
	s_and_b64 s[0:1], s[10:11], exec
	v_add_f32_e32 v106, v106, v107
	v_and_b32_e32 v107, 64, v185
	v_add_u32_e32 v113, 64, v107
	v_xor_b32_e32 v107, 1, v185
	v_cmp_lt_i32_e32 vcc, v107, v113
	s_cselect_b32 s13, s9, 0x1000
	s_mov_b32 s9, 0xf800000
	v_cndmask_b32_e32 v107, v185, v107, vcc
	v_lshlrev_b32_e32 v107, 2, v107
	ds_bpermute_b32 v108, v107, v106
	v_readlane_b32 s16, v249, 0
	v_readlane_b32 s22, v249, 6
	s_waitcnt lgkmcnt(0)
	v_add_f32_e32 v106, v106, v108
	v_xor_b32_e32 v108, 2, v185
	v_cmp_lt_i32_e32 vcc, v108, v113
	v_readlane_b32 s23, v249, 7
	v_readlane_b32 s17, v249, 1
	v_cndmask_b32_e32 v108, v185, v108, vcc
	v_lshlrev_b32_e32 v108, 2, v108
	ds_bpermute_b32 v110, v108, v106
	v_readlane_b32 s18, v249, 2
	v_readlane_b32 s19, v249, 3
	v_readlane_b32 s20, v249, 4
	v_readlane_b32 s21, v249, 5
	s_waitcnt lgkmcnt(0)
	v_add_f32_e32 v106, v106, v110
	v_xor_b32_e32 v110, 4, v185
	v_cmp_lt_i32_e32 vcc, v110, v113
	s_nop 1
	v_cndmask_b32_e32 v110, v185, v110, vcc
	v_lshlrev_b32_e32 v110, 2, v110
	ds_bpermute_b32 v111, v110, v106
	s_waitcnt lgkmcnt(0)
	v_add_f32_e32 v106, v106, v111
	v_xor_b32_e32 v111, 8, v185
	v_cmp_lt_i32_e32 vcc, v111, v113
	s_nop 1
	v_cndmask_b32_e32 v111, v185, v111, vcc
	v_lshlrev_b32_e32 v111, 2, v111
	ds_bpermute_b32 v112, v111, v106
	s_waitcnt lgkmcnt(0)
	v_add_f32_e32 v106, v106, v112
	v_xor_b32_e32 v112, 16, v185
	v_cmp_lt_i32_e32 vcc, v112, v113
	s_nop 1
	v_cndmask_b32_e32 v112, v185, v112, vcc
	v_lshlrev_b32_e32 v112, 2, v112
	ds_bpermute_b32 v114, v112, v106
	s_waitcnt lgkmcnt(0)
	v_add_f32_e32 v106, v106, v114
	v_xor_b32_e32 v114, 32, v185
	v_cmp_lt_i32_e32 vcc, v114, v113
	s_nop 1
	v_cndmask_b32_e32 v113, v185, v114, vcc
	v_lshlrev_b32_e32 v113, 2, v113
	ds_bpermute_b32 v114, v113, v106
	s_waitcnt lgkmcnt(0)
	v_add_f32_e32 v122, v106, v114
	v_fmamk_f32 v63, v122, 0xba000000, v63
	v_fmamk_f32 v59, v122, 0xba000000, v59
	v_fmamk_f32 v65, v122, 0xba000000, v65
	v_fmac_f32_e32 v62, 0xba000000, v122
	v_fmamk_f32 v61, v122, 0xba000000, v61
	v_fmac_f32_e32 v58, 0xba000000, v122
	v_mov_b32_e32 v116, v63
	v_mov_b32_e32 v117, v59
	v_fmamk_f32 v64, v122, 0xba000000, v64
	v_fmamk_f32 v60, v122, 0xba000000, v60
	v_mov_b32_e32 v114, v62
	v_mov_b32_e32 v115, v58
	v_pk_mul_f32 v[116:117], v[116:117], v[116:117]
	v_mov_b32_e32 v118, v65
	v_mov_b32_e32 v119, v61
	v_pk_fma_f32 v[114:115], v[114:115], v[114:115], v[116:117]
	v_mov_b32_e32 v116, v64
	v_mov_b32_e32 v117, v60
	v_pk_mul_f32 v[118:119], v[118:119], v[118:119]
	v_fmamk_f32 v51, v122, 0xba000000, v51
	v_pk_fma_f32 v[116:117], v[116:117], v[116:117], v[118:119]
	v_fmamk_f32 v50, v122, 0xba000000, v50
	v_fmamk_f32 v53, v122, 0xba000000, v53
	v_fmac_f32_e32 v52, 0xba000000, v122
	v_pk_add_f32 v[114:115], v[114:115], v[116:117]
	v_pk_mul_f32 v[116:117], v[52:53], v[52:53]
	v_pk_mul_f32 v[118:119], v[50:51], v[50:51]
	v_fmamk_f32 v46, v122, 0xba000000, v46
	v_pk_mov_b32 v[120:121], v[118:119], v[116:117] op_sel:[1,0]
	v_mov_b32_e32 v119, v117
	v_fmamk_f32 v47, v122, 0xba000000, v47
	v_fmac_f32_e32 v48, 0xba000000, v122
	v_mul_f32_e32 v106, v46, v46
	v_pk_add_f32 v[116:117], v[120:121], v[118:119]
	v_fmamk_f32 v49, v122, 0xba000000, v49
	v_pk_fma_f32 v[118:119], v[46:47], v[46:47], v[106:107] op_sel_hi:[1,1,0]
	v_mul_f32_e32 v106, v48, v48
	v_pk_add_f32 v[114:115], v[114:115], v[114:115] op_sel_hi:[0,1]
	v_pk_add_f32 v[116:117], v[116:117], v[116:117] op_sel_hi:[0,1]
	v_pk_fma_f32 v[120:121], v[48:49], v[48:49], v[106:107] op_sel_hi:[1,1,0]
	v_fmamk_f32 v57, v122, 0xba000000, v57
	v_fmamk_f32 v56, v122, 0xba000000, v56
	v_fmamk_f32 v55, v122, 0xba000000, v55
	v_fmac_f32_e32 v54, 0xba000000, v122
	v_mul_f32_e32 v118, v54, v54
	v_mul_f32_e32 v120, v55, v55
	v_mul_f32_e32 v116, v56, v56
	v_mul_f32_e32 v114, v57, v57
	v_pk_add_f32 v[118:119], v[118:119], v[120:121]
	v_pk_add_f32 v[114:115], v[116:117], v[114:115]
	v_fmamk_f32 v43, v122, 0xba000000, v43
	v_fmamk_f32 v42, v122, 0xba000000, v42
	v_fmamk_f32 v45, v122, 0xba000000, v45
	v_fmac_f32_e32 v44, 0xba000000, v122
	v_pk_add_f32 v[114:115], v[118:119], v[114:115]
	v_pk_mul_f32 v[116:117], v[44:45], v[44:45]
	v_pk_mul_f32 v[118:119], v[42:43], v[42:43]
	v_fmamk_f32 v38, v122, 0xba000000, v38
	v_pk_mov_b32 v[120:121], v[118:119], v[116:117] op_sel:[1,0]
	v_mov_b32_e32 v119, v117
	v_fmamk_f32 v39, v122, 0xba000000, v39
	v_fmac_f32_e32 v40, 0xba000000, v122
	v_mul_f32_e32 v106, v38, v38
	v_pk_add_f32 v[116:117], v[120:121], v[118:119]
	v_fmamk_f32 v41, v122, 0xba000000, v41
	v_pk_fma_f32 v[118:119], v[38:39], v[38:39], v[106:107] op_sel_hi:[1,1,0]
	v_mul_f32_e32 v106, v40, v40
	v_pk_add_f32 v[114:115], v[114:115], v[114:115] op_sel_hi:[0,1]
	v_pk_add_f32 v[116:117], v[116:117], v[116:117] op_sel_hi:[0,1]
	v_pk_fma_f32 v[120:121], v[40:41], v[40:41], v[106:107] op_sel_hi:[1,1,0]
	v_fmamk_f32 v37, v122, 0xba000000, v37
	v_fmamk_f32 v36, v122, 0xba000000, v36
	v_fmamk_f32 v35, v122, 0xba000000, v35
	v_fmac_f32_e32 v34, 0xba000000, v122
	v_mul_f32_e32 v118, v34, v34
	v_mul_f32_e32 v120, v35, v35
	v_mul_f32_e32 v116, v36, v36
	v_mul_f32_e32 v114, v37, v37
	v_pk_add_f32 v[118:119], v[118:119], v[120:121]
	v_pk_add_f32 v[114:115], v[116:117], v[114:115]
	s_nop 0
	v_pk_add_f32 v[114:115], v[118:119], v[114:115]
	s_nop 0
	v_add_f32_e32 v106, v114, v115
	ds_bpermute_b32 v114, v107, v106
	s_waitcnt lgkmcnt(0)
; #define LAS __attribute__((address_space(3)))
; __device__ __forceinline__ void ln_norm_only(f32x4 (&v)[8]) {
;     ...
;     const float rstd = 1.0f / sqrtf(wave_sum(q) * (1.0f / DM) + LN_EPS);
; #pragma unroll
;     for (int j = 0; j < 8; ++j) v[j] = v[j] * rstd;
; __device__ __forceinline__ void combine_ln2(Frame& F, int l, int nrows) {
;     ...
; #pragma unroll
;         for (int j = 0; j < 8; ++j) { const int cc = 256 * j + 4 * F.lane;
;             xcur[j] = (xcur[j] * *(const LAS f32x4*)(PLW1 + cc) + *(const LAS f32x4*)(PLB1 + cc)) * ALPHA_RES + *(const LAS f32x4*)(g2 + cc) * moe[j]; }
	v_add_f32_e32 v106, v106, v114
	ds_bpermute_b32 v114, v108, v106
	s_waitcnt lgkmcnt(0)
	v_add_f32_e32 v106, v106, v114
	ds_bpermute_b32 v114, v110, v106
	s_waitcnt lgkmcnt(0)
	v_add_f32_e32 v106, v106, v114
	ds_bpermute_b32 v114, v111, v106
	s_waitcnt lgkmcnt(0)
	v_add_f32_e32 v106, v106, v114
	ds_bpermute_b32 v114, v112, v106
	s_waitcnt lgkmcnt(0)
	v_add_f32_e32 v106, v106, v114
	ds_bpermute_b32 v114, v113, v106
	s_waitcnt lgkmcnt(0)
	v_add_f32_e32 v106, v106, v114
	v_fmamk_f32 v106, v106, 0x3a000000, v179
	v_cmp_gt_f32_e32 vcc, s9, v106
	v_mul_f32_e32 v114, 0x4f800000, v106
	s_nop 0
	v_cndmask_b32_e32 v106, v106, v114, vcc
	v_sqrt_f32_e32 v114, v106
	s_nop 0
	v_add_u32_e32 v115, -1, v114
	v_fma_f32 v116, -v115, v114, v106
	v_cmp_ge_f32_e64 s[0:1], 0, v116
	v_add_u32_e32 v116, 1, v114
	s_nop 0
	v_cndmask_b32_e64 v115, v114, v115, s[0:1]
	v_fma_f32 v114, -v116, v114, v106
	v_cmp_lt_f32_e64 s[0:1], 0, v114
	s_nop 1
	v_cndmask_b32_e64 v114, v115, v116, s[0:1]
	v_mul_f32_e32 v115, 0x37800000, v114
	v_cndmask_b32_e32 v114, v114, v115, vcc
	v_cmp_class_f32_e32 vcc, v106, v180
	s_nop 1
	v_cndmask_b32_e32 v106, v114, v106, vcc
	v_div_scale_f32 v114, s[0:1], v106, v106, 1.0
	v_rcp_f32_e32 v115, v114
	s_mov_b32 s0, 0x3fb504f3
	v_fma_f32 v116, -v114, v115, 1.0
	v_fmac_f32_e32 v115, v116, v115
	v_div_scale_f32 v116, vcc, 1.0, v106, 1.0
	v_mul_f32_e32 v117, v116, v115
	v_fma_f32 v118, -v114, v117, v116
	v_fmac_f32_e32 v117, v118, v115
	v_fma_f32 v114, -v114, v117, v116
	v_div_fmas_f32 v114, v114, v115, v117
	v_div_fixup_f32 v106, v114, v106, 1.0
	v_pk_mul_f32 v[114:115], v[62:63], v[106:107] op_sel_hi:[1,0]
	v_pk_mul_f32 v[118:119], v[58:59], v[106:107] op_sel_hi:[1,0]
	v_pk_mul_f32 v[122:123], v[50:51], v[106:107] op_sel_hi:[1,0]
	v_pk_mul_f32 v[124:125], v[52:53], v[106:107] op_sel_hi:[1,0]
	v_pk_mul_f32 v[58:59], v[56:57], v[106:107] op_sel_hi:[1,0]
	v_pk_mul_f32 v[56:57], v[38:39], v[106:107] op_sel_hi:[1,0]
	v_pk_mul_f32 v[62:63], v[40:41], v[106:107] op_sel_hi:[1,0]
	v_pk_mul_f32 v[50:51], v[34:35], v[106:107] op_sel_hi:[1,0]
	v_pk_mul_f32 v[52:53], v[36:37], v[106:107] op_sel_hi:[1,0]
	ds_read_b128 v[34:37], v140
	ds_read_b128 v[38:41], v141
	v_pk_mul_f32 v[116:117], v[64:65], v[106:107] op_sel_hi:[1,0]
	v_pk_mul_f32 v[120:121], v[60:61], v[106:107] op_sel_hi:[1,0]
	v_pk_mul_f32 v[126:127], v[46:47], v[106:107] op_sel_hi:[1,0]
	v_pk_mul_f32 v[128:129], v[48:49], v[106:107] op_sel_hi:[1,0]
	v_pk_mul_f32 v[48:49], v[54:55], v[106:107] op_sel_hi:[1,0]
	v_pk_mul_f32 v[60:61], v[42:43], v[106:107] op_sel_hi:[1,0]
	v_pk_mul_f32 v[64:65], v[44:45], v[106:107] op_sel_hi:[1,0]
	s_waitcnt lgkmcnt(0)
	v_pk_fma_f32 v[36:37], v[36:37], v[116:117], v[40:41]
	v_pk_fma_f32 v[34:35], v[34:35], v[114:115], v[38:39]
	v_lshl_add_u32 v106, s13, 2, v139
	v_pk_mul_f32 v[40:41], v[34:35], s[0:1] op_sel_hi:[1,0]
	v_pk_mul_f32 v[34:35], v[36:37], s[0:1] op_sel_hi:[1,0]
	ds_read_b128 v[36:39], v106
	s_waitcnt lgkmcnt(0)
	v_pk_fma_f32 v[34:35], v[104:105], v[38:39], v[34:35]
	v_pk_fma_f32 v[36:37], v[102:103], v[36:37], v[40:41]
	ds_read_b128 v[38:41], v142
	ds_read_b128 v[42:45], v143
	s_waitcnt lgkmcnt(0)
	v_pk_fma_f32 v[40:41], v[40:41], v[120:121], v[44:45]
	v_pk_fma_f32 v[38:39], v[38:39], v[118:119], v[42:43]
	s_nop 0
	v_pk_mul_f32 v[44:45], v[38:39], s[0:1] op_sel_hi:[1,0]
	v_pk_mul_f32 v[38:39], v[40:41], s[0:1] op_sel_hi:[1,0]
	ds_read_b128 v[40:43], v106 offset:1024
	s_waitcnt lgkmcnt(0)
	v_pk_fma_f32 v[38:39], v[100:101], v[42:43], v[38:39]
	v_pk_fma_f32 v[42:43], v[98:99], v[40:41], v[44:45]
	ds_read_b128 v[44:47], v144
	ds_read_b128 v[98:101], v154
	s_waitcnt lgkmcnt(0)
	v_pk_fma_f32 v[44:45], v[44:45], v[122:123], v[98:99]
	v_pk_fma_f32 v[40:41], v[46:47], v[124:125], v[100:101]
	v_pk_mul_f32 v[54:55], v[44:45], s[0:1] op_sel_hi:[1,0]
	ds_read_b128 v[44:47], v106 offset:2048
	v_pk_mul_f32 v[40:41], v[40:41], s[0:1] op_sel_hi:[1,0]
	s_waitcnt lgkmcnt(0)
	v_pk_fma_f32 v[44:45], v[94:95], v[44:45], v[54:55]
	v_pk_fma_f32 v[40:41], v[96:97], v[46:47], v[40:41]
	ds_read_b128 v[94:97], v155
	ds_read_b128 v[98:101], v156
	s_waitcnt lgkmcnt(0)
	v_pk_fma_f32 v[46:47], v[96:97], v[128:129], v[100:101]
	v_pk_fma_f32 v[54:55], v[94:95], v[126:127], v[98:99]
	ds_read_b128 v[94:97], v106 offset:3072
	v_pk_mul_f32 v[54:55], v[54:55], s[0:1] op_sel_hi:[1,0]
	v_pk_mul_f32 v[46:47], v[46:47], s[0:1] op_sel_hi:[1,0]
	s_waitcnt lgkmcnt(0)
	v_pk_fma_f32 v[54:55], v[90:91], v[94:95], v[54:55]
	v_pk_fma_f32 v[46:47], v[92:93], v[96:97], v[46:47]
	ds_read_b128 v[90:93], v157
	ds_read_b128 v[94:97], v158
	s_waitcnt lgkmcnt(0)
	v_pk_fma_f32 v[58:59], v[92:93], v[58:59], v[96:97]
	v_pk_fma_f32 v[48:49], v[90:91], v[48:49], v[94:95]
	ds_read_b128 v[90:93], v106 offset:4096
	v_pk_mul_f32 v[94:95], v[48:49], s[0:1] op_sel_hi:[1,0]
	v_pk_mul_f32 v[48:49], v[58:59], s[0:1] op_sel_hi:[1,0]
	s_waitcnt lgkmcnt(0)
	v_pk_fma_f32 v[58:59], v[86:87], v[90:91], v[94:95]
	v_pk_fma_f32 v[48:49], v[88:89], v[92:93], v[48:49]
	ds_read_b128 v[86:89], v159
	ds_read_b128 v[90:93], v160
	s_waitcnt lgkmcnt(0)
	v_pk_fma_f32 v[64:65], v[88:89], v[64:65], v[92:93]
	v_pk_fma_f32 v[60:61], v[86:87], v[60:61], v[90:91]
	ds_read_b128 v[86:89], v106 offset:5120
	v_pk_mul_f32 v[90:91], v[60:61], s[0:1] op_sel_hi:[1,0]
	v_pk_mul_f32 v[60:61], v[64:65], s[0:1] op_sel_hi:[1,0]
	s_waitcnt lgkmcnt(0)
	v_pk_fma_f32 v[64:65], v[82:83], v[86:87], v[90:91]
	v_pk_fma_f32 v[60:61], v[84:85], v[88:89], v[60:61]
	ds_read_b128 v[82:85], v161
	ds_read_b128 v[86:89], v162
	s_waitcnt lgkmcnt(0)
; #define LAS __attribute__((address_space(3)))
; __device__ __forceinline__ void ln_inplace_lds(f32x4 (&v)[8], const LAS float* w, const LAS float* b, int lane) {
;     float s = 0.f;
; #pragma unroll
;     for (int j = 0; j < 8; ++j) s += (v[j][0] + v[j][1]) + (v[j][2] + v[j][3]);
;     const float mean = wave_sum(s) * (1.0f / DM); float q = 0.f;
; #pragma unroll
;     for (int j = 0; j < 8; ++j) { v[j] = v[j] - mean; q += (v[j][0] * v[j][0] + v[j][1] * v[j][1]) + (v[j][2] * v[j][2] + v[j][3] * v[j][3]); }
;     const float rstd = 1.0f / sqrtf(wave_sum(q) * (1.0f / DM) + LN_EPS);
	v_pk_fma_f32 v[62:63], v[84:85], v[62:63], v[88:89]
	v_pk_fma_f32 v[56:57], v[82:83], v[56:57], v[86:87]
	ds_read_b128 v[82:85], v106 offset:6144
	v_pk_mul_f32 v[56:57], v[56:57], s[0:1] op_sel_hi:[1,0]
	v_pk_mul_f32 v[62:63], v[62:63], s[0:1] op_sel_hi:[1,0]
	s_waitcnt lgkmcnt(0)
	v_pk_fma_f32 v[78:79], v[78:79], v[82:83], v[56:57]
	v_pk_fma_f32 v[62:63], v[80:81], v[84:85], v[62:63]
	ds_read_b128 v[80:83], v163
	ds_read_b128 v[84:87], v164
	s_waitcnt lgkmcnt(0)
	v_pk_fma_f32 v[52:53], v[82:83], v[52:53], v[86:87]
	v_pk_fma_f32 v[50:51], v[80:81], v[50:51], v[84:85]
	v_pk_mul_f32 v[80:81], v[52:53], s[0:1] op_sel_hi:[1,0]
	v_pk_mul_f32 v[56:57], v[50:51], s[0:1] op_sel_hi:[1,0]
	ds_read_b128 v[50:53], v106 offset:7168
	s_waitcnt lgkmcnt(0)
	v_pk_fma_f32 v[76:77], v[76:77], v[52:53], v[80:81]
	v_pk_fma_f32 v[74:75], v[74:75], v[50:51], v[56:57]
	v_mov_b32_e32 v50, v42
	v_mov_b32_e32 v51, v36
	v_mov_b32_e32 v52, v43
	v_mov_b32_e32 v53, v37
	v_pk_add_f32 v[50:51], v[50:51], v[52:53]
	v_mov_b32_e32 v52, v38
	v_mov_b32_e32 v53, v34
	v_mov_b32_e32 v56, v39
	v_mov_b32_e32 v57, v35
	v_pk_add_f32 v[52:53], v[52:53], v[56:57]
	v_mov_b32_e32 v56, v44
	v_pk_add_f32 v[50:51], v[50:51], v[52:53]
	v_pk_mov_b32 v[52:53], v[44:45], v[40:41] op_sel:[1,0]
	v_mov_b32_e32 v57, v41
	v_pk_add_f32 v[52:53], v[52:53], v[56:57]
	v_add_f32_e32 v51, 0, v51
	v_pk_add_f32 v[52:53], v[52:53], v[52:53] op_sel_hi:[0,1]
	v_add_f32_e32 v51, v50, v51
	v_add_f32_e32 v57, v54, v55
	v_add_f32_e32 v81, v46, v47
	v_mov_b32_e32 v56, v58
	v_mov_b32_e32 v80, v59
	v_mov_b32_e32 v52, v48
	v_mov_b32_e32 v50, v49
	v_pk_add_f32 v[56:57], v[56:57], v[80:81]
	v_pk_add_f32 v[50:51], v[52:53], v[50:51]
	v_pk_mov_b32 v[52:53], v[64:65], v[60:61] op_sel:[1,0]
	v_pk_add_f32 v[50:51], v[56:57], v[50:51]
	v_mov_b32_e32 v56, v64
	v_mov_b32_e32 v57, v61
	v_pk_add_f32 v[52:53], v[52:53], v[56:57]
	v_pk_add_f32 v[50:51], v[50:51], v[50:51] op_sel_hi:[0,1]
	v_pk_add_f32 v[52:53], v[52:53], v[52:53] op_sel_hi:[0,1]
	v_add_f32_e32 v57, v78, v79
	v_add_f32_e32 v81, v62, v63
	v_mov_b32_e32 v56, v74
	v_mov_b32_e32 v80, v75
	v_mov_b32_e32 v52, v76
	v_mov_b32_e32 v50, v77
	v_pk_add_f32 v[56:57], v[56:57], v[80:81]
	v_pk_add_f32 v[50:51], v[52:53], v[50:51]
	s_nop 0
	v_pk_add_f32 v[50:51], v[56:57], v[50:51]
	s_nop 0
	v_add_f32_e32 v50, v50, v51
	ds_bpermute_b32 v51, v107, v50
	s_waitcnt lgkmcnt(0)
	v_add_f32_e32 v50, v50, v51
	ds_bpermute_b32 v51, v108, v50
	s_waitcnt lgkmcnt(0)
	v_add_f32_e32 v50, v50, v51
	ds_bpermute_b32 v51, v110, v50
	s_waitcnt lgkmcnt(0)
	v_add_f32_e32 v50, v50, v51
	ds_bpermute_b32 v51, v111, v50
	s_waitcnt lgkmcnt(0)
	v_add_f32_e32 v50, v50, v51
	ds_bpermute_b32 v51, v112, v50
	s_waitcnt lgkmcnt(0)
	v_add_f32_e32 v50, v50, v51
	ds_bpermute_b32 v51, v113, v50
	s_waitcnt lgkmcnt(0)
	v_add_f32_e32 v82, v50, v51
	v_fmamk_f32 v37, v82, 0xba000000, v37
	v_fmamk_f32 v43, v82, 0xba000000, v43
	v_fmamk_f32 v35, v82, 0xba000000, v35
	v_fmac_f32_e32 v36, 0xba000000, v82
	v_fmamk_f32 v39, v82, 0xba000000, v39
	v_fmac_f32_e32 v42, 0xba000000, v82
	v_mov_b32_e32 v52, v37
	v_mov_b32_e32 v53, v43
	v_fmac_f32_e32 v34, 0xba000000, v82
	v_fmac_f32_e32 v38, 0xba000000, v82
	v_mov_b32_e32 v50, v36
	v_mov_b32_e32 v51, v42
	v_pk_mul_f32 v[52:53], v[52:53], v[52:53]
	v_mov_b32_e32 v56, v35
	v_mov_b32_e32 v57, v39
	v_pk_fma_f32 v[50:51], v[50:51], v[50:51], v[52:53]
	v_mov_b32_e32 v52, v34
	v_mov_b32_e32 v53, v38
	v_pk_mul_f32 v[56:57], v[56:57], v[56:57]
	v_fmamk_f32 v45, v82, 0xba000000, v45
	v_pk_fma_f32 v[52:53], v[52:53], v[52:53], v[56:57]
	v_fmac_f32_e32 v44, 0xba000000, v82
	v_pk_add_f32 v[50:51], v[50:51], v[52:53]
	v_fmamk_f32 v41, v82, 0xba000000, v41
	v_fmac_f32_e32 v40, 0xba000000, v82
	v_pk_add_f32 v[50:51], v[50:51], v[50:51] op_sel_hi:[0,1]
	v_pk_mul_f32 v[52:53], v[40:41], v[40:41]
	v_pk_mul_f32 v[56:57], v[44:45], v[44:45]
	v_fmac_f32_e32 v54, 0xba000000, v82
	v_pk_mov_b32 v[80:81], v[56:57], v[52:53] op_sel:[1,0]
	v_mov_b32_e32 v57, v53
	v_fmamk_f32 v55, v82, 0xba000000, v55
	v_fmac_f32_e32 v46, 0xba000000, v82
	v_mul_f32_e32 v50, v54, v54
	v_pk_add_f32 v[52:53], v[80:81], v[56:57]
	v_fmamk_f32 v47, v82, 0xba000000, v47
	v_pk_fma_f32 v[56:57], v[54:55], v[54:55], v[50:51] op_sel_hi:[1,1,0]
	v_mul_f32_e32 v50, v46, v46
	v_pk_add_f32 v[52:53], v[52:53], v[52:53] op_sel_hi:[0,1]
	v_pk_fma_f32 v[80:81], v[46:47], v[46:47], v[50:51] op_sel_hi:[1,1,0]
	v_fmamk_f32 v49, v82, 0xba000000, v49
	v_fmac_f32_e32 v48, 0xba000000, v82
	v_fmamk_f32 v59, v82, 0xba000000, v59
	v_fmac_f32_e32 v58, 0xba000000, v82
	v_mul_f32_e32 v56, v58, v58
	v_mul_f32_e32 v80, v59, v59
	v_mul_f32_e32 v52, v48, v48
	v_mul_f32_e32 v50, v49, v49
	v_pk_add_f32 v[56:57], v[56:57], v[80:81]
	v_pk_add_f32 v[50:51], v[52:53], v[50:51]
	v_fmamk_f32 v65, v82, 0xba000000, v65
	v_pk_add_f32 v[50:51], v[56:57], v[50:51]
	v_fmac_f32_e32 v64, 0xba000000, v82
	v_fmamk_f32 v61, v82, 0xba000000, v61
	v_fmac_f32_e32 v60, 0xba000000, v82
	v_pk_add_f32 v[50:51], v[50:51], v[50:51] op_sel_hi:[0,1]
	v_pk_mul_f32 v[52:53], v[60:61], v[60:61]
	v_pk_mul_f32 v[56:57], v[64:65], v[64:65]
	v_fmac_f32_e32 v78, 0xba000000, v82
	v_pk_mov_b32 v[80:81], v[56:57], v[52:53] op_sel:[1,0]
	v_mov_b32_e32 v57, v53
	v_fmamk_f32 v79, v82, 0xba000000, v79
	v_fmac_f32_e32 v62, 0xba000000, v82
	v_mul_f32_e32 v50, v78, v78
	v_pk_add_f32 v[52:53], v[80:81], v[56:57]
	v_fmamk_f32 v63, v82, 0xba000000, v63
	v_pk_fma_f32 v[56:57], v[78:79], v[78:79], v[50:51] op_sel_hi:[1,1,0]
	v_mul_f32_e32 v50, v62, v62
	v_pk_add_f32 v[52:53], v[52:53], v[52:53] op_sel_hi:[0,1]
	v_pk_fma_f32 v[80:81], v[62:63], v[62:63], v[50:51] op_sel_hi:[1,1,0]
	v_fmamk_f32 v77, v82, 0xba000000, v77
	v_fmac_f32_e32 v76, 0xba000000, v82
	v_fmamk_f32 v75, v82, 0xba000000, v75
	v_fmac_f32_e32 v74, 0xba000000, v82
	v_mul_f32_e32 v56, v74, v74
	v_mul_f32_e32 v80, v75, v75
	v_mul_f32_e32 v52, v76, v76
	v_mul_f32_e32 v50, v77, v77
	v_pk_add_f32 v[56:57], v[56:57], v[80:81]
	v_pk_add_f32 v[50:51], v[52:53], v[50:51]
	s_nop 0
	v_pk_add_f32 v[50:51], v[56:57], v[50:51]
	s_nop 0
	v_add_f32_e32 v50, v50, v51
	ds_bpermute_b32 v51, v107, v50
	s_waitcnt lgkmcnt(0)
; #define LAS __attribute__((address_space(3)))
; __device__ __forceinline__ void ln_inplace_lds(f32x4 (&v)[8], const LAS float* w, const LAS float* b, int lane) {
;     ...
;     const float rstd = 1.0f / sqrtf(wave_sum(q) * (1.0f / DM) + LN_EPS);
; #pragma unroll
;     for (int j = 0; j < 8; ++j) { const int c = 256 * j + 4 * lane; v[j] = v[j] * rstd * *(const LAS f32x4*)(w + c) + *(const LAS f32x4*)(b + c); }
; __device__ __forceinline__ void combine_ln2(Frame& F, int l, int nrows) {
;     ...
;         float* orow = lat ? F.out + (size_t)row * DM : (float*)(F.ws + WS_R2C) + (size_t)(row - NLAT) * DM;
; #pragma unroll
;         for (int j = 0; j < 8; ++j) *(f32x4*)(orow + 256 * j + 4 * F.lane) = xcur[j];
;         if (l + 1 < DEPTH) store_mod_bf16_lds((bf16*)(F.ws + WS_XM) + (size_t)row * DM, xcur, PSH + brow * DM, PSC + brow * DM, F.lane);
	v_add_f32_e32 v50, v50, v51
	ds_bpermute_b32 v51, v108, v50
	s_waitcnt lgkmcnt(0)
	v_add_f32_e32 v50, v50, v51
	ds_bpermute_b32 v51, v110, v50
	s_waitcnt lgkmcnt(0)
	v_add_f32_e32 v50, v50, v51
	ds_bpermute_b32 v51, v111, v50
	s_waitcnt lgkmcnt(0)
	v_add_f32_e32 v50, v50, v51
	ds_bpermute_b32 v51, v112, v50
	s_waitcnt lgkmcnt(0)
	v_add_f32_e32 v50, v50, v51
	ds_bpermute_b32 v51, v113, v50
	s_waitcnt lgkmcnt(0)
	v_add_f32_e32 v50, v50, v51
	v_fmamk_f32 v50, v50, 0x3a000000, v179
	v_cmp_gt_f32_e32 vcc, s9, v50
	v_mul_f32_e32 v51, 0x4f800000, v50
	s_ashr_i32 s9, s8, 31
	v_cndmask_b32_e32 v50, v50, v51, vcc
	v_sqrt_f32_e32 v51, v50
	s_nop 0
	v_add_u32_e32 v52, -1, v51
	v_fma_f32 v53, -v52, v51, v50
	v_cmp_ge_f32_e64 s[0:1], 0, v53
	v_add_u32_e32 v53, 1, v51
	s_nop 0
	v_cndmask_b32_e64 v52, v51, v52, s[0:1]
	v_fma_f32 v51, -v53, v51, v50
	v_cmp_lt_f32_e64 s[0:1], 0, v51
	s_nop 1
	v_cndmask_b32_e64 v51, v52, v53, s[0:1]
	v_mul_f32_e32 v52, 0x37800000, v51
	v_cndmask_b32_e32 v51, v51, v52, vcc
	v_cmp_class_f32_e32 vcc, v50, v180
	s_and_b64 s[0:1], s[10:11], exec
	v_readlane_b32 s10, v251, 30
	v_cndmask_b32_e32 v50, v51, v50, vcc
	v_div_scale_f32 v51, s[0:1], v50, v50, 1.0
	v_rcp_f32_e32 v52, v51
	s_cselect_b32 s1, s9, 0
	s_cselect_b32 s0, s8, s5
	v_readlane_b32 s5, v251, 31
	v_fma_f32 v53, -v51, v52, 1.0
	v_fmac_f32_e32 v52, v53, v52
	v_div_scale_f32 v53, vcc, 1.0, v50, 1.0
	v_mul_f32_e32 v56, v53, v52
	v_fma_f32 v57, -v51, v56, v53
	v_fmac_f32_e32 v56, v57, v52
	v_fma_f32 v51, -v51, v56, v53
	v_div_fmas_f32 v51, v51, v52, v56
	v_div_fixup_f32 v80, v51, v50, 1.0
	v_pk_mul_f32 v[56:57], v[36:37], v[80:81] op_sel_hi:[1,0]
	v_pk_mul_f32 v[82:83], v[34:35], v[80:81] op_sel_hi:[1,0]
	ds_read_b128 v[34:37], v139 offset:24576
	ds_read_b128 v[50:53], v139 offset:32768
	v_pk_mul_f32 v[42:43], v[42:43], v[80:81] op_sel_hi:[1,0]
	v_pk_mul_f32 v[38:39], v[38:39], v[80:81] op_sel_hi:[1,0]
	v_pk_mul_f32 v[46:47], v[46:47], v[80:81] op_sel_hi:[1,0]
	v_pk_mul_f32 v[58:59], v[58:59], v[80:81] op_sel_hi:[1,0]
	s_waitcnt lgkmcnt(0)
	v_pk_fma_f32 v[36:37], v[36:37], v[82:83], v[52:53]
	v_pk_fma_f32 v[34:35], v[34:35], v[56:57], v[50:51]
	ds_read_b128 v[50:53], v139 offset:25600
	ds_read_b128 v[82:85], v139 offset:33792
	v_pk_mul_f32 v[56:57], v[44:45], v[80:81] op_sel_hi:[1,0]
	v_pk_mul_f32 v[64:65], v[64:65], v[80:81] op_sel_hi:[1,0]
	v_pk_mul_f32 v[78:79], v[78:79], v[80:81] op_sel_hi:[1,0]
	s_cselect_b32 s5, s23, s5
	s_waitcnt lgkmcnt(0)
	v_pk_fma_f32 v[52:53], v[52:53], v[38:39], v[84:85]
	v_pk_fma_f32 v[50:51], v[50:51], v[42:43], v[82:83]
	v_pk_mul_f32 v[82:83], v[40:41], v[80:81] op_sel_hi:[1,0]
	ds_read_b128 v[38:41], v139 offset:26624
	ds_read_b128 v[42:45], v139 offset:34816
	s_cselect_b32 s10, s22, s10
	s_lshl_b64 s[0:1], s[0:1], 13
	s_add_u32 s0, s10, s0
	s_addc_u32 s1, s5, s1
	s_waitcnt lgkmcnt(0)
	v_pk_fma_f32 v[40:41], v[40:41], v[82:83], v[44:45]
	v_pk_fma_f32 v[38:39], v[38:39], v[56:57], v[42:43]
	v_pk_mul_f32 v[82:83], v[54:55], v[80:81] op_sel_hi:[1,0]
	ds_read_b128 v[42:45], v139 offset:27648
	ds_read_b128 v[54:57], v139 offset:35840
	s_waitcnt lgkmcnt(0)
	v_pk_fma_f32 v[56:57], v[44:45], v[46:47], v[56:57]
	v_pk_fma_f32 v[54:55], v[42:43], v[82:83], v[54:55]
	v_pk_mul_f32 v[82:83], v[48:49], v[80:81] op_sel_hi:[1,0]
	ds_read_b128 v[42:45], v139 offset:28672
	ds_read_b128 v[46:49], v139 offset:36864
	s_waitcnt lgkmcnt(0)
	v_pk_fma_f32 v[44:45], v[44:45], v[82:83], v[48:49]
	v_pk_fma_f32 v[42:43], v[42:43], v[58:59], v[46:47]
	v_pk_mul_f32 v[82:83], v[60:61], v[80:81] op_sel_hi:[1,0]
	ds_read_b128 v[46:49], v139 offset:29696
	ds_read_b128 v[58:61], v139 offset:37888
	s_waitcnt lgkmcnt(0)
	v_pk_fma_f32 v[60:61], v[48:49], v[82:83], v[60:61]
	v_pk_fma_f32 v[58:59], v[46:47], v[64:65], v[58:59]
	v_pk_mul_f32 v[82:83], v[62:63], v[80:81] op_sel_hi:[1,0]
	ds_read_b128 v[46:49], v139 offset:30720
	ds_read_b128 v[62:65], v139 offset:38912
	s_waitcnt lgkmcnt(0)
	v_pk_fma_f32 v[48:49], v[48:49], v[82:83], v[64:65]
	v_pk_fma_f32 v[46:47], v[46:47], v[78:79], v[62:63]
	v_pk_mul_f32 v[78:79], v[74:75], v[80:81] op_sel_hi:[1,0]
	v_pk_mul_f32 v[80:81], v[76:77], v[80:81] op_sel_hi:[1,0]
	ds_read_b128 v[62:65], v139 offset:31744
	ds_read_b128 v[74:77], v139 offset:39936
	global_store_dwordx4 v146, v[34:37], s[0:1] sc0 sc1
	global_store_dwordx4 v146, v[50:53], s[0:1] offset:1024 sc0 sc1
	global_store_dwordx4 v146, v[38:41], s[0:1] offset:2048 sc0 sc1
	global_store_dwordx4 v146, v[54:57], s[0:1] offset:3072 sc0 sc1
	s_waitcnt lgkmcnt(0)
	v_pk_fma_f32 v[62:63], v[62:63], v[78:79], v[74:75]
	v_lshl_add_u64 v[74:75], s[0:1], 0, v[146:147]
	v_add_co_u32_e32 v74, vcc, 0x1000, v74
	v_readlane_b32 s0, v254, 21
	s_nop 0
	v_addc_co_u32_e32 v75, vcc, 0, v75, vcc
	v_readlane_b32 s1, v254, 22
	v_pk_fma_f32 v[64:65], v[64:65], v[80:81], v[76:77]
	s_andn2_b64 vcc, exec, s[0:1]
	global_store_dwordx4 v[74:75], v[42:45], off sc0 sc1
	global_store_dwordx4 v[74:75], v[58:61], off offset:1024 sc0 sc1
	global_store_dwordx4 v[74:75], v[46:49], off offset:2048 sc0 sc1
	global_store_dwordx4 v[74:75], v[62:65], off offset:3072 sc0 sc1
	s_cbranch_vccnz .LBB0_2511
; #define LAS __attribute__((address_space(3)))
; __device__ __forceinline__ unsigned pk2(float lo, float hi) { return f2bf(lo) | (f2bf(hi) << 16); }
; __device__ __forceinline__ void store_mod_bf16_lds(bf16* orow, const f32x4 (&v)[8], const LAS float* sh, const LAS float* sc1p, int lane) {
; #pragma unroll
;     for (int j = 0; j < 8; ++j) { const int c = 256 * j + 4 * lane; const f32x4 s1 = *(const LAS f32x4*)(sc1p + c), s0 = *(const LAS f32x4*)(sh + c);
;         const f32x4 h = v[j] * s1 + s0; v2u w; w.x = pk2(h[0], h[1]); w.y = pk2(h[2], h[3]); *(v2u*)(orow + c) = w; }
; }
; __device__ __forceinline__ void combine_ln2(Frame& F, int l, int nrows) {
;     ...
;         if (l + 1 < DEPTH) store_mod_bf16_lds((bf16*)(F.ws + WS_XM) + (size_t)row * DM, xcur, PSH + brow * DM, PSC + brow * DM, F.lane);
	v_lshl_add_u32 v92, s13, 2, v165
	ds_read_b128 v[74:77], v106 offset:40960
	ds_read_b128 v[78:81], v92
	ds_read_b128 v[82:85], v106 offset:41984
	ds_read_b128 v[86:89], v92 offset:1024
	s_lshl_b64 s[0:1], s[8:9], 12
	v_lshl_add_u64 v[90:91], v[72:73], 0, s[0:1]
	s_waitcnt lgkmcnt(2)
	v_pk_fma_f32 v[34:35], v[34:35], v[78:79], v[74:75]
	s_nop 0
	v_bfe_u32 v74, v34, 16, 1
	v_add3_u32 v34, v34, v74, s70
	v_bfe_u32 v74, v35, 16, 1
	v_pk_fma_f32 v[36:37], v[36:37], v[80:81], v[76:77]
	v_lshrrev_b32_e32 v34, 16, v34
	v_add3_u32 v35, v35, v74, s70
	v_and_or_b32 v34, v35, s33, v34
	v_bfe_u32 v35, v36, 16, 1
	v_add3_u32 v35, v36, v35, s70
	v_bfe_u32 v36, v37, 16, 1
	v_lshrrev_b32_e32 v35, 16, v35
	v_add3_u32 v36, v37, v36, s70
	v_and_or_b32 v35, v36, s33, v35
	s_waitcnt lgkmcnt(0)
	v_pk_fma_f32 v[36:37], v[50:51], v[86:87], v[82:83]
	global_store_dwordx2 v[90:91], v[34:35], off
	v_bfe_u32 v50, v36, 16, 1
	v_add3_u32 v36, v36, v50, s70
	v_bfe_u32 v50, v37, 16, 1
	v_pk_fma_f32 v[34:35], v[52:53], v[88:89], v[84:85]
	v_lshrrev_b32_e32 v36, 16, v36
	v_add3_u32 v37, v37, v50, s70
	v_and_or_b32 v74, v37, s33, v36
	v_bfe_u32 v36, v34, 16, 1
	v_add3_u32 v34, v34, v36, s70
	v_lshrrev_b32_e32 v75, 16, v34
	v_bfe_u32 v34, v35, 16, 1
	v_add3_u32 v76, v35, v34, s70
	ds_read_b128 v[34:37], v92 offset:2048
	ds_read_b128 v[50:53], v106 offset:43008
	v_and_or_b32 v75, v76, s33, v75
	global_store_dwordx2 v[90:91], v[74:75], off offset:512
	ds_read_b128 v[74:77], v92 offset:3072
	ds_read_b128 v[78:81], v106 offset:44032
	s_waitcnt lgkmcnt(2)
	v_pk_fma_f32 v[34:35], v[38:39], v[34:35], v[50:51]
	s_nop 0
	v_bfe_u32 v38, v34, 16, 1
	v_add3_u32 v34, v34, v38, s70
	v_bfe_u32 v38, v35, 16, 1
	v_pk_fma_f32 v[36:37], v[40:41], v[36:37], v[52:53]
	v_lshrrev_b32_e32 v34, 16, v34
	v_add3_u32 v35, v35, v38, s70
	v_and_or_b32 v34, v35, s33, v34
	v_bfe_u32 v35, v36, 16, 1
	v_add3_u32 v35, v36, v35, s70
	v_bfe_u32 v36, v37, 16, 1
	v_lshrrev_b32_e32 v35, 16, v35
	v_add3_u32 v36, v37, v36, s70
	v_and_or_b32 v35, v36, s33, v35
	s_waitcnt lgkmcnt(0)
	v_pk_fma_f32 v[36:37], v[54:55], v[74:75], v[78:79]
	global_store_dwordx2 v[90:91], v[34:35], off offset:1024
	v_bfe_u32 v38, v36, 16, 1
	v_add3_u32 v36, v36, v38, s70
	v_bfe_u32 v38, v37, 16, 1
	v_pk_fma_f32 v[34:35], v[56:57], v[76:77], v[80:81]
	v_lshrrev_b32_e32 v36, 16, v36
	v_add3_u32 v37, v37, v38, s70
	v_and_or_b32 v50, v37, s33, v36
	v_bfe_u32 v36, v34, 16, 1
	v_add3_u32 v34, v34, v36, s70
	v_lshrrev_b32_e32 v51, 16, v34
	v_bfe_u32 v34, v35, 16, 1
	v_add3_u32 v52, v35, v34, s70
	ds_read_b128 v[34:37], v92 offset:4096
	ds_read_b128 v[38:41], v106 offset:45056
	v_and_or_b32 v51, v52, s33, v51
	global_store_dwordx2 v[90:91], v[50:51], off offset:1536
	ds_read_b128 v[50:53], v92 offset:5120
	ds_read_b128 v[54:57], v106 offset:46080
	s_waitcnt lgkmcnt(2)
	v_pk_fma_f32 v[34:35], v[42:43], v[34:35], v[38:39]
	s_nop 0
	v_bfe_u32 v38, v34, 16, 1
	v_add3_u32 v34, v34, v38, s70
	v_bfe_u32 v38, v35, 16, 1
	v_pk_fma_f32 v[36:37], v[44:45], v[36:37], v[40:41]
	v_lshrrev_b32_e32 v34, 16, v34
	v_add3_u32 v35, v35, v38, s70
	v_and_or_b32 v34, v35, s33, v34
	v_bfe_u32 v35, v36, 16, 1
	v_add3_u32 v35, v36, v35, s70
	v_bfe_u32 v36, v37, 16, 1
	v_lshrrev_b32_e32 v35, 16, v35
	v_add3_u32 v36, v37, v36, s70
	v_and_or_b32 v35, v36, s33, v35
	s_waitcnt lgkmcnt(0)
	v_pk_fma_f32 v[36:37], v[58:59], v[50:51], v[54:55]
	global_store_dwordx2 v[90:91], v[34:35], off offset:2048
	v_bfe_u32 v38, v36, 16, 1
	v_add3_u32 v36, v36, v38, s70
	v_bfe_u32 v38, v37, 16, 1
	v_pk_fma_f32 v[34:35], v[60:61], v[52:53], v[56:57]
	v_lshrrev_b32_e32 v36, 16, v36
	v_add3_u32 v37, v37, v38, s70
	v_and_or_b32 v42, v37, s33, v36
	v_bfe_u32 v36, v34, 16, 1
	v_add3_u32 v34, v34, v36, s70
	v_lshrrev_b32_e32 v43, 16, v34
	v_bfe_u32 v34, v35, 16, 1
	v_add3_u32 v44, v35, v34, s70
	ds_read_b128 v[34:37], v92 offset:6144
	ds_read_b128 v[38:41], v106 offset:47104
	v_and_or_b32 v43, v44, s33, v43
	global_store_dwordx2 v[90:91], v[42:43], off offset:2560
	ds_read_b128 v[42:45], v92 offset:7168
	ds_read_b128 v[50:53], v106 offset:48128
	s_waitcnt lgkmcnt(2)
	v_pk_fma_f32 v[34:35], v[46:47], v[34:35], v[38:39]
	s_nop 0
	v_bfe_u32 v38, v34, 16, 1
	v_add3_u32 v34, v34, v38, s70
	v_bfe_u32 v38, v35, 16, 1
	v_pk_fma_f32 v[36:37], v[48:49], v[36:37], v[40:41]
	v_lshrrev_b32_e32 v34, 16, v34
	v_add3_u32 v35, v35, v38, s70
	v_and_or_b32 v34, v35, s33, v34
	v_bfe_u32 v35, v36, 16, 1
	v_add3_u32 v35, v36, v35, s70
	v_bfe_u32 v36, v37, 16, 1
	v_lshrrev_b32_e32 v35, 16, v35
	v_add3_u32 v36, v37, v36, s70
	v_and_or_b32 v35, v36, s33, v35
	s_waitcnt lgkmcnt(0)
	v_pk_fma_f32 v[36:37], v[62:63], v[42:43], v[50:51]
	global_store_dwordx2 v[90:91], v[34:35], off offset:3072
	v_bfe_u32 v38, v36, 16, 1
	v_add3_u32 v36, v36, v38, s70
	v_bfe_u32 v38, v37, 16, 1
	v_pk_fma_f32 v[34:35], v[64:65], v[44:45], v[52:53]
	v_lshrrev_b32_e32 v36, 16, v36
	v_add3_u32 v37, v37, v38, s70
	v_and_or_b32 v36, v37, s33, v36
	v_bfe_u32 v37, v34, 16, 1
	v_add3_u32 v34, v34, v37, s70
	v_bfe_u32 v37, v35, 16, 1
	v_lshrrev_b32_e32 v34, 16, v34
	v_add3_u32 v35, v35, v37, s70
	v_and_or_b32 v37, v35, s33, v34
	global_store_dwordx2 v[90:91], v[36:37], off offset:3584
	s_branch .LBB0_2511
